# K-loops: in phases 2 and 6 all four fragment reads are issued before the two LDS-DMA loads (the scalar pair fills the M0 wait state)
# baseline (speedup 1.0000x reference)
.LBB0_122:
	v_mov_b64_e32 v[0:1], 0x180
	s_ashr_i32 s15, s14, 31
	v_cmp_lt_i64_e32 vcc, s[16:17], v[0:1]
	s_lshl_b64 s[16:17], s[14:15], 19
	s_add_u32 s16, s30, s16
	s_addc_u32 s17, s31, s17
	s_and_b64 s[18:19], vcc, exec
	s_cselect_b32 s7, s17, s21
	s_cselect_b32 s9, s16, s20
	s_ashr_i32 s13, s12, 31
	s_lshl_b64 s[18:19], s[12:13], 19
	s_add_u32 s18, s34, s18
	s_addc_u32 s19, s35, s19
	s_and_b64 s[22:23], vcc, exec
	s_cselect_b32 s13, s19, s3
	s_cselect_b32 s15, s18, s2
	s_add_u32 s20, s20, 0x40080
	s_addc_u32 s21, s21, 0
	s_add_u32 s50, s2, 0x100
	s_addc_u32 s51, s3, 0
	s_mov_b32 s52, -2
	s_add_u32 s2, s20, 0xfffc0080
	s_addc_u32 s3, s21, -1
	ds_read_b128 v[24:27], v164
	ds_read_b128 v[28:31], v164 offset:1024
	ds_read_b128 v[32:35], v164 offset:2048
	ds_read_b128 v[36:39], v164 offset:3072
	s_cmp_eq_u32 s52, 12
	s_cselect_b32 s23, s7, s3
	s_cselect_b32 s22, s9, s2
	s_cselect_b32 s3, s13, s51
	s_cselect_b32 s2, s15, s50
	ds_read_b128 v[154:157], v165
	ds_read_b128 v[158:161], v165 offset:1024
	ds_read_b128 v[180:183], v165 offset:2048
	ds_read_b128 v[184:187], v165 offset:3072
	ds_read_b128 v[188:191], v165 offset:4096
	ds_read_b128 v[192:195], v165 offset:5120
	ds_read_b128 v[196:199], v165 offset:6144
	ds_read_b128 v[200:203], v165 offset:7168
	s_barrier
	s_waitcnt lgkmcnt(0)
	v_mfma_f32_16x16x32_bf16 v[140:143], v[24:27], v[154:157], 0
	v_mfma_f32_16x16x32_bf16 v[136:139], v[32:35], v[154:157], 0
	v_mfma_f32_16x16x32_bf16 v[124:127], v[24:27], v[180:183], 0
	v_mfma_f32_16x16x32_bf16 v[120:123], v[32:35], v[180:183], 0
	v_mfma_f32_16x16x32_bf16 v[108:111], v[24:27], v[188:191], 0
	v_mfma_f32_16x16x32_bf16 v[104:107], v[32:35], v[188:191], 0
	v_mfma_f32_16x16x32_bf16 v[92:95], v[24:27], v[196:199], 0
	v_mfma_f32_16x16x32_bf16 v[88:91], v[32:35], v[196:199], 0
	v_mfma_f32_16x16x32_bf16 v[140:143], v[28:31], v[158:161], v[140:143]
	v_mfma_f32_16x16x32_bf16 v[136:139], v[36:39], v[158:161], v[136:139]
	v_mfma_f32_16x16x32_bf16 v[124:127], v[28:31], v[184:187], v[124:127]
	v_mfma_f32_16x16x32_bf16 v[120:123], v[36:39], v[184:187], v[120:123]
	v_mfma_f32_16x16x32_bf16 v[108:111], v[28:31], v[192:195], v[108:111]
	v_mfma_f32_16x16x32_bf16 v[104:107], v[36:39], v[192:195], v[104:107]
	v_mfma_f32_16x16x32_bf16 v[92:95], v[28:31], v[200:203], v[92:95]
	v_mfma_f32_16x16x32_bf16 v[88:91], v[36:39], v[200:203], v[88:91]
	s_barrier
	s_add_i32 m0, s37, 0xc000
	ds_read_b128 v[204:207], v164 offset:16384
	ds_read_b128 v[208:211], v164 offset:17408
	ds_read_b128 v[212:215], v164 offset:18432
	ds_read_b128 v[216:219], v164 offset:19456
	global_load_lds_dwordx4 v150, s[20:21]
	s_add_i32 m0, s37, 0xe000
	s_add_u32 s98, s2, 0x80
	s_addc_u32 s99, s3, 0
	global_load_lds_dwordx4 v152, s[20:21]
	s_barrier
	s_waitcnt lgkmcnt(0)
	v_mfma_f32_16x16x32_bf16 v[132:135], v[204:207], v[154:157], 0
	v_mfma_f32_16x16x32_bf16 v[128:131], v[212:215], v[154:157], 0
	v_mfma_f32_16x16x32_bf16 v[116:119], v[204:207], v[180:183], 0
	v_mfma_f32_16x16x32_bf16 v[112:115], v[212:215], v[180:183], 0
	v_mfma_f32_16x16x32_bf16 v[100:103], v[204:207], v[188:191], 0
	v_mfma_f32_16x16x32_bf16 v[96:99], v[212:215], v[188:191], 0
	v_mfma_f32_16x16x32_bf16 v[84:87], v[204:207], v[196:199], 0
	v_mfma_f32_16x16x32_bf16 v[80:83], v[212:215], v[196:199], 0
	v_mfma_f32_16x16x32_bf16 v[132:135], v[208:211], v[158:161], v[132:135]
	v_mfma_f32_16x16x32_bf16 v[128:131], v[216:219], v[158:161], v[128:131]
	v_mfma_f32_16x16x32_bf16 v[116:119], v[208:211], v[184:187], v[116:119]
	v_mfma_f32_16x16x32_bf16 v[112:115], v[216:219], v[184:187], v[112:115]
	v_mfma_f32_16x16x32_bf16 v[100:103], v[208:211], v[192:195], v[100:103]
	v_mfma_f32_16x16x32_bf16 v[96:99], v[216:219], v[192:195], v[96:99]
	v_mfma_f32_16x16x32_bf16 v[84:87], v[208:211], v[200:203], v[84:87]
	v_mfma_f32_16x16x32_bf16 v[80:83], v[216:219], v[200:203], v[80:83]
	s_add_u32 s100, s22, 0x80
	s_addc_u32 s101, s23, 0
	s_barrier
	ds_read_b128 v[154:157], v165 offset:16384
	ds_read_b128 v[158:161], v165 offset:17408
	ds_read_b128 v[180:183], v165 offset:18432
	ds_read_b128 v[184:187], v165 offset:19456
	ds_read_b128 v[188:191], v165 offset:20480
	ds_read_b128 v[192:195], v165 offset:21504
	ds_read_b128 v[196:199], v165 offset:22528
	ds_read_b128 v[200:203], v165 offset:23552
	s_add_i32 m0, s36, 0x10000
	s_nop 0
	global_load_lds_dwordx4 v168, s[2:3]
	s_add_i32 m0, s36, 0x12000
	s_nop 0
	global_load_lds_dwordx4 v148, s[2:3]
	s_barrier
	s_waitcnt lgkmcnt(0)
	v_mfma_f32_16x16x32_bf16 v[76:79], v[24:27], v[154:157], 0
	v_mfma_f32_16x16x32_bf16 v[72:75], v[32:35], v[154:157], 0
	v_mfma_f32_16x16x32_bf16 v[60:63], v[24:27], v[180:183], 0
	v_mfma_f32_16x16x32_bf16 v[56:59], v[32:35], v[180:183], 0
	v_mfma_f32_16x16x32_bf16 v[44:47], v[24:27], v[188:191], 0
	v_mfma_f32_16x16x32_bf16 v[40:43], v[32:35], v[188:191], 0
	v_mfma_f32_16x16x32_bf16 v[12:15], v[24:27], v[196:199], 0
	v_mfma_f32_16x16x32_bf16 v[8:11], v[32:35], v[196:199], 0
	v_mfma_f32_16x16x32_bf16 v[76:79], v[28:31], v[158:161], v[76:79]
	v_mfma_f32_16x16x32_bf16 v[72:75], v[36:39], v[158:161], v[72:75]
	v_mfma_f32_16x16x32_bf16 v[60:63], v[28:31], v[184:187], v[60:63]
	v_mfma_f32_16x16x32_bf16 v[56:59], v[36:39], v[184:187], v[56:59]
	v_mfma_f32_16x16x32_bf16 v[44:47], v[28:31], v[192:195], v[44:47]
	v_mfma_f32_16x16x32_bf16 v[40:43], v[36:39], v[192:195], v[40:43]
	v_mfma_f32_16x16x32_bf16 v[12:15], v[28:31], v[200:203], v[12:15]
	v_mfma_f32_16x16x32_bf16 v[8:11], v[36:39], v[200:203], v[8:11]
	s_barrier
	s_mov_b32 m0, s37
	s_nop 0
	global_load_lds_dwordx4 v144, s[22:23]
	s_mov_b32 m0, s38
	s_nop 0
	global_load_lds_dwordx4 v146, s[22:23]
	s_add_i32 m0, s36, 0x14000
	s_add_u32 s54, s2, 0x40000
	s_addc_u32 s55, s3, 0
	global_load_lds_dwordx4 v168, s[54:55]
	s_add_i32 m0, s36, 0x16000
	s_add_u32 s22, s22, 0x40000
	s_addc_u32 s23, s23, 0
	global_load_lds_dwordx4 v148, s[54:55]
	s_waitcnt vmcnt(6)
	s_barrier
	v_mfma_f32_16x16x32_bf16 v[20:23], v[204:207], v[188:191], 0
	v_mfma_f32_16x16x32_bf16 v[16:19], v[212:215], v[188:191], 0
	v_mfma_f32_16x16x32_bf16 v[4:7], v[204:207], v[196:199], 0
	v_mfma_f32_16x16x32_bf16 v[0:3], v[212:215], v[196:199], 0
	v_mfma_f32_16x16x32_bf16 v[24:27], v[204:207], v[154:157], 0
	v_mfma_f32_16x16x32_bf16 v[28:31], v[212:215], v[154:157], 0
	v_mfma_f32_16x16x32_bf16 v[32:35], v[204:207], v[180:183], 0
	v_mfma_f32_16x16x32_bf16 v[36:39], v[212:215], v[180:183], 0
	v_mfma_f32_16x16x32_bf16 v[20:23], v[208:211], v[192:195], v[20:23]
	v_mfma_f32_16x16x32_bf16 v[16:19], v[216:219], v[192:195], v[16:19]
	v_mfma_f32_16x16x32_bf16 v[4:7], v[208:211], v[200:203], v[4:7]
	v_mfma_f32_16x16x32_bf16 v[0:3], v[216:219], v[200:203], v[0:3]
	v_mfma_f32_16x16x32_bf16 v[24:27], v[208:211], v[158:161], v[24:27]
	v_mfma_f32_16x16x32_bf16 v[28:31], v[216:219], v[158:161], v[28:31]
	v_mfma_f32_16x16x32_bf16 v[32:35], v[208:211], v[184:187], v[32:35]
	v_mfma_f32_16x16x32_bf16 v[36:39], v[216:219], v[184:187], v[36:39]
	s_barrier
	ds_read_b128 v[48:51], v164 offset:32768
	ds_read_b128 v[52:55], v164 offset:33792
	ds_read_b128 v[64:67], v164 offset:34816
	ds_read_b128 v[68:71], v164 offset:35840
	ds_read_b128 v[154:157], v165 offset:32768
	ds_read_b128 v[158:161], v165 offset:33792
	ds_read_b128 v[180:183], v165 offset:34816
	ds_read_b128 v[184:187], v165 offset:35840
	ds_read_b128 v[188:191], v165 offset:36864
	ds_read_b128 v[192:195], v165 offset:37888
	ds_read_b128 v[196:199], v165 offset:38912
	ds_read_b128 v[200:203], v165 offset:39936
	s_barrier
	s_waitcnt lgkmcnt(0)
	v_mfma_f32_16x16x32_bf16 v[140:143], v[48:51], v[154:157], v[140:143]
	v_mfma_f32_16x16x32_bf16 v[136:139], v[64:67], v[154:157], v[136:139]
	v_mfma_f32_16x16x32_bf16 v[124:127], v[48:51], v[180:183], v[124:127]
	v_mfma_f32_16x16x32_bf16 v[120:123], v[64:67], v[180:183], v[120:123]
	v_mfma_f32_16x16x32_bf16 v[108:111], v[48:51], v[188:191], v[108:111]
	v_mfma_f32_16x16x32_bf16 v[104:107], v[64:67], v[188:191], v[104:107]
	v_mfma_f32_16x16x32_bf16 v[92:95], v[48:51], v[196:199], v[92:95]
	v_mfma_f32_16x16x32_bf16 v[88:91], v[64:67], v[196:199], v[88:91]
	v_mfma_f32_16x16x32_bf16 v[140:143], v[52:55], v[158:161], v[140:143]
	v_mfma_f32_16x16x32_bf16 v[136:139], v[68:71], v[158:161], v[136:139]
	v_mfma_f32_16x16x32_bf16 v[124:127], v[52:55], v[184:187], v[124:127]
	v_mfma_f32_16x16x32_bf16 v[120:123], v[68:71], v[184:187], v[120:123]
	v_mfma_f32_16x16x32_bf16 v[108:111], v[52:55], v[192:195], v[108:111]
	v_mfma_f32_16x16x32_bf16 v[104:107], v[68:71], v[192:195], v[104:107]
	v_mfma_f32_16x16x32_bf16 v[92:95], v[52:55], v[200:203], v[92:95]
	v_mfma_f32_16x16x32_bf16 v[88:91], v[68:71], v[200:203], v[88:91]
	s_barrier
	s_mov_b32 m0, s39
	ds_read_b128 v[204:207], v164 offset:49152
	ds_read_b128 v[208:211], v164 offset:50176
	ds_read_b128 v[212:215], v164 offset:51200
	ds_read_b128 v[216:219], v164 offset:52224
	global_load_lds_dwordx4 v144, s[22:23]
	s_mov_b32 m0, s40
	s_nop 0
	global_load_lds_dwordx4 v146, s[22:23]
	s_barrier
	s_waitcnt lgkmcnt(0)
	v_mfma_f32_16x16x32_bf16 v[132:135], v[204:207], v[154:157], v[132:135]
	v_mfma_f32_16x16x32_bf16 v[128:131], v[212:215], v[154:157], v[128:131]
	v_mfma_f32_16x16x32_bf16 v[116:119], v[204:207], v[180:183], v[116:119]
	v_mfma_f32_16x16x32_bf16 v[112:115], v[212:215], v[180:183], v[112:115]
	v_mfma_f32_16x16x32_bf16 v[100:103], v[204:207], v[188:191], v[100:103]
	v_mfma_f32_16x16x32_bf16 v[96:99], v[212:215], v[188:191], v[96:99]
	v_mfma_f32_16x16x32_bf16 v[84:87], v[204:207], v[196:199], v[84:87]
	v_mfma_f32_16x16x32_bf16 v[80:83], v[212:215], v[196:199], v[80:83]
	v_mfma_f32_16x16x32_bf16 v[132:135], v[208:211], v[158:161], v[132:135]
	v_mfma_f32_16x16x32_bf16 v[128:131], v[216:219], v[158:161], v[128:131]
	v_mfma_f32_16x16x32_bf16 v[116:119], v[208:211], v[184:187], v[116:119]
	v_mfma_f32_16x16x32_bf16 v[112:115], v[216:219], v[184:187], v[112:115]
	v_mfma_f32_16x16x32_bf16 v[100:103], v[208:211], v[192:195], v[100:103]
	v_mfma_f32_16x16x32_bf16 v[96:99], v[216:219], v[192:195], v[96:99]
	v_mfma_f32_16x16x32_bf16 v[84:87], v[208:211], v[200:203], v[84:87]
	v_mfma_f32_16x16x32_bf16 v[80:83], v[216:219], v[200:203], v[80:83]
	s_barrier
	ds_read_b128 v[154:157], v165 offset:49152
	ds_read_b128 v[158:161], v165 offset:50176
	ds_read_b128 v[180:183], v165 offset:51200
	ds_read_b128 v[184:187], v165 offset:52224
	ds_read_b128 v[188:191], v165 offset:53248
	ds_read_b128 v[192:195], v165 offset:54272
	ds_read_b128 v[196:199], v165 offset:55296
	ds_read_b128 v[200:203], v165 offset:56320
	s_add_i32 m0, s36, 0x18000
	s_nop 0
	global_load_lds_dwordx4 v168, s[98:99]
	s_add_i32 m0, s36, 0x1a000
	s_nop 0
	global_load_lds_dwordx4 v148, s[98:99]
	s_barrier
	s_waitcnt lgkmcnt(0)
	v_mfma_f32_16x16x32_bf16 v[76:79], v[48:51], v[154:157], v[76:79]
	v_mfma_f32_16x16x32_bf16 v[72:75], v[64:67], v[154:157], v[72:75]
	v_mfma_f32_16x16x32_bf16 v[60:63], v[48:51], v[180:183], v[60:63]
	v_mfma_f32_16x16x32_bf16 v[56:59], v[64:67], v[180:183], v[56:59]
	v_mfma_f32_16x16x32_bf16 v[44:47], v[48:51], v[188:191], v[44:47]
	v_mfma_f32_16x16x32_bf16 v[40:43], v[64:67], v[188:191], v[40:43]
	v_mfma_f32_16x16x32_bf16 v[12:15], v[48:51], v[196:199], v[12:15]
	v_mfma_f32_16x16x32_bf16 v[8:11], v[64:67], v[196:199], v[8:11]
	v_mfma_f32_16x16x32_bf16 v[76:79], v[52:55], v[158:161], v[76:79]
	v_mfma_f32_16x16x32_bf16 v[72:75], v[68:71], v[158:161], v[72:75]
	v_mfma_f32_16x16x32_bf16 v[60:63], v[52:55], v[184:187], v[60:63]
	v_mfma_f32_16x16x32_bf16 v[56:59], v[68:71], v[184:187], v[56:59]
	v_mfma_f32_16x16x32_bf16 v[44:47], v[52:55], v[192:195], v[44:47]
	v_mfma_f32_16x16x32_bf16 v[40:43], v[68:71], v[192:195], v[40:43]
	v_mfma_f32_16x16x32_bf16 v[12:15], v[52:55], v[200:203], v[12:15]
	v_mfma_f32_16x16x32_bf16 v[8:11], v[68:71], v[200:203], v[8:11]
	s_barrier
	s_mov_b32 m0, s45
	s_nop 0
	global_load_lds_dwordx4 v144, s[100:101]
	s_mov_b32 m0, s46
	s_nop 0
	global_load_lds_dwordx4 v146, s[100:101]
	s_add_i32 m0, s36, 0x1c000
	s_add_u32 s2, s2, 0x40080
	s_addc_u32 s3, s3, 0
	global_load_lds_dwordx4 v168, s[2:3]
	s_add_i32 m0, s36, 0x1e000
	s_add_i32 s52, s52, 2
	global_load_lds_dwordx4 v148, s[2:3]
	s_waitcnt vmcnt(6)
	s_barrier
	v_mfma_f32_16x16x32_bf16 v[24:27], v[204:207], v[154:157], v[24:27]
	v_mfma_f32_16x16x32_bf16 v[68:71], v[208:211], v[158:161], v[24:27]
	v_mfma_f32_16x16x32_bf16 v[24:27], v[212:215], v[154:157], v[28:31]
	v_mfma_f32_16x16x32_bf16 v[64:67], v[216:219], v[158:161], v[24:27]
	v_mfma_f32_16x16x32_bf16 v[24:27], v[204:207], v[180:183], v[32:35]
	v_mfma_f32_16x16x32_bf16 v[52:55], v[208:211], v[184:187], v[24:27]
	v_mfma_f32_16x16x32_bf16 v[24:27], v[212:215], v[180:183], v[36:39]
	v_mfma_f32_16x16x32_bf16 v[20:23], v[204:207], v[188:191], v[20:23]
	v_mfma_f32_16x16x32_bf16 v[16:19], v[212:215], v[188:191], v[16:19]
	v_mfma_f32_16x16x32_bf16 v[4:7], v[204:207], v[196:199], v[4:7]
	v_mfma_f32_16x16x32_bf16 v[0:3], v[212:215], v[196:199], v[0:3]
	v_mfma_f32_16x16x32_bf16 v[48:51], v[216:219], v[184:187], v[24:27]
	v_mfma_f32_16x16x32_bf16 v[20:23], v[208:211], v[192:195], v[20:23]
	v_mfma_f32_16x16x32_bf16 v[16:19], v[216:219], v[192:195], v[16:19]
	v_mfma_f32_16x16x32_bf16 v[4:7], v[208:211], v[200:203], v[4:7]
	v_mfma_f32_16x16x32_bf16 v[0:3], v[216:219], v[200:203], v[0:3]
	s_add_u32 s20, s20, 0x100
	s_addc_u32 s21, s21, 0
	s_add_u32 s50, s50, 0x100
	s_addc_u32 s51, s51, 0
	s_cmp_gt_u32 s52, 13
	s_barrier
.LBB0_123:
	s_add_u32 s2, s20, 0xfffc0080
	s_addc_u32 s3, s21, -1
	ds_read_b128 v[24:27], v164
	ds_read_b128 v[28:31], v164 offset:1024
	ds_read_b128 v[32:35], v164 offset:2048
	ds_read_b128 v[36:39], v164 offset:3072
	s_cmp_eq_u32 s52, 12
	s_cselect_b32 s23, s7, s3
	s_cselect_b32 s22, s9, s2
	s_cselect_b32 s3, s13, s51
	s_cselect_b32 s2, s15, s50
	ds_read_b128 v[154:157], v165
	ds_read_b128 v[158:161], v165 offset:1024
	ds_read_b128 v[180:183], v165 offset:2048
	ds_read_b128 v[184:187], v165 offset:3072
	ds_read_b128 v[188:191], v165 offset:4096
	ds_read_b128 v[192:195], v165 offset:5120
	ds_read_b128 v[196:199], v165 offset:6144
	ds_read_b128 v[200:203], v165 offset:7168
	s_barrier
	s_waitcnt lgkmcnt(0)
	v_mfma_f32_16x16x32_bf16 v[140:143], v[24:27], v[154:157], v[140:143]
	v_mfma_f32_16x16x32_bf16 v[136:139], v[32:35], v[154:157], v[136:139]
	v_mfma_f32_16x16x32_bf16 v[124:127], v[24:27], v[180:183], v[124:127]
	v_mfma_f32_16x16x32_bf16 v[120:123], v[32:35], v[180:183], v[120:123]
	v_mfma_f32_16x16x32_bf16 v[108:111], v[24:27], v[188:191], v[108:111]
	v_mfma_f32_16x16x32_bf16 v[104:107], v[32:35], v[188:191], v[104:107]
	v_mfma_f32_16x16x32_bf16 v[92:95], v[24:27], v[196:199], v[92:95]
	v_mfma_f32_16x16x32_bf16 v[88:91], v[32:35], v[196:199], v[88:91]
	v_mfma_f32_16x16x32_bf16 v[140:143], v[28:31], v[158:161], v[140:143]
	v_mfma_f32_16x16x32_bf16 v[136:139], v[36:39], v[158:161], v[136:139]
	v_mfma_f32_16x16x32_bf16 v[124:127], v[28:31], v[184:187], v[124:127]
	v_mfma_f32_16x16x32_bf16 v[120:123], v[36:39], v[184:187], v[120:123]
	v_mfma_f32_16x16x32_bf16 v[108:111], v[28:31], v[192:195], v[108:111]
	v_mfma_f32_16x16x32_bf16 v[104:107], v[36:39], v[192:195], v[104:107]
	v_mfma_f32_16x16x32_bf16 v[92:95], v[28:31], v[200:203], v[92:95]
	v_mfma_f32_16x16x32_bf16 v[88:91], v[36:39], v[200:203], v[88:91]
	s_barrier
	s_add_i32 m0, s37, 0xc000
	ds_read_b128 v[204:207], v164 offset:16384
	ds_read_b128 v[208:211], v164 offset:17408
	ds_read_b128 v[212:215], v164 offset:18432
	ds_read_b128 v[216:219], v164 offset:19456
	global_load_lds_dwordx4 v150, s[20:21]
	s_add_i32 m0, s37, 0xe000
	s_add_u32 s98, s2, 0x80
	s_addc_u32 s99, s3, 0
	global_load_lds_dwordx4 v152, s[20:21]
	s_barrier
	s_waitcnt lgkmcnt(0)
	v_mfma_f32_16x16x32_bf16 v[132:135], v[204:207], v[154:157], v[132:135]
	v_mfma_f32_16x16x32_bf16 v[128:131], v[212:215], v[154:157], v[128:131]
	v_mfma_f32_16x16x32_bf16 v[116:119], v[204:207], v[180:183], v[116:119]
	v_mfma_f32_16x16x32_bf16 v[112:115], v[212:215], v[180:183], v[112:115]
	v_mfma_f32_16x16x32_bf16 v[100:103], v[204:207], v[188:191], v[100:103]
	v_mfma_f32_16x16x32_bf16 v[96:99], v[212:215], v[188:191], v[96:99]
	v_mfma_f32_16x16x32_bf16 v[84:87], v[204:207], v[196:199], v[84:87]
	v_mfma_f32_16x16x32_bf16 v[80:83], v[212:215], v[196:199], v[80:83]
	v_mfma_f32_16x16x32_bf16 v[132:135], v[208:211], v[158:161], v[132:135]
	v_mfma_f32_16x16x32_bf16 v[128:131], v[216:219], v[158:161], v[128:131]
	v_mfma_f32_16x16x32_bf16 v[116:119], v[208:211], v[184:187], v[116:119]
	v_mfma_f32_16x16x32_bf16 v[112:115], v[216:219], v[184:187], v[112:115]
	v_mfma_f32_16x16x32_bf16 v[100:103], v[208:211], v[192:195], v[100:103]
	v_mfma_f32_16x16x32_bf16 v[96:99], v[216:219], v[192:195], v[96:99]
	v_mfma_f32_16x16x32_bf16 v[84:87], v[208:211], v[200:203], v[84:87]
	v_mfma_f32_16x16x32_bf16 v[80:83], v[216:219], v[200:203], v[80:83]
	s_add_u32 s100, s22, 0x80
	s_addc_u32 s101, s23, 0
	s_barrier
	ds_read_b128 v[154:157], v165 offset:16384
	ds_read_b128 v[158:161], v165 offset:17408
	ds_read_b128 v[180:183], v165 offset:18432
	ds_read_b128 v[184:187], v165 offset:19456
	ds_read_b128 v[188:191], v165 offset:20480
	ds_read_b128 v[192:195], v165 offset:21504
	ds_read_b128 v[196:199], v165 offset:22528
	ds_read_b128 v[200:203], v165 offset:23552
	s_add_i32 m0, s36, 0x10000
	s_nop 0
	global_load_lds_dwordx4 v168, s[2:3]
	s_add_i32 m0, s36, 0x12000
	s_nop 0
	global_load_lds_dwordx4 v148, s[2:3]
	s_barrier
	s_waitcnt lgkmcnt(0)
	v_mfma_f32_16x16x32_bf16 v[76:79], v[24:27], v[154:157], v[76:79]
	v_mfma_f32_16x16x32_bf16 v[72:75], v[32:35], v[154:157], v[72:75]
	v_mfma_f32_16x16x32_bf16 v[60:63], v[24:27], v[180:183], v[60:63]
	v_mfma_f32_16x16x32_bf16 v[56:59], v[32:35], v[180:183], v[56:59]
	v_mfma_f32_16x16x32_bf16 v[44:47], v[24:27], v[188:191], v[44:47]
	v_mfma_f32_16x16x32_bf16 v[40:43], v[32:35], v[188:191], v[40:43]
	v_mfma_f32_16x16x32_bf16 v[12:15], v[24:27], v[196:199], v[12:15]
	v_mfma_f32_16x16x32_bf16 v[8:11], v[32:35], v[196:199], v[8:11]
	v_mfma_f32_16x16x32_bf16 v[76:79], v[28:31], v[158:161], v[76:79]
	v_mfma_f32_16x16x32_bf16 v[72:75], v[36:39], v[158:161], v[72:75]
	v_mfma_f32_16x16x32_bf16 v[60:63], v[28:31], v[184:187], v[60:63]
	v_mfma_f32_16x16x32_bf16 v[56:59], v[36:39], v[184:187], v[56:59]
	v_mfma_f32_16x16x32_bf16 v[44:47], v[28:31], v[192:195], v[44:47]
	v_mfma_f32_16x16x32_bf16 v[40:43], v[36:39], v[192:195], v[40:43]
	v_mfma_f32_16x16x32_bf16 v[12:15], v[28:31], v[200:203], v[12:15]
	v_mfma_f32_16x16x32_bf16 v[8:11], v[36:39], v[200:203], v[8:11]
	s_barrier
	s_mov_b32 m0, s37
	s_nop 0
	global_load_lds_dwordx4 v144, s[22:23]
	s_mov_b32 m0, s38
	s_nop 0
	global_load_lds_dwordx4 v146, s[22:23]
	s_add_i32 m0, s36, 0x14000
	s_add_u32 s54, s2, 0x40000
	s_addc_u32 s55, s3, 0
	global_load_lds_dwordx4 v168, s[54:55]
	s_add_i32 m0, s36, 0x16000
	s_add_u32 s22, s22, 0x40000
	s_addc_u32 s23, s23, 0
	global_load_lds_dwordx4 v148, s[54:55]
	s_waitcnt vmcnt(6)
	s_barrier
	v_mfma_f32_16x16x32_bf16 v[20:23], v[204:207], v[188:191], v[20:23]
	v_mfma_f32_16x16x32_bf16 v[16:19], v[212:215], v[188:191], v[16:19]
	v_mfma_f32_16x16x32_bf16 v[4:7], v[204:207], v[196:199], v[4:7]
	v_mfma_f32_16x16x32_bf16 v[0:3], v[212:215], v[196:199], v[0:3]
	v_mfma_f32_16x16x32_bf16 v[24:27], v[204:207], v[154:157], v[68:71]
	v_mfma_f32_16x16x32_bf16 v[28:31], v[212:215], v[154:157], v[64:67]
	v_mfma_f32_16x16x32_bf16 v[32:35], v[204:207], v[180:183], v[52:55]
	v_mfma_f32_16x16x32_bf16 v[36:39], v[212:215], v[180:183], v[48:51]
	v_mfma_f32_16x16x32_bf16 v[20:23], v[208:211], v[192:195], v[20:23]
	v_mfma_f32_16x16x32_bf16 v[16:19], v[216:219], v[192:195], v[16:19]
	v_mfma_f32_16x16x32_bf16 v[4:7], v[208:211], v[200:203], v[4:7]
	v_mfma_f32_16x16x32_bf16 v[0:3], v[216:219], v[200:203], v[0:3]
	v_mfma_f32_16x16x32_bf16 v[24:27], v[208:211], v[158:161], v[24:27]
	v_mfma_f32_16x16x32_bf16 v[28:31], v[216:219], v[158:161], v[28:31]
	v_mfma_f32_16x16x32_bf16 v[32:35], v[208:211], v[184:187], v[32:35]
	v_mfma_f32_16x16x32_bf16 v[36:39], v[216:219], v[184:187], v[36:39]
	s_barrier
	ds_read_b128 v[48:51], v164 offset:32768
	ds_read_b128 v[52:55], v164 offset:33792
	ds_read_b128 v[64:67], v164 offset:34816
	ds_read_b128 v[68:71], v164 offset:35840
	ds_read_b128 v[154:157], v165 offset:32768
	ds_read_b128 v[158:161], v165 offset:33792
	ds_read_b128 v[180:183], v165 offset:34816
	ds_read_b128 v[184:187], v165 offset:35840
	ds_read_b128 v[188:191], v165 offset:36864
	ds_read_b128 v[192:195], v165 offset:37888
	ds_read_b128 v[196:199], v165 offset:38912
	ds_read_b128 v[200:203], v165 offset:39936
	s_barrier
	s_waitcnt lgkmcnt(0)
	v_mfma_f32_16x16x32_bf16 v[140:143], v[48:51], v[154:157], v[140:143]
	v_mfma_f32_16x16x32_bf16 v[136:139], v[64:67], v[154:157], v[136:139]
	v_mfma_f32_16x16x32_bf16 v[124:127], v[48:51], v[180:183], v[124:127]
	v_mfma_f32_16x16x32_bf16 v[120:123], v[64:67], v[180:183], v[120:123]
	v_mfma_f32_16x16x32_bf16 v[108:111], v[48:51], v[188:191], v[108:111]
	v_mfma_f32_16x16x32_bf16 v[104:107], v[64:67], v[188:191], v[104:107]
	v_mfma_f32_16x16x32_bf16 v[92:95], v[48:51], v[196:199], v[92:95]
	v_mfma_f32_16x16x32_bf16 v[88:91], v[64:67], v[196:199], v[88:91]
	v_mfma_f32_16x16x32_bf16 v[140:143], v[52:55], v[158:161], v[140:143]
	v_mfma_f32_16x16x32_bf16 v[136:139], v[68:71], v[158:161], v[136:139]
	v_mfma_f32_16x16x32_bf16 v[124:127], v[52:55], v[184:187], v[124:127]
	v_mfma_f32_16x16x32_bf16 v[120:123], v[68:71], v[184:187], v[120:123]
	v_mfma_f32_16x16x32_bf16 v[108:111], v[52:55], v[192:195], v[108:111]
	v_mfma_f32_16x16x32_bf16 v[104:107], v[68:71], v[192:195], v[104:107]
	v_mfma_f32_16x16x32_bf16 v[92:95], v[52:55], v[200:203], v[92:95]
	v_mfma_f32_16x16x32_bf16 v[88:91], v[68:71], v[200:203], v[88:91]
	s_barrier
	s_mov_b32 m0, s39
	ds_read_b128 v[204:207], v164 offset:49152
	ds_read_b128 v[208:211], v164 offset:50176
	ds_read_b128 v[212:215], v164 offset:51200
	ds_read_b128 v[216:219], v164 offset:52224
	global_load_lds_dwordx4 v144, s[22:23]
	s_mov_b32 m0, s40
	s_nop 0
	global_load_lds_dwordx4 v146, s[22:23]
	s_barrier
	s_waitcnt lgkmcnt(0)
	v_mfma_f32_16x16x32_bf16 v[132:135], v[204:207], v[154:157], v[132:135]
	v_mfma_f32_16x16x32_bf16 v[128:131], v[212:215], v[154:157], v[128:131]
	v_mfma_f32_16x16x32_bf16 v[116:119], v[204:207], v[180:183], v[116:119]
	v_mfma_f32_16x16x32_bf16 v[112:115], v[212:215], v[180:183], v[112:115]
	v_mfma_f32_16x16x32_bf16 v[100:103], v[204:207], v[188:191], v[100:103]
	v_mfma_f32_16x16x32_bf16 v[96:99], v[212:215], v[188:191], v[96:99]
	v_mfma_f32_16x16x32_bf16 v[84:87], v[204:207], v[196:199], v[84:87]
	v_mfma_f32_16x16x32_bf16 v[80:83], v[212:215], v[196:199], v[80:83]
	v_mfma_f32_16x16x32_bf16 v[132:135], v[208:211], v[158:161], v[132:135]
	v_mfma_f32_16x16x32_bf16 v[128:131], v[216:219], v[158:161], v[128:131]
	v_mfma_f32_16x16x32_bf16 v[116:119], v[208:211], v[184:187], v[116:119]
	v_mfma_f32_16x16x32_bf16 v[112:115], v[216:219], v[184:187], v[112:115]
	v_mfma_f32_16x16x32_bf16 v[100:103], v[208:211], v[192:195], v[100:103]
	v_mfma_f32_16x16x32_bf16 v[96:99], v[216:219], v[192:195], v[96:99]
	v_mfma_f32_16x16x32_bf16 v[84:87], v[208:211], v[200:203], v[84:87]
	v_mfma_f32_16x16x32_bf16 v[80:83], v[216:219], v[200:203], v[80:83]
	s_barrier
	ds_read_b128 v[154:157], v165 offset:49152
	ds_read_b128 v[158:161], v165 offset:50176
	ds_read_b128 v[180:183], v165 offset:51200
	ds_read_b128 v[184:187], v165 offset:52224
	ds_read_b128 v[188:191], v165 offset:53248
	ds_read_b128 v[192:195], v165 offset:54272
	ds_read_b128 v[196:199], v165 offset:55296
	ds_read_b128 v[200:203], v165 offset:56320
	s_add_i32 m0, s36, 0x18000
	s_nop 0
	global_load_lds_dwordx4 v168, s[98:99]
	s_add_i32 m0, s36, 0x1a000
	s_nop 0
	global_load_lds_dwordx4 v148, s[98:99]
	s_barrier
	s_waitcnt lgkmcnt(0)
	v_mfma_f32_16x16x32_bf16 v[76:79], v[48:51], v[154:157], v[76:79]
	v_mfma_f32_16x16x32_bf16 v[72:75], v[64:67], v[154:157], v[72:75]
	v_mfma_f32_16x16x32_bf16 v[60:63], v[48:51], v[180:183], v[60:63]
	v_mfma_f32_16x16x32_bf16 v[56:59], v[64:67], v[180:183], v[56:59]
	v_mfma_f32_16x16x32_bf16 v[44:47], v[48:51], v[188:191], v[44:47]
	v_mfma_f32_16x16x32_bf16 v[40:43], v[64:67], v[188:191], v[40:43]
	v_mfma_f32_16x16x32_bf16 v[12:15], v[48:51], v[196:199], v[12:15]
	v_mfma_f32_16x16x32_bf16 v[8:11], v[64:67], v[196:199], v[8:11]
	v_mfma_f32_16x16x32_bf16 v[76:79], v[52:55], v[158:161], v[76:79]
	v_mfma_f32_16x16x32_bf16 v[72:75], v[68:71], v[158:161], v[72:75]
	v_mfma_f32_16x16x32_bf16 v[60:63], v[52:55], v[184:187], v[60:63]
	v_mfma_f32_16x16x32_bf16 v[56:59], v[68:71], v[184:187], v[56:59]
	v_mfma_f32_16x16x32_bf16 v[44:47], v[52:55], v[192:195], v[44:47]
	v_mfma_f32_16x16x32_bf16 v[40:43], v[68:71], v[192:195], v[40:43]
	v_mfma_f32_16x16x32_bf16 v[12:15], v[52:55], v[200:203], v[12:15]
	v_mfma_f32_16x16x32_bf16 v[8:11], v[68:71], v[200:203], v[8:11]
	s_barrier
	s_mov_b32 m0, s45
	s_nop 0
	global_load_lds_dwordx4 v144, s[100:101]
	s_mov_b32 m0, s46
	s_nop 0
	global_load_lds_dwordx4 v146, s[100:101]
	s_add_i32 m0, s36, 0x1c000
	s_add_u32 s2, s2, 0x40080
	s_addc_u32 s3, s3, 0
	global_load_lds_dwordx4 v168, s[2:3]
	s_add_i32 m0, s36, 0x1e000
	s_add_i32 s52, s52, 2
	global_load_lds_dwordx4 v148, s[2:3]
	s_waitcnt vmcnt(6)
	s_barrier
	v_mfma_f32_16x16x32_bf16 v[24:27], v[204:207], v[154:157], v[24:27]
	v_mfma_f32_16x16x32_bf16 v[68:71], v[208:211], v[158:161], v[24:27]
	v_mfma_f32_16x16x32_bf16 v[24:27], v[212:215], v[154:157], v[28:31]
	v_mfma_f32_16x16x32_bf16 v[64:67], v[216:219], v[158:161], v[24:27]
	v_mfma_f32_16x16x32_bf16 v[24:27], v[204:207], v[180:183], v[32:35]
	v_mfma_f32_16x16x32_bf16 v[52:55], v[208:211], v[184:187], v[24:27]
	v_mfma_f32_16x16x32_bf16 v[24:27], v[212:215], v[180:183], v[36:39]
	v_mfma_f32_16x16x32_bf16 v[20:23], v[204:207], v[188:191], v[20:23]
	v_mfma_f32_16x16x32_bf16 v[16:19], v[212:215], v[188:191], v[16:19]
	v_mfma_f32_16x16x32_bf16 v[4:7], v[204:207], v[196:199], v[4:7]
	v_mfma_f32_16x16x32_bf16 v[0:3], v[212:215], v[196:199], v[0:3]
	v_mfma_f32_16x16x32_bf16 v[48:51], v[216:219], v[184:187], v[24:27]
	v_mfma_f32_16x16x32_bf16 v[20:23], v[208:211], v[192:195], v[20:23]
	v_mfma_f32_16x16x32_bf16 v[16:19], v[216:219], v[192:195], v[16:19]
	v_mfma_f32_16x16x32_bf16 v[4:7], v[208:211], v[200:203], v[4:7]
	v_mfma_f32_16x16x32_bf16 v[0:3], v[216:219], v[200:203], v[0:3]
	s_add_u32 s20, s20, 0x100
	s_addc_u32 s21, s21, 0
	s_add_u32 s50, s50, 0x100
	s_addc_u32 s51, s51, 0
	s_cmp_gt_u32 s52, 13
	s_barrier
	s_cbranch_scc0 .LBB0_123
	s_lshl_b32 s2, s6, 8
	s_add_i32 s3, s2, s43
	s_lshl_b32 s2, s8, 8
	s_cmp_gt_i32 s8, 3
	s_cselect_b64 s[20:21], -1, 0
	s_and_b64 s[22:23], s[20:21], exec
	s_mov_b32 s7, 0x8982000
	s_cselect_b32 s7, s7, 0x7182000
	s_add_u32 s22, s26, s7
	s_addc_u32 s23, s25, 0
	s_add_i32 s7, s6, -16
	v_mov_b32_e32 v160, v163
	v_mov_b32_e32 v24, v162
	s_lshr_b32 s7, s7, 3
	s_add_i32 s96, s7, 1
	v_add_u32_e32 v154, s3, v24
	s_lshl_b64 s[50:51], s[96:97], 11
	v_ashrrev_i32_e32 v155, 31, v154
	s_cmp_gt_i32 s6, 15
	v_lshl_add_u64 v[156:157], v[154:155], 2, s[10:11]
	s_cselect_b32 s7, s51, 0
	s_cselect_b32 s6, s50, 0
	global_load_dword v166, v[156:157], off
	global_load_dword v191, v[156:157], off offset:64
	global_load_dword v192, v[156:157], off offset:128
	global_load_dword v193, v[156:157], off offset:192
	global_load_dword v194, v[156:157], off offset:512
	global_load_dword v195, v[156:157], off offset:576
	global_load_dword v196, v[156:157], off offset:640
	global_load_dword v197, v[156:157], off offset:704
	s_lshl_b64 s[6:7], s[6:7], 2
	s_add_u32 s9, s41, s6
	s_addc_u32 s13, s42, s7
	s_ashr_i32 s3, s2, 31
	s_lshl_b64 s[6:7], s[2:3], 2
	s_add_u32 s3, s9, s6
	s_addc_u32 s7, s13, s7
	v_lshlrev_b32_e32 v158, 3, v160
	s_add_u32 s6, s3, s49
	s_addc_u32 s7, s7, 0
	v_ashrrev_i32_e32 v159, 31, v158
	v_lshl_add_u64 v[24:25], v[158:159], 2, s[6:7]
	global_load_dwordx4 v[36:39], v[24:25], off
	global_load_dwordx4 v[32:35], v[24:25], off offset:16
	global_load_dwordx4 v[28:31], v[24:25], off offset:512
	s_nop 0
	global_load_dwordx4 v[24:27], v[24:25], off offset:528
	s_and_b32 s2, s2, 0x300
	s_or_b32 s2, s2, s44
	v_add_u32_e32 v158, s2, v158
	v_cmp_eq_u32_e64 s[6:7], 0, v160
	v_lshlrev_b64 v[160:161], 11, v[154:155]
	s_cmp_lt_i32 s8, 4
	s_waitcnt vmcnt(0)
	v_ashrrev_i32_e32 v159, 31, v158
	v_lshl_add_u64 v[158:159], v[158:159], 1, s[22:23]
	v_lshl_add_u64 v[160:161], v[158:159], 0, v[160:161]
	v_lshl_add_u64 v[156:157], v[154:155], 2, s[0:1]
	s_and_b64 s[6:7], s[6:7], s[20:21]
	s_mov_b64 s[2:3], 0x8000
	s_mov_b64 s[50:51], 0x28000
	v_mov_b32_e32 v180, 0xc0135761
	v_mov_b32_e32 v181, 0xc0135761
	v_mov_b32_e32 v182, 0xbdd2d3e7
	v_mov_b32_e32 v183, 0xbdd2d3e7
	v_fmamk_f32 v166, v166, 0x3a800000, v225
	v_fmamk_f32 v190, v191, 0x3a800000, v225
	v_fmamk_f32 v192, v192, 0x3a800000, v225
	v_fmamk_f32 v188, v193, 0x3a800000, v225
	v_fmamk_f32 v194, v194, 0x3a800000, v225
	v_fmamk_f32 v186, v195, 0x3a800000, v225
	v_fmamk_f32 v196, v196, 0x3a800000, v225
	v_fmamk_f32 v184, v197, 0x3a800000, v225
	v_rsq_f32_e32 v166, v166
	v_rsq_f32_e32 v190, v190
	v_rsq_f32_e32 v192, v192
	v_rsq_f32_e32 v188, v188
	v_rsq_f32_e32 v194, v194
	v_rsq_f32_e32 v186, v186
	v_rsq_f32_e32 v196, v196
	v_rsq_f32_e32 v184, v184
	v_pk_fma_f32 v[140:141], v[140:141], v[166:167], v[36:37] op_sel_hi:[1,0,1]
	v_pk_fma_f32 v[142:143], v[142:143], v[166:167], v[38:39] op_sel_hi:[1,0,1]
	v_pk_fma_f32 v[136:137], v[136:137], v[166:167], v[32:33] op_sel_hi:[1,0,1]
	v_pk_fma_f32 v[138:139], v[138:139], v[166:167], v[34:35] op_sel_hi:[1,0,1]
	v_pk_fma_f32 v[132:133], v[132:133], v[166:167], v[28:29] op_sel_hi:[1,0,1]
	v_pk_fma_f32 v[134:135], v[134:135], v[166:167], v[30:31] op_sel_hi:[1,0,1]
	v_pk_fma_f32 v[128:129], v[128:129], v[166:167], v[24:25] op_sel_hi:[1,0,1]
	v_pk_fma_f32 v[130:131], v[130:131], v[166:167], v[26:27] op_sel_hi:[1,0,1]
	v_pk_fma_f32 v[124:125], v[124:125], v[190:191], v[36:37] op_sel_hi:[1,0,1]
	v_pk_fma_f32 v[126:127], v[126:127], v[190:191], v[38:39] op_sel_hi:[1,0,1]
	v_pk_fma_f32 v[120:121], v[120:121], v[190:191], v[32:33] op_sel_hi:[1,0,1]
	v_pk_fma_f32 v[122:123], v[122:123], v[190:191], v[34:35] op_sel_hi:[1,0,1]
	v_pk_fma_f32 v[116:117], v[116:117], v[190:191], v[28:29] op_sel_hi:[1,0,1]
	v_pk_fma_f32 v[118:119], v[118:119], v[190:191], v[30:31] op_sel_hi:[1,0,1]
	v_pk_fma_f32 v[112:113], v[112:113], v[190:191], v[24:25] op_sel_hi:[1,0,1]
	v_pk_fma_f32 v[114:115], v[114:115], v[190:191], v[26:27] op_sel_hi:[1,0,1]
	v_pk_fma_f32 v[108:109], v[108:109], v[192:193], v[36:37] op_sel_hi:[1,0,1]
	v_pk_fma_f32 v[110:111], v[110:111], v[192:193], v[38:39] op_sel_hi:[1,0,1]
	v_pk_fma_f32 v[104:105], v[104:105], v[192:193], v[32:33] op_sel_hi:[1,0,1]
	v_pk_fma_f32 v[106:107], v[106:107], v[192:193], v[34:35] op_sel_hi:[1,0,1]
	v_pk_fma_f32 v[100:101], v[100:101], v[192:193], v[28:29] op_sel_hi:[1,0,1]
	v_pk_fma_f32 v[102:103], v[102:103], v[192:193], v[30:31] op_sel_hi:[1,0,1]
	v_pk_fma_f32 v[96:97], v[96:97], v[192:193], v[24:25] op_sel_hi:[1,0,1]
	v_pk_fma_f32 v[98:99], v[98:99], v[192:193], v[26:27] op_sel_hi:[1,0,1]
	v_pk_fma_f32 v[92:93], v[92:93], v[188:189], v[36:37] op_sel_hi:[1,0,1]
	v_pk_fma_f32 v[94:95], v[94:95], v[188:189], v[38:39] op_sel_hi:[1,0,1]
	v_pk_fma_f32 v[88:89], v[88:89], v[188:189], v[32:33] op_sel_hi:[1,0,1]
	v_pk_fma_f32 v[90:91], v[90:91], v[188:189], v[34:35] op_sel_hi:[1,0,1]
	v_pk_fma_f32 v[84:85], v[84:85], v[188:189], v[28:29] op_sel_hi:[1,0,1]
	v_pk_fma_f32 v[86:87], v[86:87], v[188:189], v[30:31] op_sel_hi:[1,0,1]
	v_pk_fma_f32 v[80:81], v[80:81], v[188:189], v[24:25] op_sel_hi:[1,0,1]
	v_pk_fma_f32 v[82:83], v[82:83], v[188:189], v[26:27] op_sel_hi:[1,0,1]
	v_pk_fma_f32 v[76:77], v[76:77], v[194:195], v[36:37] op_sel_hi:[1,0,1]
	v_pk_fma_f32 v[78:79], v[78:79], v[194:195], v[38:39] op_sel_hi:[1,0,1]
	v_pk_fma_f32 v[72:73], v[72:73], v[194:195], v[32:33] op_sel_hi:[1,0,1]
	v_pk_fma_f32 v[74:75], v[74:75], v[194:195], v[34:35] op_sel_hi:[1,0,1]
	v_pk_fma_f32 v[68:69], v[68:69], v[194:195], v[28:29] op_sel_hi:[1,0,1]
	v_pk_fma_f32 v[70:71], v[70:71], v[194:195], v[30:31] op_sel_hi:[1,0,1]
	v_pk_fma_f32 v[64:65], v[64:65], v[194:195], v[24:25] op_sel_hi:[1,0,1]
	v_pk_fma_f32 v[66:67], v[66:67], v[194:195], v[26:27] op_sel_hi:[1,0,1]
	v_pk_fma_f32 v[60:61], v[60:61], v[186:187], v[36:37] op_sel_hi:[1,0,1]
	v_pk_fma_f32 v[62:63], v[62:63], v[186:187], v[38:39] op_sel_hi:[1,0,1]
	v_pk_fma_f32 v[56:57], v[56:57], v[186:187], v[32:33] op_sel_hi:[1,0,1]
	v_pk_fma_f32 v[58:59], v[58:59], v[186:187], v[34:35] op_sel_hi:[1,0,1]
	v_pk_fma_f32 v[52:53], v[52:53], v[186:187], v[28:29] op_sel_hi:[1,0,1]
	v_pk_fma_f32 v[54:55], v[54:55], v[186:187], v[30:31] op_sel_hi:[1,0,1]
	v_pk_fma_f32 v[48:49], v[48:49], v[186:187], v[24:25] op_sel_hi:[1,0,1]
	v_pk_fma_f32 v[50:51], v[50:51], v[186:187], v[26:27] op_sel_hi:[1,0,1]
	v_pk_fma_f32 v[44:45], v[44:45], v[196:197], v[36:37] op_sel_hi:[1,0,1]
	v_pk_fma_f32 v[46:47], v[46:47], v[196:197], v[38:39] op_sel_hi:[1,0,1]
	v_pk_fma_f32 v[40:41], v[40:41], v[196:197], v[32:33] op_sel_hi:[1,0,1]
	v_pk_fma_f32 v[42:43], v[42:43], v[196:197], v[34:35] op_sel_hi:[1,0,1]
	v_pk_fma_f32 v[20:21], v[20:21], v[196:197], v[28:29] op_sel_hi:[1,0,1]
	v_pk_fma_f32 v[22:23], v[22:23], v[196:197], v[30:31] op_sel_hi:[1,0,1]
	v_pk_fma_f32 v[16:17], v[16:17], v[196:197], v[24:25] op_sel_hi:[1,0,1]
	v_pk_fma_f32 v[18:19], v[18:19], v[196:197], v[26:27] op_sel_hi:[1,0,1]
	v_pk_fma_f32 v[12:13], v[12:13], v[184:185], v[36:37] op_sel_hi:[1,0,1]
	v_pk_fma_f32 v[14:15], v[14:15], v[184:185], v[38:39] op_sel_hi:[1,0,1]
	v_pk_fma_f32 v[8:9], v[8:9], v[184:185], v[32:33] op_sel_hi:[1,0,1]
	v_pk_fma_f32 v[10:11], v[10:11], v[184:185], v[34:35] op_sel_hi:[1,0,1]
	v_pk_fma_f32 v[4:5], v[4:5], v[184:185], v[28:29] op_sel_hi:[1,0,1]
	v_pk_fma_f32 v[6:7], v[6:7], v[184:185], v[30:31] op_sel_hi:[1,0,1]
	v_pk_fma_f32 v[0:1], v[0:1], v[184:185], v[24:25] op_sel_hi:[1,0,1]
	v_pk_fma_f32 v[2:3], v[2:3], v[184:185], v[26:27] op_sel_hi:[1,0,1]
	v_pk_mul_f32 v[24:25], v[140:141], v[140:141]
	v_pk_mul_f32 v[26:27], v[142:143], v[142:143]
	v_pk_mul_f32 v[28:29], v[136:137], v[136:137]
	v_pk_mul_f32 v[30:31], v[138:139], v[138:139]
	v_pk_mul_f32 v[32:33], v[132:133], v[132:133]
	v_pk_mul_f32 v[34:35], v[134:135], v[134:135]
	v_pk_mul_f32 v[36:37], v[128:129], v[128:129]
	v_pk_mul_f32 v[38:39], v[130:131], v[130:131]
	v_pk_fma_f32 v[24:25], v[24:25], v[182:183], v[180:181]
	v_pk_fma_f32 v[26:27], v[26:27], v[182:183], v[180:181]
	v_pk_fma_f32 v[28:29], v[28:29], v[182:183], v[180:181]
	v_pk_fma_f32 v[30:31], v[30:31], v[182:183], v[180:181]
	v_pk_fma_f32 v[32:33], v[32:33], v[182:183], v[180:181]
	v_pk_fma_f32 v[34:35], v[34:35], v[182:183], v[180:181]
	v_pk_fma_f32 v[36:37], v[36:37], v[182:183], v[180:181]
	v_pk_fma_f32 v[38:39], v[38:39], v[182:183], v[180:181]
	v_pk_mul_f32 v[24:25], v[24:25], v[140:141]
	v_pk_mul_f32 v[26:27], v[26:27], v[142:143]
	v_pk_mul_f32 v[28:29], v[28:29], v[136:137]
	v_pk_mul_f32 v[30:31], v[30:31], v[138:139]
	v_pk_mul_f32 v[32:33], v[32:33], v[132:133]
	v_pk_mul_f32 v[34:35], v[34:35], v[134:135]
	v_pk_mul_f32 v[36:37], v[36:37], v[128:129]
	v_pk_mul_f32 v[38:39], v[38:39], v[130:131]
	v_exp_f32_e32 v24, v24
	v_exp_f32_e32 v25, v25
	v_exp_f32_e32 v26, v26
	v_exp_f32_e32 v27, v27
	v_exp_f32_e32 v28, v28
	v_exp_f32_e32 v29, v29
	v_exp_f32_e32 v30, v30
	v_exp_f32_e32 v31, v31
	v_exp_f32_e32 v32, v32
	v_exp_f32_e32 v33, v33
	v_exp_f32_e32 v34, v34
	v_exp_f32_e32 v35, v35
	v_exp_f32_e32 v36, v36
	v_exp_f32_e32 v37, v37
	v_exp_f32_e32 v38, v38
	v_exp_f32_e32 v39, v39
	v_pk_add_f32 v[24:25], v[24:25], 1.0 op_sel_hi:[1,0]
	v_pk_add_f32 v[26:27], v[26:27], 1.0 op_sel_hi:[1,0]
	v_pk_add_f32 v[28:29], v[28:29], 1.0 op_sel_hi:[1,0]
	v_pk_add_f32 v[30:31], v[30:31], 1.0 op_sel_hi:[1,0]
	v_pk_add_f32 v[32:33], v[32:33], 1.0 op_sel_hi:[1,0]
	v_pk_add_f32 v[34:35], v[34:35], 1.0 op_sel_hi:[1,0]
	v_pk_add_f32 v[36:37], v[36:37], 1.0 op_sel_hi:[1,0]
	v_pk_add_f32 v[38:39], v[38:39], 1.0 op_sel_hi:[1,0]
	v_rcp_f32_e32 v24, v24
	v_rcp_f32_e32 v25, v25
	v_rcp_f32_e32 v26, v26
	v_rcp_f32_e32 v27, v27
	v_rcp_f32_e32 v28, v28
	v_rcp_f32_e32 v29, v29
	v_rcp_f32_e32 v30, v30
	v_rcp_f32_e32 v31, v31
	v_rcp_f32_e32 v32, v32
	v_rcp_f32_e32 v33, v33
	v_rcp_f32_e32 v34, v34
	v_rcp_f32_e32 v35, v35
	v_rcp_f32_e32 v36, v36
	v_rcp_f32_e32 v37, v37
	v_rcp_f32_e32 v38, v38
	v_rcp_f32_e32 v39, v39
	v_pk_mul_f32 v[140:141], v[140:141], v[24:25]
	v_pk_mul_f32 v[142:143], v[142:143], v[26:27]
	v_pk_mul_f32 v[136:137], v[136:137], v[28:29]
	v_pk_mul_f32 v[138:139], v[138:139], v[30:31]
	v_pk_mul_f32 v[132:133], v[132:133], v[32:33]
	v_pk_mul_f32 v[134:135], v[134:135], v[34:35]
	v_pk_mul_f32 v[128:129], v[128:129], v[36:37]
	v_pk_mul_f32 v[130:131], v[130:131], v[38:39]
	v_cvt_pk_bf16_f32 v24, v140, v141
	v_cvt_pk_bf16_f32 v25, v142, v143
	v_cvt_pk_bf16_f32 v26, v136, v137
	v_cvt_pk_bf16_f32 v27, v138, v139
	v_cvt_pk_bf16_f32 v28, v132, v133
	v_cvt_pk_bf16_f32 v29, v134, v135
	v_cvt_pk_bf16_f32 v30, v128, v129
	v_cvt_pk_bf16_f32 v31, v130, v131
	global_store_dwordx4 v[160:161], v[24:27], off
	global_store_dwordx4 v[160:161], v[28:31], off offset:256
	s_and_b64 vcc, exec, s[20:21]
	s_cbranch_vccz .Lio_skip_0
	v_pk_mul_f32 v[32:33], v[140:141], v[140:141]
	v_pk_fma_f32 v[32:33], v[142:143], v[142:143], v[32:33]
	v_pk_fma_f32 v[32:33], v[136:137], v[136:137], v[32:33]
	v_pk_fma_f32 v[32:33], v[138:139], v[138:139], v[32:33]
	v_pk_fma_f32 v[32:33], v[132:133], v[132:133], v[32:33]
	v_pk_fma_f32 v[32:33], v[134:135], v[134:135], v[32:33]
	v_pk_fma_f32 v[32:33], v[128:129], v[128:129], v[32:33]
	v_pk_fma_f32 v[32:33], v[130:131], v[130:131], v[32:33]
	s_nop 0
	v_add_f32_e32 v32, v32, v33
	v_mov_b32_e32 v33, v32
	s_nop 1
	v_permlane16_swap_b32_e32 v32, v33
	v_add_f32_e32 v32, v32, v33
	v_mov_b32_e32 v33, v32
	s_nop 1
	v_permlane32_swap_b32_e32 v32, v33
	s_and_saveexec_b64 vcc, s[6:7]
	v_add_f32_e32 v32, v32, v33
	global_atomic_add_f32 v[156:157], v32, off
	s_mov_b64 exec, vcc

.Lie_done_b:
.LBB0_354:
	s_ashr_i32 s31, s30, 31
	v_cmp_lt_i64_e32 vcc, s[8:9], v[170:171]
	s_lshl_b64 s[8:9], s[30:31], 19
	s_add_u32 s34, s52, s8
	s_addc_u32 s35, s53, s9
	s_and_b64 s[8:9], vcc, exec
	s_cselect_b32 s1, s35, s7
	s_cselect_b32 s31, s34, s6
	s_ashr_i32 s29, s28, 31
	s_lshl_b64 s[8:9], s[28:29], 19
	s_add_u32 s36, s43, s8
	s_addc_u32 s37, s42, s9
	s_and_b64 s[8:9], vcc, exec
	s_cselect_b32 s29, s37, s3
	s_cselect_b32 s38, s36, s2
	s_add_u32 s6, s6, 0x40080
	s_addc_u32 s7, s7, 0
	s_add_u32 s39, s2, 0x100
	s_addc_u32 s40, s3, 0
	s_mov_b32 s41, -2
	s_add_u32 s2, s6, 0xfffc0080
	s_addc_u32 s3, s7, -1
	ds_read_b128 v[128:131], v208
	ds_read_b128 v[132:135], v208 offset:1024
	ds_read_b128 v[136:139], v208 offset:2048
	ds_read_b128 v[140:143], v208 offset:3072
	s_cmp_eq_u32 s41, 12
	s_cselect_b32 s9, s1, s3
	s_cselect_b32 s8, s31, s2
	s_cselect_b32 s3, s29, s40
	s_cselect_b32 s2, s38, s39
	ds_read_b128 v[144:147], v209
	ds_read_b128 v[148:151], v209 offset:1024
	ds_read_b128 v[152:155], v209 offset:2048
	ds_read_b128 v[156:159], v209 offset:3072
	ds_read_b128 v[180:183], v209 offset:4096
	ds_read_b128 v[184:187], v209 offset:5120
	ds_read_b128 v[188:191], v209 offset:6144
	ds_read_b128 v[192:195], v209 offset:7168
	s_barrier
	s_waitcnt lgkmcnt(0)
	v_mfma_f32_16x16x32_bf16 v[124:127], v[128:131], v[144:147], 0
	v_mfma_f32_16x16x32_bf16 v[120:123], v[136:139], v[144:147], 0
	v_mfma_f32_16x16x32_bf16 v[116:119], v[128:131], v[152:155], 0
	v_mfma_f32_16x16x32_bf16 v[112:115], v[136:139], v[152:155], 0
	v_mfma_f32_16x16x32_bf16 v[100:103], v[128:131], v[180:183], 0
	v_mfma_f32_16x16x32_bf16 v[96:99], v[136:139], v[180:183], 0
	v_mfma_f32_16x16x32_bf16 v[84:87], v[128:131], v[188:191], 0
	v_mfma_f32_16x16x32_bf16 v[80:83], v[136:139], v[188:191], 0
	v_mfma_f32_16x16x32_bf16 v[124:127], v[132:135], v[148:151], v[124:127]
	v_mfma_f32_16x16x32_bf16 v[120:123], v[140:143], v[148:151], v[120:123]
	v_mfma_f32_16x16x32_bf16 v[116:119], v[132:135], v[156:159], v[116:119]
	v_mfma_f32_16x16x32_bf16 v[112:115], v[140:143], v[156:159], v[112:115]
	v_mfma_f32_16x16x32_bf16 v[100:103], v[132:135], v[184:187], v[100:103]
	v_mfma_f32_16x16x32_bf16 v[96:99], v[140:143], v[184:187], v[96:99]
	v_mfma_f32_16x16x32_bf16 v[84:87], v[132:135], v[192:195], v[84:87]
	v_mfma_f32_16x16x32_bf16 v[80:83], v[140:143], v[192:195], v[80:83]
	s_barrier
	s_add_i32 m0, s21, 0xc000
	ds_read_b128 v[196:199], v208 offset:16384
	ds_read_b128 v[200:203], v208 offset:17408
	ds_read_b128 v[210:213], v208 offset:18432
	ds_read_b128 v[214:217], v208 offset:19456
	global_load_lds_dwordx4 v164, s[6:7]
	s_add_i32 m0, s21, 0xe000
	s_add_u32 s98, s2, 0x80
	s_addc_u32 s99, s3, 0
	global_load_lds_dwordx4 v166, s[6:7]
	s_barrier
	s_waitcnt lgkmcnt(0)
	v_mfma_f32_16x16x32_bf16 v[108:111], v[196:199], v[144:147], 0
	v_mfma_f32_16x16x32_bf16 v[104:107], v[210:213], v[144:147], 0
	v_mfma_f32_16x16x32_bf16 v[92:95], v[196:199], v[152:155], 0
	v_mfma_f32_16x16x32_bf16 v[88:91], v[210:213], v[152:155], 0
	v_mfma_f32_16x16x32_bf16 v[76:79], v[196:199], v[180:183], 0
	v_mfma_f32_16x16x32_bf16 v[72:75], v[210:213], v[180:183], 0
	v_mfma_f32_16x16x32_bf16 v[68:71], v[196:199], v[188:191], 0
	v_mfma_f32_16x16x32_bf16 v[64:67], v[210:213], v[188:191], 0
	v_mfma_f32_16x16x32_bf16 v[108:111], v[200:203], v[148:151], v[108:111]
	v_mfma_f32_16x16x32_bf16 v[104:107], v[214:217], v[148:151], v[104:107]
	v_mfma_f32_16x16x32_bf16 v[92:95], v[200:203], v[156:159], v[92:95]
	v_mfma_f32_16x16x32_bf16 v[88:91], v[214:217], v[156:159], v[88:91]
	v_mfma_f32_16x16x32_bf16 v[76:79], v[200:203], v[184:187], v[76:79]
	v_mfma_f32_16x16x32_bf16 v[72:75], v[214:217], v[184:187], v[72:75]
	v_mfma_f32_16x16x32_bf16 v[68:71], v[200:203], v[192:195], v[68:71]
	v_mfma_f32_16x16x32_bf16 v[64:67], v[214:217], v[192:195], v[64:67]
	s_add_u32 s100, s8, 0x80
	s_addc_u32 s101, s9, 0
	s_barrier
	ds_read_b128 v[144:147], v209 offset:16384
	ds_read_b128 v[148:151], v209 offset:17408
	ds_read_b128 v[152:155], v209 offset:18432
	ds_read_b128 v[156:159], v209 offset:19456
	ds_read_b128 v[180:183], v209 offset:20480
	ds_read_b128 v[184:187], v209 offset:21504
	ds_read_b128 v[188:191], v209 offset:22528
	ds_read_b128 v[192:195], v209 offset:23552
	s_add_i32 m0, s54, 0x10000
	s_nop 0
	global_load_lds_dwordx4 v160, s[2:3]
	s_add_i32 m0, s54, 0x12000
	s_nop 0
	global_load_lds_dwordx4 v162, s[2:3]
	s_barrier
	s_waitcnt lgkmcnt(0)
	v_mfma_f32_16x16x32_bf16 v[60:63], v[128:131], v[144:147], 0
	v_mfma_f32_16x16x32_bf16 v[56:59], v[136:139], v[144:147], 0
	v_mfma_f32_16x16x32_bf16 v[52:55], v[128:131], v[152:155], 0
	v_mfma_f32_16x16x32_bf16 v[48:51], v[136:139], v[152:155], 0
	v_mfma_f32_16x16x32_bf16 v[36:39], v[128:131], v[180:183], 0
	v_mfma_f32_16x16x32_bf16 v[32:35], v[136:139], v[180:183], 0
	v_mfma_f32_16x16x32_bf16 v[20:23], v[128:131], v[188:191], 0
	v_mfma_f32_16x16x32_bf16 v[16:19], v[136:139], v[188:191], 0
	v_mfma_f32_16x16x32_bf16 v[60:63], v[132:135], v[148:151], v[60:63]
	v_mfma_f32_16x16x32_bf16 v[56:59], v[140:143], v[148:151], v[56:59]
	v_mfma_f32_16x16x32_bf16 v[52:55], v[132:135], v[156:159], v[52:55]
	v_mfma_f32_16x16x32_bf16 v[48:51], v[140:143], v[156:159], v[48:51]
	v_mfma_f32_16x16x32_bf16 v[36:39], v[132:135], v[184:187], v[36:39]
	v_mfma_f32_16x16x32_bf16 v[32:35], v[140:143], v[184:187], v[32:35]
	v_mfma_f32_16x16x32_bf16 v[20:23], v[132:135], v[192:195], v[20:23]
	v_mfma_f32_16x16x32_bf16 v[16:19], v[140:143], v[192:195], v[16:19]
	s_barrier
	s_mov_b32 m0, s21
	s_nop 0
	global_load_lds_dwordx4 v160, s[8:9]
	s_mov_b32 m0, s55
	s_nop 0
	global_load_lds_dwordx4 v162, s[8:9]
	s_add_i32 m0, s54, 0x14000
	s_add_u32 s64, s2, 0x40000
	s_addc_u32 s65, s3, 0
	global_load_lds_dwordx4 v160, s[64:65]
	s_add_i32 m0, s54, 0x16000
	s_add_u32 s8, s8, 0x40000
	s_addc_u32 s9, s9, 0
	global_load_lds_dwordx4 v162, s[64:65]
	s_waitcnt vmcnt(6)
	s_barrier
	v_mfma_f32_16x16x32_bf16 v[44:47], v[196:199], v[144:147], 0
	v_mfma_f32_16x16x32_bf16 v[40:43], v[210:213], v[144:147], 0
	v_mfma_f32_16x16x32_bf16 v[28:31], v[196:199], v[152:155], 0
	v_mfma_f32_16x16x32_bf16 v[24:27], v[210:213], v[152:155], 0
	v_mfma_f32_16x16x32_bf16 v[12:15], v[196:199], v[180:183], 0
	v_mfma_f32_16x16x32_bf16 v[8:11], v[210:213], v[180:183], 0
	v_mfma_f32_16x16x32_bf16 v[4:7], v[196:199], v[188:191], 0
	v_mfma_f32_16x16x32_bf16 v[0:3], v[210:213], v[188:191], 0
	v_mfma_f32_16x16x32_bf16 v[44:47], v[200:203], v[148:151], v[44:47]
	v_mfma_f32_16x16x32_bf16 v[40:43], v[214:217], v[148:151], v[40:43]
	v_mfma_f32_16x16x32_bf16 v[28:31], v[200:203], v[156:159], v[28:31]
	v_mfma_f32_16x16x32_bf16 v[24:27], v[214:217], v[156:159], v[24:27]
	v_mfma_f32_16x16x32_bf16 v[12:15], v[200:203], v[184:187], v[12:15]
	v_mfma_f32_16x16x32_bf16 v[8:11], v[214:217], v[184:187], v[8:11]
	v_mfma_f32_16x16x32_bf16 v[4:7], v[200:203], v[192:195], v[4:7]
	v_mfma_f32_16x16x32_bf16 v[0:3], v[214:217], v[192:195], v[0:3]
	s_barrier
	ds_read_b128 v[128:131], v208 offset:32768
	ds_read_b128 v[132:135], v208 offset:33792
	ds_read_b128 v[136:139], v208 offset:34816
	ds_read_b128 v[140:143], v208 offset:35840
	ds_read_b128 v[144:147], v209 offset:32768
	ds_read_b128 v[148:151], v209 offset:33792
	ds_read_b128 v[152:155], v209 offset:34816
	ds_read_b128 v[156:159], v209 offset:35840
	ds_read_b128 v[180:183], v209 offset:36864
	ds_read_b128 v[184:187], v209 offset:37888
	ds_read_b128 v[188:191], v209 offset:38912
	ds_read_b128 v[192:195], v209 offset:39936
	s_barrier
	s_waitcnt lgkmcnt(0)
	v_mfma_f32_16x16x32_bf16 v[124:127], v[128:131], v[144:147], v[124:127]
	v_mfma_f32_16x16x32_bf16 v[120:123], v[136:139], v[144:147], v[120:123]
	v_mfma_f32_16x16x32_bf16 v[116:119], v[128:131], v[152:155], v[116:119]
	v_mfma_f32_16x16x32_bf16 v[112:115], v[136:139], v[152:155], v[112:115]
	v_mfma_f32_16x16x32_bf16 v[100:103], v[128:131], v[180:183], v[100:103]
	v_mfma_f32_16x16x32_bf16 v[96:99], v[136:139], v[180:183], v[96:99]
	v_mfma_f32_16x16x32_bf16 v[84:87], v[128:131], v[188:191], v[84:87]
	v_mfma_f32_16x16x32_bf16 v[80:83], v[136:139], v[188:191], v[80:83]
	v_mfma_f32_16x16x32_bf16 v[124:127], v[132:135], v[148:151], v[124:127]
	v_mfma_f32_16x16x32_bf16 v[120:123], v[140:143], v[148:151], v[120:123]
	v_mfma_f32_16x16x32_bf16 v[116:119], v[132:135], v[156:159], v[116:119]
	v_mfma_f32_16x16x32_bf16 v[112:115], v[140:143], v[156:159], v[112:115]
	v_mfma_f32_16x16x32_bf16 v[100:103], v[132:135], v[184:187], v[100:103]
	v_mfma_f32_16x16x32_bf16 v[96:99], v[140:143], v[184:187], v[96:99]
	v_mfma_f32_16x16x32_bf16 v[84:87], v[132:135], v[192:195], v[84:87]
	v_mfma_f32_16x16x32_bf16 v[80:83], v[140:143], v[192:195], v[80:83]
	s_barrier
	s_mov_b32 m0, s56
	ds_read_b128 v[196:199], v208 offset:49152
	ds_read_b128 v[200:203], v208 offset:50176
	ds_read_b128 v[210:213], v208 offset:51200
	ds_read_b128 v[214:217], v208 offset:52224
	global_load_lds_dwordx4 v160, s[8:9]
	s_mov_b32 m0, s57
	s_nop 0
	global_load_lds_dwordx4 v162, s[8:9]
	s_barrier
	s_waitcnt lgkmcnt(0)
	v_mfma_f32_16x16x32_bf16 v[108:111], v[196:199], v[144:147], v[108:111]
	v_mfma_f32_16x16x32_bf16 v[104:107], v[210:213], v[144:147], v[104:107]
	v_mfma_f32_16x16x32_bf16 v[92:95], v[196:199], v[152:155], v[92:95]
	v_mfma_f32_16x16x32_bf16 v[88:91], v[210:213], v[152:155], v[88:91]
	v_mfma_f32_16x16x32_bf16 v[76:79], v[196:199], v[180:183], v[76:79]
	v_mfma_f32_16x16x32_bf16 v[72:75], v[210:213], v[180:183], v[72:75]
	v_mfma_f32_16x16x32_bf16 v[68:71], v[196:199], v[188:191], v[68:71]
	v_mfma_f32_16x16x32_bf16 v[64:67], v[210:213], v[188:191], v[64:67]
	v_mfma_f32_16x16x32_bf16 v[108:111], v[200:203], v[148:151], v[108:111]
	v_mfma_f32_16x16x32_bf16 v[104:107], v[214:217], v[148:151], v[104:107]
	v_mfma_f32_16x16x32_bf16 v[92:95], v[200:203], v[156:159], v[92:95]
	v_mfma_f32_16x16x32_bf16 v[88:91], v[214:217], v[156:159], v[88:91]
	v_mfma_f32_16x16x32_bf16 v[76:79], v[200:203], v[184:187], v[76:79]
	v_mfma_f32_16x16x32_bf16 v[72:75], v[214:217], v[184:187], v[72:75]
	v_mfma_f32_16x16x32_bf16 v[68:71], v[200:203], v[192:195], v[68:71]
	v_mfma_f32_16x16x32_bf16 v[64:67], v[214:217], v[192:195], v[64:67]
	s_barrier
	ds_read_b128 v[144:147], v209 offset:49152
	ds_read_b128 v[148:151], v209 offset:50176
	ds_read_b128 v[152:155], v209 offset:51200
	ds_read_b128 v[156:159], v209 offset:52224
	ds_read_b128 v[180:183], v209 offset:53248
	ds_read_b128 v[184:187], v209 offset:54272
	ds_read_b128 v[188:191], v209 offset:55296
	ds_read_b128 v[192:195], v209 offset:56320
	s_add_i32 m0, s54, 0x18000
	s_nop 0
	global_load_lds_dwordx4 v160, s[98:99]
	s_add_i32 m0, s54, 0x1a000
	s_nop 0
	global_load_lds_dwordx4 v162, s[98:99]
	s_barrier
	s_waitcnt lgkmcnt(0)
	v_mfma_f32_16x16x32_bf16 v[60:63], v[128:131], v[144:147], v[60:63]
	v_mfma_f32_16x16x32_bf16 v[56:59], v[136:139], v[144:147], v[56:59]
	v_mfma_f32_16x16x32_bf16 v[52:55], v[128:131], v[152:155], v[52:55]
	v_mfma_f32_16x16x32_bf16 v[48:51], v[136:139], v[152:155], v[48:51]
	v_mfma_f32_16x16x32_bf16 v[36:39], v[128:131], v[180:183], v[36:39]
	v_mfma_f32_16x16x32_bf16 v[32:35], v[136:139], v[180:183], v[32:35]
	v_mfma_f32_16x16x32_bf16 v[20:23], v[128:131], v[188:191], v[20:23]
	v_mfma_f32_16x16x32_bf16 v[16:19], v[136:139], v[188:191], v[16:19]
	v_mfma_f32_16x16x32_bf16 v[60:63], v[132:135], v[148:151], v[60:63]
	v_mfma_f32_16x16x32_bf16 v[56:59], v[140:143], v[148:151], v[56:59]
	v_mfma_f32_16x16x32_bf16 v[52:55], v[132:135], v[156:159], v[52:55]
	v_mfma_f32_16x16x32_bf16 v[48:51], v[140:143], v[156:159], v[48:51]
	v_mfma_f32_16x16x32_bf16 v[36:39], v[132:135], v[184:187], v[36:39]
	v_mfma_f32_16x16x32_bf16 v[32:35], v[140:143], v[184:187], v[32:35]
	v_mfma_f32_16x16x32_bf16 v[20:23], v[132:135], v[192:195], v[20:23]
	v_mfma_f32_16x16x32_bf16 v[16:19], v[140:143], v[192:195], v[16:19]
	s_barrier
	s_mov_b32 m0, s60
	s_nop 0
	global_load_lds_dwordx4 v160, s[100:101]
	s_mov_b32 m0, s61
	s_nop 0
	global_load_lds_dwordx4 v162, s[100:101]
	s_add_i32 m0, s54, 0x1c000
	s_add_u32 s2, s2, 0x40080
	s_addc_u32 s3, s3, 0
	global_load_lds_dwordx4 v160, s[2:3]
	s_add_i32 m0, s54, 0x1e000
	s_add_i32 s41, s41, 2
	global_load_lds_dwordx4 v162, s[2:3]
	s_waitcnt vmcnt(6)
	s_barrier
	v_mfma_f32_16x16x32_bf16 v[44:47], v[196:199], v[144:147], v[44:47]
	v_mfma_f32_16x16x32_bf16 v[40:43], v[210:213], v[144:147], v[40:43]
	v_mfma_f32_16x16x32_bf16 v[28:31], v[196:199], v[152:155], v[28:31]
	v_mfma_f32_16x16x32_bf16 v[24:27], v[210:213], v[152:155], v[24:27]
	v_mfma_f32_16x16x32_bf16 v[12:15], v[196:199], v[180:183], v[12:15]
	v_mfma_f32_16x16x32_bf16 v[8:11], v[210:213], v[180:183], v[8:11]
	v_mfma_f32_16x16x32_bf16 v[4:7], v[196:199], v[188:191], v[4:7]
	v_mfma_f32_16x16x32_bf16 v[0:3], v[210:213], v[188:191], v[0:3]
	v_mfma_f32_16x16x32_bf16 v[44:47], v[200:203], v[148:151], v[44:47]
	v_mfma_f32_16x16x32_bf16 v[40:43], v[214:217], v[148:151], v[40:43]
	v_mfma_f32_16x16x32_bf16 v[28:31], v[200:203], v[156:159], v[28:31]
	v_mfma_f32_16x16x32_bf16 v[24:27], v[214:217], v[156:159], v[24:27]
	v_mfma_f32_16x16x32_bf16 v[12:15], v[200:203], v[184:187], v[12:15]
	v_mfma_f32_16x16x32_bf16 v[8:11], v[214:217], v[184:187], v[8:11]
	v_mfma_f32_16x16x32_bf16 v[4:7], v[200:203], v[192:195], v[4:7]
	v_mfma_f32_16x16x32_bf16 v[0:3], v[214:217], v[192:195], v[0:3]
	s_add_u32 s6, s6, 0x100
	s_addc_u32 s7, s7, 0
	s_add_u32 s39, s39, 0x100
	s_addc_u32 s40, s40, 0
	s_cmp_gt_u32 s41, 13
	s_barrier
.LBB0_355:
	s_add_u32 s2, s6, 0xfffc0080
	s_addc_u32 s3, s7, -1
	ds_read_b128 v[128:131], v208
	ds_read_b128 v[132:135], v208 offset:1024
	ds_read_b128 v[136:139], v208 offset:2048
	ds_read_b128 v[140:143], v208 offset:3072
	s_cmp_eq_u32 s41, 12
	s_cselect_b32 s9, s1, s3
	s_cselect_b32 s8, s31, s2
	s_cselect_b32 s3, s29, s40
	s_cselect_b32 s2, s38, s39
	ds_read_b128 v[144:147], v209
	ds_read_b128 v[148:151], v209 offset:1024
	ds_read_b128 v[152:155], v209 offset:2048
	ds_read_b128 v[156:159], v209 offset:3072
	ds_read_b128 v[180:183], v209 offset:4096
	ds_read_b128 v[184:187], v209 offset:5120
	ds_read_b128 v[188:191], v209 offset:6144
	ds_read_b128 v[192:195], v209 offset:7168
	s_barrier
	s_waitcnt lgkmcnt(0)
	v_mfma_f32_16x16x32_bf16 v[124:127], v[128:131], v[144:147], v[124:127]
	v_mfma_f32_16x16x32_bf16 v[120:123], v[136:139], v[144:147], v[120:123]
	v_mfma_f32_16x16x32_bf16 v[116:119], v[128:131], v[152:155], v[116:119]
	v_mfma_f32_16x16x32_bf16 v[112:115], v[136:139], v[152:155], v[112:115]
	v_mfma_f32_16x16x32_bf16 v[100:103], v[128:131], v[180:183], v[100:103]
	v_mfma_f32_16x16x32_bf16 v[96:99], v[136:139], v[180:183], v[96:99]
	v_mfma_f32_16x16x32_bf16 v[84:87], v[128:131], v[188:191], v[84:87]
	v_mfma_f32_16x16x32_bf16 v[80:83], v[136:139], v[188:191], v[80:83]
	v_mfma_f32_16x16x32_bf16 v[124:127], v[132:135], v[148:151], v[124:127]
	v_mfma_f32_16x16x32_bf16 v[120:123], v[140:143], v[148:151], v[120:123]
	v_mfma_f32_16x16x32_bf16 v[116:119], v[132:135], v[156:159], v[116:119]
	v_mfma_f32_16x16x32_bf16 v[112:115], v[140:143], v[156:159], v[112:115]
	v_mfma_f32_16x16x32_bf16 v[100:103], v[132:135], v[184:187], v[100:103]
	v_mfma_f32_16x16x32_bf16 v[96:99], v[140:143], v[184:187], v[96:99]
	v_mfma_f32_16x16x32_bf16 v[84:87], v[132:135], v[192:195], v[84:87]
	v_mfma_f32_16x16x32_bf16 v[80:83], v[140:143], v[192:195], v[80:83]
	s_barrier
	s_add_i32 m0, s21, 0xc000
	ds_read_b128 v[196:199], v208 offset:16384
	ds_read_b128 v[200:203], v208 offset:17408
	ds_read_b128 v[210:213], v208 offset:18432
	ds_read_b128 v[214:217], v208 offset:19456
	global_load_lds_dwordx4 v164, s[6:7]
	s_add_i32 m0, s21, 0xe000
	s_add_u32 s98, s2, 0x80
	s_addc_u32 s99, s3, 0
	global_load_lds_dwordx4 v166, s[6:7]
	s_barrier
	s_waitcnt lgkmcnt(0)
	v_mfma_f32_16x16x32_bf16 v[108:111], v[196:199], v[144:147], v[108:111]
	v_mfma_f32_16x16x32_bf16 v[104:107], v[210:213], v[144:147], v[104:107]
	v_mfma_f32_16x16x32_bf16 v[92:95], v[196:199], v[152:155], v[92:95]
	v_mfma_f32_16x16x32_bf16 v[88:91], v[210:213], v[152:155], v[88:91]
	v_mfma_f32_16x16x32_bf16 v[76:79], v[196:199], v[180:183], v[76:79]
	v_mfma_f32_16x16x32_bf16 v[72:75], v[210:213], v[180:183], v[72:75]
	v_mfma_f32_16x16x32_bf16 v[68:71], v[196:199], v[188:191], v[68:71]
	v_mfma_f32_16x16x32_bf16 v[64:67], v[210:213], v[188:191], v[64:67]
	v_mfma_f32_16x16x32_bf16 v[108:111], v[200:203], v[148:151], v[108:111]
	v_mfma_f32_16x16x32_bf16 v[104:107], v[214:217], v[148:151], v[104:107]
	v_mfma_f32_16x16x32_bf16 v[92:95], v[200:203], v[156:159], v[92:95]
	v_mfma_f32_16x16x32_bf16 v[88:91], v[214:217], v[156:159], v[88:91]
	v_mfma_f32_16x16x32_bf16 v[76:79], v[200:203], v[184:187], v[76:79]
	v_mfma_f32_16x16x32_bf16 v[72:75], v[214:217], v[184:187], v[72:75]
	v_mfma_f32_16x16x32_bf16 v[68:71], v[200:203], v[192:195], v[68:71]
	v_mfma_f32_16x16x32_bf16 v[64:67], v[214:217], v[192:195], v[64:67]
	s_add_u32 s100, s8, 0x80
	s_addc_u32 s101, s9, 0
	s_barrier
	ds_read_b128 v[144:147], v209 offset:16384
	ds_read_b128 v[148:151], v209 offset:17408
	ds_read_b128 v[152:155], v209 offset:18432
	ds_read_b128 v[156:159], v209 offset:19456
	ds_read_b128 v[180:183], v209 offset:20480
	ds_read_b128 v[184:187], v209 offset:21504
	ds_read_b128 v[188:191], v209 offset:22528
	ds_read_b128 v[192:195], v209 offset:23552
	s_add_i32 m0, s54, 0x10000
	s_nop 0
	global_load_lds_dwordx4 v160, s[2:3]
	s_add_i32 m0, s54, 0x12000
	s_nop 0
	global_load_lds_dwordx4 v162, s[2:3]
	s_barrier
	s_waitcnt lgkmcnt(0)
	v_mfma_f32_16x16x32_bf16 v[60:63], v[128:131], v[144:147], v[60:63]
	v_mfma_f32_16x16x32_bf16 v[56:59], v[136:139], v[144:147], v[56:59]
	v_mfma_f32_16x16x32_bf16 v[52:55], v[128:131], v[152:155], v[52:55]
	v_mfma_f32_16x16x32_bf16 v[48:51], v[136:139], v[152:155], v[48:51]
	v_mfma_f32_16x16x32_bf16 v[36:39], v[128:131], v[180:183], v[36:39]
	v_mfma_f32_16x16x32_bf16 v[32:35], v[136:139], v[180:183], v[32:35]
	v_mfma_f32_16x16x32_bf16 v[20:23], v[128:131], v[188:191], v[20:23]
	v_mfma_f32_16x16x32_bf16 v[16:19], v[136:139], v[188:191], v[16:19]
	v_mfma_f32_16x16x32_bf16 v[60:63], v[132:135], v[148:151], v[60:63]
	v_mfma_f32_16x16x32_bf16 v[56:59], v[140:143], v[148:151], v[56:59]
	v_mfma_f32_16x16x32_bf16 v[52:55], v[132:135], v[156:159], v[52:55]
	v_mfma_f32_16x16x32_bf16 v[48:51], v[140:143], v[156:159], v[48:51]
	v_mfma_f32_16x16x32_bf16 v[36:39], v[132:135], v[184:187], v[36:39]
	v_mfma_f32_16x16x32_bf16 v[32:35], v[140:143], v[184:187], v[32:35]
	v_mfma_f32_16x16x32_bf16 v[20:23], v[132:135], v[192:195], v[20:23]
	v_mfma_f32_16x16x32_bf16 v[16:19], v[140:143], v[192:195], v[16:19]
	s_barrier
	s_mov_b32 m0, s21
	s_nop 0
	global_load_lds_dwordx4 v160, s[8:9]
	s_mov_b32 m0, s55
	s_nop 0
	global_load_lds_dwordx4 v162, s[8:9]
	s_add_i32 m0, s54, 0x14000
	s_add_u32 s64, s2, 0x40000
	s_addc_u32 s65, s3, 0
	global_load_lds_dwordx4 v160, s[64:65]
	s_add_i32 m0, s54, 0x16000
	s_add_u32 s8, s8, 0x40000
	s_addc_u32 s9, s9, 0
	global_load_lds_dwordx4 v162, s[64:65]
	s_waitcnt vmcnt(6)
	s_barrier
	v_mfma_f32_16x16x32_bf16 v[44:47], v[196:199], v[144:147], v[44:47]
	v_mfma_f32_16x16x32_bf16 v[40:43], v[210:213], v[144:147], v[40:43]
	v_mfma_f32_16x16x32_bf16 v[28:31], v[196:199], v[152:155], v[28:31]
	v_mfma_f32_16x16x32_bf16 v[24:27], v[210:213], v[152:155], v[24:27]
	v_mfma_f32_16x16x32_bf16 v[12:15], v[196:199], v[180:183], v[12:15]
	v_mfma_f32_16x16x32_bf16 v[8:11], v[210:213], v[180:183], v[8:11]
	v_mfma_f32_16x16x32_bf16 v[4:7], v[196:199], v[188:191], v[4:7]
	v_mfma_f32_16x16x32_bf16 v[0:3], v[210:213], v[188:191], v[0:3]
	v_mfma_f32_16x16x32_bf16 v[44:47], v[200:203], v[148:151], v[44:47]
	v_mfma_f32_16x16x32_bf16 v[40:43], v[214:217], v[148:151], v[40:43]
	v_mfma_f32_16x16x32_bf16 v[28:31], v[200:203], v[156:159], v[28:31]
	v_mfma_f32_16x16x32_bf16 v[24:27], v[214:217], v[156:159], v[24:27]
	v_mfma_f32_16x16x32_bf16 v[12:15], v[200:203], v[184:187], v[12:15]
	v_mfma_f32_16x16x32_bf16 v[8:11], v[214:217], v[184:187], v[8:11]
	v_mfma_f32_16x16x32_bf16 v[4:7], v[200:203], v[192:195], v[4:7]
	v_mfma_f32_16x16x32_bf16 v[0:3], v[214:217], v[192:195], v[0:3]
	s_barrier
	ds_read_b128 v[128:131], v208 offset:32768
	ds_read_b128 v[132:135], v208 offset:33792
	ds_read_b128 v[136:139], v208 offset:34816
	ds_read_b128 v[140:143], v208 offset:35840
	ds_read_b128 v[144:147], v209 offset:32768
	ds_read_b128 v[148:151], v209 offset:33792
	ds_read_b128 v[152:155], v209 offset:34816
	ds_read_b128 v[156:159], v209 offset:35840
	ds_read_b128 v[180:183], v209 offset:36864
	ds_read_b128 v[184:187], v209 offset:37888
	ds_read_b128 v[188:191], v209 offset:38912
	ds_read_b128 v[192:195], v209 offset:39936
	s_barrier
	s_waitcnt lgkmcnt(0)
	v_mfma_f32_16x16x32_bf16 v[124:127], v[128:131], v[144:147], v[124:127]
	v_mfma_f32_16x16x32_bf16 v[120:123], v[136:139], v[144:147], v[120:123]
	v_mfma_f32_16x16x32_bf16 v[116:119], v[128:131], v[152:155], v[116:119]
	v_mfma_f32_16x16x32_bf16 v[112:115], v[136:139], v[152:155], v[112:115]
	v_mfma_f32_16x16x32_bf16 v[100:103], v[128:131], v[180:183], v[100:103]
	v_mfma_f32_16x16x32_bf16 v[96:99], v[136:139], v[180:183], v[96:99]
	v_mfma_f32_16x16x32_bf16 v[84:87], v[128:131], v[188:191], v[84:87]
	v_mfma_f32_16x16x32_bf16 v[80:83], v[136:139], v[188:191], v[80:83]
	v_mfma_f32_16x16x32_bf16 v[124:127], v[132:135], v[148:151], v[124:127]
	v_mfma_f32_16x16x32_bf16 v[120:123], v[140:143], v[148:151], v[120:123]
	v_mfma_f32_16x16x32_bf16 v[116:119], v[132:135], v[156:159], v[116:119]
	v_mfma_f32_16x16x32_bf16 v[112:115], v[140:143], v[156:159], v[112:115]
	v_mfma_f32_16x16x32_bf16 v[100:103], v[132:135], v[184:187], v[100:103]
	v_mfma_f32_16x16x32_bf16 v[96:99], v[140:143], v[184:187], v[96:99]
	v_mfma_f32_16x16x32_bf16 v[84:87], v[132:135], v[192:195], v[84:87]
	v_mfma_f32_16x16x32_bf16 v[80:83], v[140:143], v[192:195], v[80:83]
	s_barrier
	s_mov_b32 m0, s56
	ds_read_b128 v[196:199], v208 offset:49152
	ds_read_b128 v[200:203], v208 offset:50176
	ds_read_b128 v[210:213], v208 offset:51200
	ds_read_b128 v[214:217], v208 offset:52224
	global_load_lds_dwordx4 v160, s[8:9]
	s_mov_b32 m0, s57
	s_nop 0
	global_load_lds_dwordx4 v162, s[8:9]
	s_barrier
	s_waitcnt lgkmcnt(0)
	v_mfma_f32_16x16x32_bf16 v[108:111], v[196:199], v[144:147], v[108:111]
	v_mfma_f32_16x16x32_bf16 v[104:107], v[210:213], v[144:147], v[104:107]
	v_mfma_f32_16x16x32_bf16 v[92:95], v[196:199], v[152:155], v[92:95]
	v_mfma_f32_16x16x32_bf16 v[88:91], v[210:213], v[152:155], v[88:91]
	v_mfma_f32_16x16x32_bf16 v[76:79], v[196:199], v[180:183], v[76:79]
	v_mfma_f32_16x16x32_bf16 v[72:75], v[210:213], v[180:183], v[72:75]
	v_mfma_f32_16x16x32_bf16 v[68:71], v[196:199], v[188:191], v[68:71]
	v_mfma_f32_16x16x32_bf16 v[64:67], v[210:213], v[188:191], v[64:67]
	v_mfma_f32_16x16x32_bf16 v[108:111], v[200:203], v[148:151], v[108:111]
	v_mfma_f32_16x16x32_bf16 v[104:107], v[214:217], v[148:151], v[104:107]
	v_mfma_f32_16x16x32_bf16 v[92:95], v[200:203], v[156:159], v[92:95]
	v_mfma_f32_16x16x32_bf16 v[88:91], v[214:217], v[156:159], v[88:91]
	v_mfma_f32_16x16x32_bf16 v[76:79], v[200:203], v[184:187], v[76:79]
	v_mfma_f32_16x16x32_bf16 v[72:75], v[214:217], v[184:187], v[72:75]
	v_mfma_f32_16x16x32_bf16 v[68:71], v[200:203], v[192:195], v[68:71]
	v_mfma_f32_16x16x32_bf16 v[64:67], v[214:217], v[192:195], v[64:67]
	s_barrier
	ds_read_b128 v[144:147], v209 offset:49152
	ds_read_b128 v[148:151], v209 offset:50176
	ds_read_b128 v[152:155], v209 offset:51200
	ds_read_b128 v[156:159], v209 offset:52224
	ds_read_b128 v[180:183], v209 offset:53248
	ds_read_b128 v[184:187], v209 offset:54272
	ds_read_b128 v[188:191], v209 offset:55296
	ds_read_b128 v[192:195], v209 offset:56320
	s_add_i32 m0, s54, 0x18000
	s_nop 0
	global_load_lds_dwordx4 v160, s[98:99]
	s_add_i32 m0, s54, 0x1a000
	s_nop 0
	global_load_lds_dwordx4 v162, s[98:99]
	s_barrier
	s_waitcnt lgkmcnt(0)
	v_mfma_f32_16x16x32_bf16 v[60:63], v[128:131], v[144:147], v[60:63]
	v_mfma_f32_16x16x32_bf16 v[56:59], v[136:139], v[144:147], v[56:59]
	v_mfma_f32_16x16x32_bf16 v[52:55], v[128:131], v[152:155], v[52:55]
	v_mfma_f32_16x16x32_bf16 v[48:51], v[136:139], v[152:155], v[48:51]
	v_mfma_f32_16x16x32_bf16 v[36:39], v[128:131], v[180:183], v[36:39]
	v_mfma_f32_16x16x32_bf16 v[32:35], v[136:139], v[180:183], v[32:35]
	v_mfma_f32_16x16x32_bf16 v[20:23], v[128:131], v[188:191], v[20:23]
	v_mfma_f32_16x16x32_bf16 v[16:19], v[136:139], v[188:191], v[16:19]
	v_mfma_f32_16x16x32_bf16 v[60:63], v[132:135], v[148:151], v[60:63]
	v_mfma_f32_16x16x32_bf16 v[56:59], v[140:143], v[148:151], v[56:59]
	v_mfma_f32_16x16x32_bf16 v[52:55], v[132:135], v[156:159], v[52:55]
	v_mfma_f32_16x16x32_bf16 v[48:51], v[140:143], v[156:159], v[48:51]
	v_mfma_f32_16x16x32_bf16 v[36:39], v[132:135], v[184:187], v[36:39]
	v_mfma_f32_16x16x32_bf16 v[32:35], v[140:143], v[184:187], v[32:35]
	v_mfma_f32_16x16x32_bf16 v[20:23], v[132:135], v[192:195], v[20:23]
	v_mfma_f32_16x16x32_bf16 v[16:19], v[140:143], v[192:195], v[16:19]
	s_barrier
	s_mov_b32 m0, s60
	s_nop 0
	global_load_lds_dwordx4 v160, s[100:101]
	s_mov_b32 m0, s61
	s_nop 0
	global_load_lds_dwordx4 v162, s[100:101]
	s_add_i32 m0, s54, 0x1c000
	s_add_u32 s2, s2, 0x40080
	s_addc_u32 s3, s3, 0
	global_load_lds_dwordx4 v160, s[2:3]
	s_add_i32 m0, s54, 0x1e000
	s_add_i32 s41, s41, 2
	global_load_lds_dwordx4 v162, s[2:3]
	s_waitcnt vmcnt(6)
	s_barrier
	v_mfma_f32_16x16x32_bf16 v[44:47], v[196:199], v[144:147], v[44:47]
	v_mfma_f32_16x16x32_bf16 v[40:43], v[210:213], v[144:147], v[40:43]
	v_mfma_f32_16x16x32_bf16 v[28:31], v[196:199], v[152:155], v[28:31]
	v_mfma_f32_16x16x32_bf16 v[24:27], v[210:213], v[152:155], v[24:27]
	v_mfma_f32_16x16x32_bf16 v[12:15], v[196:199], v[180:183], v[12:15]
	v_mfma_f32_16x16x32_bf16 v[8:11], v[210:213], v[180:183], v[8:11]
	v_mfma_f32_16x16x32_bf16 v[4:7], v[196:199], v[188:191], v[4:7]
	v_mfma_f32_16x16x32_bf16 v[0:3], v[210:213], v[188:191], v[0:3]
	v_mfma_f32_16x16x32_bf16 v[44:47], v[200:203], v[148:151], v[44:47]
	v_mfma_f32_16x16x32_bf16 v[40:43], v[214:217], v[148:151], v[40:43]
	v_mfma_f32_16x16x32_bf16 v[28:31], v[200:203], v[156:159], v[28:31]
	v_mfma_f32_16x16x32_bf16 v[24:27], v[214:217], v[156:159], v[24:27]
	v_mfma_f32_16x16x32_bf16 v[12:15], v[200:203], v[184:187], v[12:15]
	v_mfma_f32_16x16x32_bf16 v[8:11], v[214:217], v[184:187], v[8:11]
	v_mfma_f32_16x16x32_bf16 v[4:7], v[200:203], v[192:195], v[4:7]
	v_mfma_f32_16x16x32_bf16 v[0:3], v[214:217], v[192:195], v[0:3]
	s_add_u32 s6, s6, 0x100
	s_addc_u32 s7, s7, 0
	s_add_u32 s39, s39, 0x100
	s_addc_u32 s40, s40, 0
	s_cmp_gt_u32 s41, 13
	s_barrier
	s_cbranch_scc0 .LBB0_355
	s_lshl_b32 s1, s0, 8
	v_mov_b32_e32 v211, v206
	v_mov_b32_e32 v210, v207
	s_add_i32 s1, s1, s59
	s_cmp_lt_i32 s20, 3
	v_add_u32_e32 v180, s1, v211
	s_mov_b64 s[2:3], -1
	s_cbranch_scc0 .LBB0_490
	s_cmp_gt_i32 s0, 15
	s_cselect_b64 s[2:3], -1, 0
	s_cmp_lt_i32 s0, 16
	s_cselect_b64 s[38:39], -1, 0
	s_cmp_eq_u32 s20, 2
	s_cselect_b64 s[8:9], -1, 0
	s_cmp_lg_u32 s20, 2
	s_cselect_b64 s[0:1], -1, 0
	s_and_b64 s[40:41], s[8:9], s[22:23]
	v_lshlrev_b32_e32 v182, 2, v210
	s_mov_b64 s[6:7], -1
	s_and_b64 vcc, exec, s[40:41]
	v_ashrrev_i32_e32 v183, 31, v182
	s_cbranch_vccnz .LBB0_447
	s_and_b64 s[6:7], s[8:9], exec
	s_cselect_b32 s6, s46, s44
	s_cselect_b32 s7, s47, s45
	v_mov_b32_e32 v128, s7
	v_mov_b32_e32 v129, s6
	v_lshl_add_u64 v[128:129], v[182:183], 2, v[128:129]
	global_load_dwordx4 v[140:143], v[128:129], off
	global_load_dwordx4 v[136:139], v[128:129], off offset:64
	global_load_dwordx4 v[132:135], v[128:129], off offset:128
	s_nop 0
	global_load_dwordx4 v[128:131], v[128:129], off offset:192
	v_mul_f32_e32 v144, v125, v125
	v_mul_f32_e32 v145, v127, v127
	v_fmac_f32_e32 v144, v124, v124
	v_fmac_f32_e32 v145, v126, v126
	v_add_f32_e32 v144, v144, v145
	v_mul_f32_e32 v145, v121, v121
	v_mul_f32_e32 v146, v123, v123
	v_fmac_f32_e32 v145, v120, v120
	v_fmac_f32_e32 v146, v122, v122
	v_add_f32_e32 v145, v145, v146
	v_add_f32_e32 v144, v144, v145
	v_mul_f32_e32 v145, v109, v109
	v_mul_f32_e32 v146, v111, v111
	v_fmac_f32_e32 v145, v108, v108
	v_fmac_f32_e32 v146, v110, v110
	v_add_f32_e32 v145, v145, v146
	v_add_f32_e32 v144, v144, v145
	v_mul_f32_e32 v145, v105, v105
	v_mul_f32_e32 v146, v107, v107
	v_fmac_f32_e32 v145, v104, v104
	v_fmac_f32_e32 v146, v106, v106
	v_add_f32_e32 v145, v145, v146
	v_add_f32_e32 v144, v144, v145
	v_mov_b32_e32 v145, v144
	s_nop 1
	v_permlane16_swap_b32_e32 v144, v145
	v_add_f32_e32 v144, v144, v145
	v_mov_b32_e32 v145, v144
	s_nop 1
	v_permlane32_swap_b32_e32 v144, v145
	v_add_f32_e32 v144, v144, v145
	v_fmamk_f32 v144, v144, 0x3c800000, v225
	v_cmp_gt_f32_e32 vcc, s93, v144
	v_mul_f32_e32 v145, 0x4b800000, v144
	v_and_b32_e32 v202, 63, v211
	v_cndmask_b32_e32 v144, v144, v145, vcc
	v_rsq_f32_e32 v144, v144
	v_cndmask_b32_e64 v168, 0, 1, s[2:3]
	v_cmp_ne_u32_e64 s[6:7], 1, v168
	v_lshlrev_b32_e32 v186, 7, v202
	v_mul_f32_e32 v145, 0x45800000, v144
	v_cndmask_b32_e32 v152, v144, v145, vcc
	v_pk_mul_f32 v[144:145], v[124:125], v[152:153] op_sel_hi:[1,0]
	v_pk_mul_f32 v[146:147], v[126:127], v[152:153] op_sel_hi:[1,0]
	v_pk_mul_f32 v[148:149], v[108:109], v[152:153] op_sel_hi:[1,0]
	v_pk_mul_f32 v[150:151], v[110:111], v[152:153] op_sel_hi:[1,0]
	v_pk_mul_f32 v[184:185], v[104:105], v[152:153] op_sel_hi:[1,0]
	s_andn2_b64 vcc, exec, s[2:3]
	s_waitcnt vmcnt(0)
	v_pk_mul_f32 v[158:159], v[142:143], v[146:147]
	v_pk_mul_f32 v[156:157], v[140:141], v[144:145]
	v_pk_mul_f32 v[144:145], v[120:121], v[152:153] op_sel_hi:[1,0]
	v_pk_mul_f32 v[146:147], v[122:123], v[152:153] op_sel_hi:[1,0]
	v_pk_mul_f32 v[152:153], v[106:107], v[152:153] op_sel_hi:[1,0]
	v_pk_mul_f32 v[146:147], v[138:139], v[146:147]
	v_pk_mul_f32 v[144:145], v[136:137], v[144:145]
	v_pk_mul_f32 v[150:151], v[134:135], v[150:151]
	v_pk_mul_f32 v[148:149], v[132:133], v[148:149]
	v_pk_mul_f32 v[154:155], v[130:131], v[152:153]
	v_pk_mul_f32 v[152:153], v[128:129], v[184:185]
	v_lshl_add_u64 v[184:185], v[182:183], 3, s[18:19]
	s_cbranch_vccnz .LBB0_360
	v_lshlrev_b32_e32 v168, 1, v180
	v_and_b32_e32 v168, 0xf80, v168
	v_lshl_add_u64 v[188:189], v[184:185], 0, v[168:169]
	global_load_dwordx4 v[190:193], v[188:189], off offset:16
	global_load_dwordx4 v[194:197], v[188:189], off
	v_mov_b32_e32 v187, v169
	s_waitcnt vmcnt(0)
	v_mul_f32_e32 v198, v158, v190
	v_mov_b32_e32 v188, v194
	v_mov_b32_e32 v189, v196
	v_mov_b32_e32 v196, v195
	v_mul_f32_e32 v200, v146, v191
	v_mul_f32_e32 v204, v146, v190
	v_mul_f32_e32 v212, v158, v191
	v_mov_b32_e32 v146, v159
	v_mov_b32_e32 v158, v147
	v_pk_mul_f32 v[194:195], v[144:145], v[196:197]
	v_pk_mul_f32 v[144:145], v[144:145], v[188:189]
	v_pk_mul_f32 v[190:191], v[146:147], v[192:193]
	v_pk_mul_f32 v[146:147], v[158:159], v[192:193]
	v_lshl_add_u64 v[192:193], v[184:185], 0, v[186:187]
	v_mov_b32_e32 v199, v190
	v_mov_b32_e32 v201, v191
	v_pk_fma_f32 v[190:191], v[156:157], v[188:189], v[194:195] neg_lo:[0,0,1] neg_hi:[0,0,1]
	v_pk_fma_f32 v[144:145], v[156:157], v[196:197], v[144:145]
	global_load_dwordx4 v[156:159], v[192:193], off offset:16
	s_nop 0
	global_load_dwordx4 v[192:195], v[192:193], off
	v_pk_add_f32 v[188:189], v[198:199], v[200:201] neg_lo:[0,1] neg_hi:[0,1]
	v_mov_b32_e32 v213, v147
	v_mov_b32_e32 v205, v146
	v_pk_add_f32 v[146:147], v[212:213], v[204:205]
	s_waitcnt vmcnt(0)
	v_mul_f32_e32 v198, v150, v156
	v_mul_f32_e32 v200, v154, v157
	v_mul_f32_e32 v156, v154, v156
	v_mov_b32_e32 v154, v151
	v_mov_b32_e32 v197, v194
	v_mov_b32_e32 v194, v193
	v_mul_f32_e32 v204, v150, v157
	v_pk_mul_f32 v[212:213], v[154:155], v[158:159]
	v_mov_b32_e32 v150, v155
	v_mov_b32_e32 v196, v192
	v_pk_mul_f32 v[192:193], v[152:153], v[194:195]
	v_mov_b32_e32 v199, v212
	v_mov_b32_e32 v201, v213
	v_pk_mul_f32 v[150:151], v[150:151], v[158:159]
	v_pk_mul_f32 v[152:153], v[152:153], v[196:197]
	v_pk_fma_f32 v[192:193], v[148:149], v[196:197], v[192:193] neg_lo:[0,0,1] neg_hi:[0,0,1]
	v_pk_add_f32 v[196:197], v[198:199], v[200:201] neg_lo:[0,1] neg_hi:[0,1]
	v_mov_b32_e32 v205, v151
	v_mov_b32_e32 v157, v150
	v_pk_fma_f32 v[152:153], v[148:149], v[194:195], v[152:153]
	v_pk_add_f32 v[154:155], v[204:205], v[156:157]
	v_mov_b32_e32 v148, v192
	v_mov_b32_e32 v149, v193
	v_mov_b32_e32 v150, v196
	v_mov_b32_e32 v151, v197
	v_mov_b32_e32 v156, v190
	v_mov_b32_e32 v157, v191
	v_mov_b32_e32 v158, v188
	v_mov_b32_e32 v159, v189

.LBB0_677:
	s_ashr_i32 s23, s22, 31
	v_cmp_lt_i64_e32 vcc, s[24:25], v[174:175]
	s_lshl_b64 s[24:25], s[22:23], 19
	s_add_u32 s24, s36, s24
	s_addc_u32 s25, s37, s25
	s_and_b64 s[26:27], vcc, exec
	s_cselect_b32 s1, s25, s9
	s_cselect_b32 s7, s24, s8
	s_ashr_i32 s21, s20, 31
	s_lshl_b64 s[26:27], s[20:21], 19
	s_add_u32 s26, s38, s26
	s_addc_u32 s27, s39, s27
	s_and_b64 s[28:29], vcc, exec
	s_cselect_b32 s21, s27, s3
	s_cselect_b32 s23, s26, s2
	s_add_u32 s8, s8, 0x40080
	s_addc_u32 s9, s9, 0
	s_add_u32 s56, s2, 0x100
	s_addc_u32 s57, s3, 0
	s_mov_b32 s58, -2
	s_add_u32 s2, s8, 0xfffc0080
	s_addc_u32 s3, s9, -1
	ds_read_b128 v[48:51], v206
	ds_read_b128 v[52:55], v206 offset:1024
	ds_read_b128 v[60:63], v206 offset:2048
	ds_read_b128 v[68:71], v206 offset:3072
	s_cmp_eq_u32 s58, 12
	s_cselect_b32 s29, s1, s3
	s_cselect_b32 s28, s7, s2
	s_cselect_b32 s3, s21, s57
	s_cselect_b32 s2, s23, s56
	ds_read_b128 v[72:75], v207
	ds_read_b128 v[76:79], v207 offset:1024
	ds_read_b128 v[80:83], v207 offset:2048
	ds_read_b128 v[84:87], v207 offset:3072
	ds_read_b128 v[160:163], v207 offset:4096
	ds_read_b128 v[164:167], v207 offset:5120
	ds_read_b128 v[192:195], v207 offset:6144
	ds_read_b128 v[196:199], v207 offset:7168
	s_barrier
	s_waitcnt lgkmcnt(0)
	v_mfma_f32_16x16x32_bf16 v[156:159], v[48:51], v[72:75], 0
	v_mfma_f32_16x16x32_bf16 v[152:155], v[60:63], v[72:75], 0
	v_mfma_f32_16x16x32_bf16 v[140:143], v[48:51], v[80:83], 0
	v_mfma_f32_16x16x32_bf16 v[136:139], v[60:63], v[80:83], 0
	v_mfma_f32_16x16x32_bf16 v[124:127], v[48:51], v[160:163], 0
	v_mfma_f32_16x16x32_bf16 v[120:123], v[60:63], v[160:163], 0
	v_mfma_f32_16x16x32_bf16 v[108:111], v[48:51], v[192:195], 0
	v_mfma_f32_16x16x32_bf16 v[104:107], v[60:63], v[192:195], 0
	v_mfma_f32_16x16x32_bf16 v[156:159], v[52:55], v[76:79], v[156:159]
	v_mfma_f32_16x16x32_bf16 v[152:155], v[68:71], v[76:79], v[152:155]
	v_mfma_f32_16x16x32_bf16 v[140:143], v[52:55], v[84:87], v[140:143]
	v_mfma_f32_16x16x32_bf16 v[136:139], v[68:71], v[84:87], v[136:139]
	v_mfma_f32_16x16x32_bf16 v[124:127], v[52:55], v[164:167], v[124:127]
	v_mfma_f32_16x16x32_bf16 v[120:123], v[68:71], v[164:167], v[120:123]
	v_mfma_f32_16x16x32_bf16 v[108:111], v[52:55], v[196:199], v[108:111]
	v_mfma_f32_16x16x32_bf16 v[104:107], v[68:71], v[196:199], v[104:107]
	s_barrier
	s_add_i32 m0, s41, 0xc000
	ds_read_b128 v[200:203], v206 offset:16384
	ds_read_b128 v[208:211], v206 offset:17408
	ds_read_b128 v[212:215], v206 offset:18432
	ds_read_b128 v[216:219], v206 offset:19456
	global_load_lds_dwordx4 v188, s[8:9]
	s_add_i32 m0, s41, 0xe000
	s_add_u32 s98, s2, 0x80
	s_addc_u32 s99, s3, 0
	global_load_lds_dwordx4 v190, s[8:9]
	s_barrier
	s_waitcnt lgkmcnt(0)
	v_mfma_f32_16x16x32_bf16 v[148:151], v[200:203], v[72:75], 0
	v_mfma_f32_16x16x32_bf16 v[72:75], v[212:215], v[72:75], 0
	v_mfma_f32_16x16x32_bf16 v[148:151], v[208:211], v[76:79], v[148:151]
	v_mfma_f32_16x16x32_bf16 v[72:75], v[216:219], v[76:79], v[72:75]
	v_mfma_f32_16x16x32_bf16 v[76:79], v[200:203], v[80:83], 0
	v_mfma_f32_16x16x32_bf16 v[80:83], v[212:215], v[80:83], 0
	v_mfma_f32_16x16x32_bf16 v[112:115], v[212:215], v[160:163], 0
	v_mfma_f32_16x16x32_bf16 v[100:103], v[200:203], v[192:195], 0
	v_mfma_f32_16x16x32_bf16 v[96:99], v[212:215], v[192:195], 0
	v_mfma_f32_16x16x32_bf16 v[76:79], v[208:211], v[84:87], v[76:79]
	v_mfma_f32_16x16x32_bf16 v[80:83], v[216:219], v[84:87], v[80:83]
	v_mfma_f32_16x16x32_bf16 v[84:87], v[200:203], v[160:163], 0
	v_mfma_f32_16x16x32_bf16 v[112:115], v[216:219], v[164:167], v[112:115]
	v_mfma_f32_16x16x32_bf16 v[100:103], v[208:211], v[196:199], v[100:103]
	v_mfma_f32_16x16x32_bf16 v[96:99], v[216:219], v[196:199], v[96:99]
	v_mfma_f32_16x16x32_bf16 v[84:87], v[208:211], v[164:167], v[84:87]
	s_add_u32 s100, s28, 0x80
	s_addc_u32 s101, s29, 0
	s_barrier
	ds_read_b128 v[116:119], v207 offset:16384
	ds_read_b128 v[128:131], v207 offset:17408
	ds_read_b128 v[132:135], v207 offset:18432
	ds_read_b128 v[144:147], v207 offset:19456
	ds_read_b128 v[160:163], v207 offset:20480
	ds_read_b128 v[164:167], v207 offset:21504
	ds_read_b128 v[192:195], v207 offset:22528
	ds_read_b128 v[196:199], v207 offset:23552
	s_add_i32 m0, s40, 0x10000
	s_nop 0
	global_load_lds_dwordx4 v182, s[2:3]
	s_add_i32 m0, s40, 0x12000
	s_nop 0
	global_load_lds_dwordx4 v186, s[2:3]
	s_barrier
	s_waitcnt lgkmcnt(0)
	v_mfma_f32_16x16x32_bf16 v[92:95], v[48:51], v[116:119], 0
	v_mfma_f32_16x16x32_bf16 v[88:91], v[60:63], v[116:119], 0
	v_mfma_f32_16x16x32_bf16 v[44:47], v[48:51], v[132:135], 0
	v_mfma_f32_16x16x32_bf16 v[40:43], v[60:63], v[132:135], 0
	v_mfma_f32_16x16x32_bf16 v[28:31], v[48:51], v[160:163], 0
	v_mfma_f32_16x16x32_bf16 v[24:27], v[60:63], v[160:163], 0
	v_mfma_f32_16x16x32_bf16 v[12:15], v[48:51], v[192:195], 0
	v_mfma_f32_16x16x32_bf16 v[8:11], v[60:63], v[192:195], 0
	v_mfma_f32_16x16x32_bf16 v[92:95], v[52:55], v[128:131], v[92:95]
	v_mfma_f32_16x16x32_bf16 v[88:91], v[68:71], v[128:131], v[88:91]
	v_mfma_f32_16x16x32_bf16 v[44:47], v[52:55], v[144:147], v[44:47]
	v_mfma_f32_16x16x32_bf16 v[40:43], v[68:71], v[144:147], v[40:43]
	v_mfma_f32_16x16x32_bf16 v[28:31], v[52:55], v[164:167], v[28:31]
	v_mfma_f32_16x16x32_bf16 v[24:27], v[68:71], v[164:167], v[24:27]
	v_mfma_f32_16x16x32_bf16 v[12:15], v[52:55], v[196:199], v[12:15]
	v_mfma_f32_16x16x32_bf16 v[8:11], v[68:71], v[196:199], v[8:11]
	s_barrier
	s_mov_b32 m0, s41
	s_nop 0
	global_load_lds_dwordx4 v180, s[28:29]
	s_mov_b32 m0, s42
	s_nop 0
	global_load_lds_dwordx4 v184, s[28:29]
	s_add_i32 m0, s40, 0x14000
	s_add_u32 s60, s2, 0x40000
	s_addc_u32 s61, s3, 0
	global_load_lds_dwordx4 v182, s[60:61]
	s_add_i32 m0, s40, 0x16000
	s_add_u32 s28, s28, 0x40000
	s_addc_u32 s29, s29, 0
	global_load_lds_dwordx4 v186, s[60:61]
	s_waitcnt vmcnt(6)
	s_barrier
	v_mfma_f32_16x16x32_bf16 v[36:39], v[200:203], v[132:135], 0
	v_mfma_f32_16x16x32_bf16 v[32:35], v[212:215], v[132:135], 0
	v_mfma_f32_16x16x32_bf16 v[20:23], v[200:203], v[160:163], 0
	v_mfma_f32_16x16x32_bf16 v[16:19], v[212:215], v[160:163], 0
	v_mfma_f32_16x16x32_bf16 v[4:7], v[200:203], v[192:195], 0
	v_mfma_f32_16x16x32_bf16 v[0:3], v[212:215], v[192:195], 0
	v_mfma_f32_16x16x32_bf16 v[48:51], v[200:203], v[116:119], 0
	v_mfma_f32_16x16x32_bf16 v[52:55], v[212:215], v[116:119], 0
	v_mfma_f32_16x16x32_bf16 v[36:39], v[208:211], v[144:147], v[36:39]
	v_mfma_f32_16x16x32_bf16 v[32:35], v[216:219], v[144:147], v[32:35]
	v_mfma_f32_16x16x32_bf16 v[20:23], v[208:211], v[164:167], v[20:23]
	v_mfma_f32_16x16x32_bf16 v[16:19], v[216:219], v[164:167], v[16:19]
	v_mfma_f32_16x16x32_bf16 v[4:7], v[208:211], v[196:199], v[4:7]
	v_mfma_f32_16x16x32_bf16 v[0:3], v[216:219], v[196:199], v[0:3]
	v_mfma_f32_16x16x32_bf16 v[48:51], v[208:211], v[128:131], v[48:51]
	v_mfma_f32_16x16x32_bf16 v[52:55], v[216:219], v[128:131], v[52:55]
	s_barrier
	ds_read_b128 v[56:59], v206 offset:32768
	ds_read_b128 v[60:63], v206 offset:33792
	ds_read_b128 v[64:67], v206 offset:34816
	ds_read_b128 v[68:71], v206 offset:35840
	ds_read_b128 v[116:119], v207 offset:32768
	ds_read_b128 v[128:131], v207 offset:33792
	ds_read_b128 v[160:163], v207 offset:34816
	ds_read_b128 v[164:167], v207 offset:35840
	ds_read_b128 v[192:195], v207 offset:36864
	ds_read_b128 v[196:199], v207 offset:37888
	ds_read_b128 v[200:203], v207 offset:38912
	ds_read_b128 v[208:211], v207 offset:39936
	s_barrier
	s_waitcnt lgkmcnt(0)
	v_mfma_f32_16x16x32_bf16 v[132:135], v[56:59], v[116:119], v[156:159]
	v_mfma_f32_16x16x32_bf16 v[156:159], v[60:63], v[128:131], v[132:135]
	v_mfma_f32_16x16x32_bf16 v[132:135], v[64:67], v[116:119], v[152:155]
	v_mfma_f32_16x16x32_bf16 v[152:155], v[68:71], v[128:131], v[132:135]
	v_mfma_f32_16x16x32_bf16 v[132:135], v[56:59], v[160:163], v[140:143]
	v_mfma_f32_16x16x32_bf16 v[140:143], v[60:63], v[164:167], v[132:135]
	v_mfma_f32_16x16x32_bf16 v[132:135], v[64:67], v[160:163], v[136:139]
	v_mfma_f32_16x16x32_bf16 v[124:127], v[56:59], v[192:195], v[124:127]
	v_mfma_f32_16x16x32_bf16 v[120:123], v[64:67], v[192:195], v[120:123]
	v_mfma_f32_16x16x32_bf16 v[108:111], v[56:59], v[200:203], v[108:111]
	v_mfma_f32_16x16x32_bf16 v[104:107], v[64:67], v[200:203], v[104:107]
	v_mfma_f32_16x16x32_bf16 v[136:139], v[68:71], v[164:167], v[132:135]
	v_mfma_f32_16x16x32_bf16 v[124:127], v[60:63], v[196:199], v[124:127]
	v_mfma_f32_16x16x32_bf16 v[120:123], v[68:71], v[196:199], v[120:123]
	v_mfma_f32_16x16x32_bf16 v[108:111], v[60:63], v[208:211], v[108:111]
	v_mfma_f32_16x16x32_bf16 v[104:107], v[68:71], v[208:211], v[104:107]
	s_barrier
	s_mov_b32 m0, s43
	ds_read_b128 v[212:215], v206 offset:49152
	ds_read_b128 v[216:219], v206 offset:50176
	ds_read_b128 v[220:223], v206 offset:51200
	ds_read_b128 v[236:239], v206 offset:52224
	global_load_lds_dwordx4 v180, s[28:29]
	s_mov_b32 m0, s44
	s_nop 0
	global_load_lds_dwordx4 v184, s[28:29]
	s_barrier
	s_waitcnt lgkmcnt(0)
	v_mfma_f32_16x16x32_bf16 v[72:75], v[220:223], v[116:119], v[72:75]
	v_mfma_f32_16x16x32_bf16 v[132:135], v[212:215], v[116:119], v[148:151]
	v_mfma_f32_16x16x32_bf16 v[144:147], v[236:239], v[128:131], v[72:75]
	v_mfma_f32_16x16x32_bf16 v[72:75], v[212:215], v[160:163], v[76:79]
	v_mfma_f32_16x16x32_bf16 v[148:151], v[216:219], v[128:131], v[132:135]
	v_mfma_f32_16x16x32_bf16 v[132:135], v[216:219], v[164:167], v[72:75]
	v_mfma_f32_16x16x32_bf16 v[72:75], v[220:223], v[160:163], v[80:83]
	v_mfma_f32_16x16x32_bf16 v[128:131], v[236:239], v[164:167], v[72:75]
	v_mfma_f32_16x16x32_bf16 v[72:75], v[212:215], v[192:195], v[84:87]
	v_mfma_f32_16x16x32_bf16 v[116:119], v[216:219], v[196:199], v[72:75]
	v_mfma_f32_16x16x32_bf16 v[72:75], v[220:223], v[192:195], v[112:115]
	v_mfma_f32_16x16x32_bf16 v[112:115], v[236:239], v[196:199], v[72:75]
	v_mfma_f32_16x16x32_bf16 v[72:75], v[212:215], v[200:203], v[100:103]
	v_mfma_f32_16x16x32_bf16 v[100:103], v[216:219], v[208:211], v[72:75]
	v_mfma_f32_16x16x32_bf16 v[72:75], v[220:223], v[200:203], v[96:99]
	v_mfma_f32_16x16x32_bf16 v[96:99], v[236:239], v[208:211], v[72:75]
	s_barrier
	s_nop 2
	ds_read_b128 v[72:75], v207 offset:49152
	ds_read_b128 v[76:79], v207 offset:50176
	ds_read_b128 v[80:83], v207 offset:51200
	ds_read_b128 v[84:87], v207 offset:52224
	ds_read_b128 v[160:163], v207 offset:53248
	ds_read_b128 v[164:167], v207 offset:54272
	ds_read_b128 v[192:195], v207 offset:55296
	ds_read_b128 v[196:199], v207 offset:56320
	s_add_i32 m0, s40, 0x18000
	s_nop 0
	global_load_lds_dwordx4 v182, s[98:99]
	s_add_i32 m0, s40, 0x1a000
	s_nop 0
	global_load_lds_dwordx4 v186, s[98:99]
	s_barrier
	s_waitcnt lgkmcnt(0)
	v_mfma_f32_16x16x32_bf16 v[92:95], v[56:59], v[72:75], v[92:95]
	v_mfma_f32_16x16x32_bf16 v[88:91], v[64:67], v[72:75], v[88:91]
	v_mfma_f32_16x16x32_bf16 v[44:47], v[56:59], v[80:83], v[44:47]
	v_mfma_f32_16x16x32_bf16 v[40:43], v[64:67], v[80:83], v[40:43]
	v_mfma_f32_16x16x32_bf16 v[28:31], v[56:59], v[160:163], v[28:31]
	v_mfma_f32_16x16x32_bf16 v[24:27], v[64:67], v[160:163], v[24:27]
	v_mfma_f32_16x16x32_bf16 v[12:15], v[56:59], v[192:195], v[12:15]
	v_mfma_f32_16x16x32_bf16 v[8:11], v[64:67], v[192:195], v[8:11]
	v_mfma_f32_16x16x32_bf16 v[92:95], v[60:63], v[76:79], v[92:95]
	v_mfma_f32_16x16x32_bf16 v[88:91], v[68:71], v[76:79], v[88:91]
	v_mfma_f32_16x16x32_bf16 v[44:47], v[60:63], v[84:87], v[44:47]
	v_mfma_f32_16x16x32_bf16 v[40:43], v[68:71], v[84:87], v[40:43]
	v_mfma_f32_16x16x32_bf16 v[28:31], v[60:63], v[164:167], v[28:31]
	v_mfma_f32_16x16x32_bf16 v[24:27], v[68:71], v[164:167], v[24:27]
	v_mfma_f32_16x16x32_bf16 v[12:15], v[60:63], v[196:199], v[12:15]
	v_mfma_f32_16x16x32_bf16 v[8:11], v[68:71], v[196:199], v[8:11]
	s_barrier
	s_mov_b32 m0, s53
	s_nop 0
	global_load_lds_dwordx4 v180, s[100:101]
	s_mov_b32 m0, s54
	s_nop 0
	global_load_lds_dwordx4 v184, s[100:101]
	s_add_i32 m0, s40, 0x1c000
	s_add_u32 s2, s2, 0x40080
	s_addc_u32 s3, s3, 0
	global_load_lds_dwordx4 v182, s[2:3]
	s_add_i32 m0, s40, 0x1e000
	s_add_i32 s58, s58, 2
	global_load_lds_dwordx4 v186, s[2:3]
	s_waitcnt vmcnt(6)
	s_barrier
	v_mfma_f32_16x16x32_bf16 v[48:51], v[212:215], v[72:75], v[48:51]
	v_mfma_f32_16x16x32_bf16 v[64:67], v[216:219], v[76:79], v[48:51]
	v_mfma_f32_16x16x32_bf16 v[48:51], v[220:223], v[72:75], v[52:55]
	v_mfma_f32_16x16x32_bf16 v[36:39], v[212:215], v[80:83], v[36:39]
	v_mfma_f32_16x16x32_bf16 v[32:35], v[220:223], v[80:83], v[32:35]
	v_mfma_f32_16x16x32_bf16 v[20:23], v[212:215], v[160:163], v[20:23]
	v_mfma_f32_16x16x32_bf16 v[16:19], v[220:223], v[160:163], v[16:19]
	v_mfma_f32_16x16x32_bf16 v[4:7], v[212:215], v[192:195], v[4:7]
	v_mfma_f32_16x16x32_bf16 v[0:3], v[220:223], v[192:195], v[0:3]
	v_mfma_f32_16x16x32_bf16 v[56:59], v[236:239], v[76:79], v[48:51]
	v_mfma_f32_16x16x32_bf16 v[36:39], v[216:219], v[84:87], v[36:39]
	v_mfma_f32_16x16x32_bf16 v[32:35], v[236:239], v[84:87], v[32:35]
	v_mfma_f32_16x16x32_bf16 v[20:23], v[216:219], v[164:167], v[20:23]
	v_mfma_f32_16x16x32_bf16 v[16:19], v[236:239], v[164:167], v[16:19]
	v_mfma_f32_16x16x32_bf16 v[4:7], v[216:219], v[196:199], v[4:7]
	v_mfma_f32_16x16x32_bf16 v[0:3], v[236:239], v[196:199], v[0:3]
	s_add_u32 s8, s8, 0x100
	s_addc_u32 s9, s9, 0
	s_add_u32 s56, s56, 0x100
	s_addc_u32 s57, s57, 0
	s_cmp_gt_u32 s58, 13
	s_barrier
.LBB0_678:
	s_add_u32 s2, s8, 0xfffc0080
	s_addc_u32 s3, s9, -1
	ds_read_b128 v[48:51], v206
	ds_read_b128 v[52:55], v206 offset:1024
	ds_read_b128 v[60:63], v206 offset:2048
	ds_read_b128 v[68:71], v206 offset:3072
	s_cmp_eq_u32 s58, 12
	s_cselect_b32 s29, s1, s3
	s_cselect_b32 s28, s7, s2
	s_cselect_b32 s3, s21, s57
	s_cselect_b32 s2, s23, s56
	ds_read_b128 v[72:75], v207
	ds_read_b128 v[76:79], v207 offset:1024
	ds_read_b128 v[80:83], v207 offset:2048
	ds_read_b128 v[84:87], v207 offset:3072
	ds_read_b128 v[160:163], v207 offset:4096
	ds_read_b128 v[164:167], v207 offset:5120
	ds_read_b128 v[192:195], v207 offset:6144
	ds_read_b128 v[196:199], v207 offset:7168
	s_barrier
	s_waitcnt lgkmcnt(0)
	v_mfma_f32_16x16x32_bf16 v[156:159], v[48:51], v[72:75], v[156:159]
	v_mfma_f32_16x16x32_bf16 v[152:155], v[60:63], v[72:75], v[152:155]
	v_mfma_f32_16x16x32_bf16 v[140:143], v[48:51], v[80:83], v[140:143]
	v_mfma_f32_16x16x32_bf16 v[136:139], v[60:63], v[80:83], v[136:139]
	v_mfma_f32_16x16x32_bf16 v[124:127], v[48:51], v[160:163], v[124:127]
	v_mfma_f32_16x16x32_bf16 v[120:123], v[60:63], v[160:163], v[120:123]
	v_mfma_f32_16x16x32_bf16 v[108:111], v[48:51], v[192:195], v[108:111]
	v_mfma_f32_16x16x32_bf16 v[104:107], v[60:63], v[192:195], v[104:107]
	v_mfma_f32_16x16x32_bf16 v[156:159], v[52:55], v[76:79], v[156:159]
	v_mfma_f32_16x16x32_bf16 v[152:155], v[68:71], v[76:79], v[152:155]
	v_mfma_f32_16x16x32_bf16 v[140:143], v[52:55], v[84:87], v[140:143]
	v_mfma_f32_16x16x32_bf16 v[136:139], v[68:71], v[84:87], v[136:139]
	v_mfma_f32_16x16x32_bf16 v[124:127], v[52:55], v[164:167], v[124:127]
	v_mfma_f32_16x16x32_bf16 v[120:123], v[68:71], v[164:167], v[120:123]
	v_mfma_f32_16x16x32_bf16 v[108:111], v[52:55], v[196:199], v[108:111]
	v_mfma_f32_16x16x32_bf16 v[104:107], v[68:71], v[196:199], v[104:107]
	s_barrier
	s_add_i32 m0, s41, 0xc000
	ds_read_b128 v[200:203], v206 offset:16384
	ds_read_b128 v[208:211], v206 offset:17408
	ds_read_b128 v[212:215], v206 offset:18432
	ds_read_b128 v[216:219], v206 offset:19456
	global_load_lds_dwordx4 v188, s[8:9]
	s_add_i32 m0, s41, 0xe000
	s_add_u32 s98, s2, 0x80
	s_addc_u32 s99, s3, 0
	global_load_lds_dwordx4 v190, s[8:9]
	s_barrier
	s_waitcnt lgkmcnt(0)
	v_mfma_f32_16x16x32_bf16 v[148:151], v[200:203], v[72:75], v[148:151]
	v_mfma_f32_16x16x32_bf16 v[72:75], v[212:215], v[72:75], v[144:147]
	v_mfma_f32_16x16x32_bf16 v[148:151], v[208:211], v[76:79], v[148:151]
	v_mfma_f32_16x16x32_bf16 v[72:75], v[216:219], v[76:79], v[72:75]
	v_mfma_f32_16x16x32_bf16 v[76:79], v[200:203], v[80:83], v[132:135]
	v_mfma_f32_16x16x32_bf16 v[80:83], v[212:215], v[80:83], v[128:131]
	v_mfma_f32_16x16x32_bf16 v[112:115], v[212:215], v[160:163], v[112:115]
	v_mfma_f32_16x16x32_bf16 v[100:103], v[200:203], v[192:195], v[100:103]
	v_mfma_f32_16x16x32_bf16 v[96:99], v[212:215], v[192:195], v[96:99]
	v_mfma_f32_16x16x32_bf16 v[76:79], v[208:211], v[84:87], v[76:79]
	v_mfma_f32_16x16x32_bf16 v[80:83], v[216:219], v[84:87], v[80:83]
	v_mfma_f32_16x16x32_bf16 v[84:87], v[200:203], v[160:163], v[116:119]
	v_mfma_f32_16x16x32_bf16 v[112:115], v[216:219], v[164:167], v[112:115]
	v_mfma_f32_16x16x32_bf16 v[100:103], v[208:211], v[196:199], v[100:103]
	v_mfma_f32_16x16x32_bf16 v[96:99], v[216:219], v[196:199], v[96:99]
	v_mfma_f32_16x16x32_bf16 v[84:87], v[208:211], v[164:167], v[84:87]
	s_add_u32 s100, s28, 0x80
	s_addc_u32 s101, s29, 0
	s_barrier
	ds_read_b128 v[116:119], v207 offset:16384
	ds_read_b128 v[128:131], v207 offset:17408
	ds_read_b128 v[132:135], v207 offset:18432
	ds_read_b128 v[144:147], v207 offset:19456
	ds_read_b128 v[160:163], v207 offset:20480
	ds_read_b128 v[164:167], v207 offset:21504
	ds_read_b128 v[192:195], v207 offset:22528
	ds_read_b128 v[196:199], v207 offset:23552
	s_add_i32 m0, s40, 0x10000
	s_nop 0
	global_load_lds_dwordx4 v182, s[2:3]
	s_add_i32 m0, s40, 0x12000
	s_nop 0
	global_load_lds_dwordx4 v186, s[2:3]
	s_barrier
	s_waitcnt lgkmcnt(0)
	v_mfma_f32_16x16x32_bf16 v[92:95], v[48:51], v[116:119], v[92:95]
	v_mfma_f32_16x16x32_bf16 v[88:91], v[60:63], v[116:119], v[88:91]
	v_mfma_f32_16x16x32_bf16 v[44:47], v[48:51], v[132:135], v[44:47]
	v_mfma_f32_16x16x32_bf16 v[40:43], v[60:63], v[132:135], v[40:43]
	v_mfma_f32_16x16x32_bf16 v[28:31], v[48:51], v[160:163], v[28:31]
	v_mfma_f32_16x16x32_bf16 v[24:27], v[60:63], v[160:163], v[24:27]
	v_mfma_f32_16x16x32_bf16 v[12:15], v[48:51], v[192:195], v[12:15]
	v_mfma_f32_16x16x32_bf16 v[8:11], v[60:63], v[192:195], v[8:11]
	v_mfma_f32_16x16x32_bf16 v[92:95], v[52:55], v[128:131], v[92:95]
	v_mfma_f32_16x16x32_bf16 v[88:91], v[68:71], v[128:131], v[88:91]
	v_mfma_f32_16x16x32_bf16 v[44:47], v[52:55], v[144:147], v[44:47]
	v_mfma_f32_16x16x32_bf16 v[40:43], v[68:71], v[144:147], v[40:43]
	v_mfma_f32_16x16x32_bf16 v[28:31], v[52:55], v[164:167], v[28:31]
	v_mfma_f32_16x16x32_bf16 v[24:27], v[68:71], v[164:167], v[24:27]
	v_mfma_f32_16x16x32_bf16 v[12:15], v[52:55], v[196:199], v[12:15]
	v_mfma_f32_16x16x32_bf16 v[8:11], v[68:71], v[196:199], v[8:11]
	s_barrier
	s_mov_b32 m0, s41
	s_nop 0
	global_load_lds_dwordx4 v180, s[28:29]
	s_mov_b32 m0, s42
	s_nop 0
	global_load_lds_dwordx4 v184, s[28:29]
	s_add_i32 m0, s40, 0x14000
	s_add_u32 s60, s2, 0x40000
	s_addc_u32 s61, s3, 0
	global_load_lds_dwordx4 v182, s[60:61]
	s_add_i32 m0, s40, 0x16000
	s_add_u32 s28, s28, 0x40000
	s_addc_u32 s29, s29, 0
	global_load_lds_dwordx4 v186, s[60:61]
	s_waitcnt vmcnt(6)
	s_barrier
	v_mfma_f32_16x16x32_bf16 v[36:39], v[200:203], v[132:135], v[36:39]
	v_mfma_f32_16x16x32_bf16 v[32:35], v[212:215], v[132:135], v[32:35]
	v_mfma_f32_16x16x32_bf16 v[20:23], v[200:203], v[160:163], v[20:23]
	v_mfma_f32_16x16x32_bf16 v[16:19], v[212:215], v[160:163], v[16:19]
	v_mfma_f32_16x16x32_bf16 v[4:7], v[200:203], v[192:195], v[4:7]
	v_mfma_f32_16x16x32_bf16 v[0:3], v[212:215], v[192:195], v[0:3]
	v_mfma_f32_16x16x32_bf16 v[48:51], v[200:203], v[116:119], v[64:67]
	v_mfma_f32_16x16x32_bf16 v[52:55], v[212:215], v[116:119], v[56:59]
	v_mfma_f32_16x16x32_bf16 v[36:39], v[208:211], v[144:147], v[36:39]
	v_mfma_f32_16x16x32_bf16 v[32:35], v[216:219], v[144:147], v[32:35]
	v_mfma_f32_16x16x32_bf16 v[20:23], v[208:211], v[164:167], v[20:23]
	v_mfma_f32_16x16x32_bf16 v[16:19], v[216:219], v[164:167], v[16:19]
	v_mfma_f32_16x16x32_bf16 v[4:7], v[208:211], v[196:199], v[4:7]
	v_mfma_f32_16x16x32_bf16 v[0:3], v[216:219], v[196:199], v[0:3]
	v_mfma_f32_16x16x32_bf16 v[48:51], v[208:211], v[128:131], v[48:51]
	v_mfma_f32_16x16x32_bf16 v[52:55], v[216:219], v[128:131], v[52:55]
	s_barrier
	ds_read_b128 v[56:59], v206 offset:32768
	ds_read_b128 v[60:63], v206 offset:33792
	ds_read_b128 v[64:67], v206 offset:34816
	ds_read_b128 v[68:71], v206 offset:35840
	ds_read_b128 v[116:119], v207 offset:32768
	ds_read_b128 v[128:131], v207 offset:33792
	ds_read_b128 v[160:163], v207 offset:34816
	ds_read_b128 v[164:167], v207 offset:35840
	ds_read_b128 v[192:195], v207 offset:36864
	ds_read_b128 v[196:199], v207 offset:37888
	ds_read_b128 v[200:203], v207 offset:38912
	ds_read_b128 v[208:211], v207 offset:39936
	s_barrier
	s_waitcnt lgkmcnt(0)
	v_mfma_f32_16x16x32_bf16 v[132:135], v[56:59], v[116:119], v[156:159]
	v_mfma_f32_16x16x32_bf16 v[156:159], v[60:63], v[128:131], v[132:135]
	v_mfma_f32_16x16x32_bf16 v[132:135], v[64:67], v[116:119], v[152:155]
	v_mfma_f32_16x16x32_bf16 v[152:155], v[68:71], v[128:131], v[132:135]
	v_mfma_f32_16x16x32_bf16 v[132:135], v[56:59], v[160:163], v[140:143]
	v_mfma_f32_16x16x32_bf16 v[140:143], v[60:63], v[164:167], v[132:135]
	v_mfma_f32_16x16x32_bf16 v[132:135], v[64:67], v[160:163], v[136:139]
	v_mfma_f32_16x16x32_bf16 v[124:127], v[56:59], v[192:195], v[124:127]
	v_mfma_f32_16x16x32_bf16 v[120:123], v[64:67], v[192:195], v[120:123]
	v_mfma_f32_16x16x32_bf16 v[108:111], v[56:59], v[200:203], v[108:111]
	v_mfma_f32_16x16x32_bf16 v[104:107], v[64:67], v[200:203], v[104:107]
	v_mfma_f32_16x16x32_bf16 v[136:139], v[68:71], v[164:167], v[132:135]
	v_mfma_f32_16x16x32_bf16 v[124:127], v[60:63], v[196:199], v[124:127]
	v_mfma_f32_16x16x32_bf16 v[120:123], v[68:71], v[196:199], v[120:123]
	v_mfma_f32_16x16x32_bf16 v[108:111], v[60:63], v[208:211], v[108:111]
	v_mfma_f32_16x16x32_bf16 v[104:107], v[68:71], v[208:211], v[104:107]
	s_barrier
	s_mov_b32 m0, s43
	ds_read_b128 v[212:215], v206 offset:49152
	ds_read_b128 v[216:219], v206 offset:50176
	ds_read_b128 v[220:223], v206 offset:51200
	ds_read_b128 v[236:239], v206 offset:52224
	global_load_lds_dwordx4 v180, s[28:29]
	s_mov_b32 m0, s44
	s_nop 0
	global_load_lds_dwordx4 v184, s[28:29]
	s_barrier
	s_waitcnt lgkmcnt(0)
	v_mfma_f32_16x16x32_bf16 v[72:75], v[220:223], v[116:119], v[72:75]
	v_mfma_f32_16x16x32_bf16 v[132:135], v[212:215], v[116:119], v[148:151]
	v_mfma_f32_16x16x32_bf16 v[144:147], v[236:239], v[128:131], v[72:75]
	v_mfma_f32_16x16x32_bf16 v[72:75], v[212:215], v[160:163], v[76:79]
	v_mfma_f32_16x16x32_bf16 v[148:151], v[216:219], v[128:131], v[132:135]
	v_mfma_f32_16x16x32_bf16 v[132:135], v[216:219], v[164:167], v[72:75]
	v_mfma_f32_16x16x32_bf16 v[72:75], v[220:223], v[160:163], v[80:83]
	v_mfma_f32_16x16x32_bf16 v[128:131], v[236:239], v[164:167], v[72:75]
	v_mfma_f32_16x16x32_bf16 v[72:75], v[212:215], v[192:195], v[84:87]
	v_mfma_f32_16x16x32_bf16 v[116:119], v[216:219], v[196:199], v[72:75]
	v_mfma_f32_16x16x32_bf16 v[72:75], v[220:223], v[192:195], v[112:115]
	v_mfma_f32_16x16x32_bf16 v[112:115], v[236:239], v[196:199], v[72:75]
	v_mfma_f32_16x16x32_bf16 v[72:75], v[212:215], v[200:203], v[100:103]
	v_mfma_f32_16x16x32_bf16 v[100:103], v[216:219], v[208:211], v[72:75]
	v_mfma_f32_16x16x32_bf16 v[72:75], v[220:223], v[200:203], v[96:99]
	v_mfma_f32_16x16x32_bf16 v[96:99], v[236:239], v[208:211], v[72:75]
	s_barrier
	s_nop 2
	ds_read_b128 v[72:75], v207 offset:49152
	ds_read_b128 v[76:79], v207 offset:50176
	ds_read_b128 v[80:83], v207 offset:51200
	ds_read_b128 v[84:87], v207 offset:52224
	ds_read_b128 v[160:163], v207 offset:53248
	ds_read_b128 v[164:167], v207 offset:54272
	ds_read_b128 v[192:195], v207 offset:55296
	ds_read_b128 v[196:199], v207 offset:56320
	s_add_i32 m0, s40, 0x18000
	s_nop 0
	global_load_lds_dwordx4 v182, s[98:99]
	s_add_i32 m0, s40, 0x1a000
	s_nop 0
	global_load_lds_dwordx4 v186, s[98:99]
	s_barrier
	s_waitcnt lgkmcnt(0)
	v_mfma_f32_16x16x32_bf16 v[92:95], v[56:59], v[72:75], v[92:95]
	v_mfma_f32_16x16x32_bf16 v[88:91], v[64:67], v[72:75], v[88:91]
	v_mfma_f32_16x16x32_bf16 v[44:47], v[56:59], v[80:83], v[44:47]
	v_mfma_f32_16x16x32_bf16 v[40:43], v[64:67], v[80:83], v[40:43]
	v_mfma_f32_16x16x32_bf16 v[28:31], v[56:59], v[160:163], v[28:31]
	v_mfma_f32_16x16x32_bf16 v[24:27], v[64:67], v[160:163], v[24:27]
	v_mfma_f32_16x16x32_bf16 v[12:15], v[56:59], v[192:195], v[12:15]
	v_mfma_f32_16x16x32_bf16 v[8:11], v[64:67], v[192:195], v[8:11]
	v_mfma_f32_16x16x32_bf16 v[92:95], v[60:63], v[76:79], v[92:95]
	v_mfma_f32_16x16x32_bf16 v[88:91], v[68:71], v[76:79], v[88:91]
	v_mfma_f32_16x16x32_bf16 v[44:47], v[60:63], v[84:87], v[44:47]
	v_mfma_f32_16x16x32_bf16 v[40:43], v[68:71], v[84:87], v[40:43]
	v_mfma_f32_16x16x32_bf16 v[28:31], v[60:63], v[164:167], v[28:31]
	v_mfma_f32_16x16x32_bf16 v[24:27], v[68:71], v[164:167], v[24:27]
	v_mfma_f32_16x16x32_bf16 v[12:15], v[60:63], v[196:199], v[12:15]
	v_mfma_f32_16x16x32_bf16 v[8:11], v[68:71], v[196:199], v[8:11]
	s_barrier
	s_mov_b32 m0, s53
	s_nop 0
	global_load_lds_dwordx4 v180, s[100:101]
	s_mov_b32 m0, s54
	s_nop 0
	global_load_lds_dwordx4 v184, s[100:101]
	s_add_i32 m0, s40, 0x1c000
	s_add_u32 s2, s2, 0x40080
	s_addc_u32 s3, s3, 0
	global_load_lds_dwordx4 v182, s[2:3]
	s_add_i32 m0, s40, 0x1e000
	s_add_i32 s58, s58, 2
	global_load_lds_dwordx4 v186, s[2:3]
	s_waitcnt vmcnt(6)
	s_barrier
	v_mfma_f32_16x16x32_bf16 v[48:51], v[212:215], v[72:75], v[48:51]
	v_mfma_f32_16x16x32_bf16 v[64:67], v[216:219], v[76:79], v[48:51]
	v_mfma_f32_16x16x32_bf16 v[48:51], v[220:223], v[72:75], v[52:55]
	v_mfma_f32_16x16x32_bf16 v[36:39], v[212:215], v[80:83], v[36:39]
	v_mfma_f32_16x16x32_bf16 v[32:35], v[220:223], v[80:83], v[32:35]
	v_mfma_f32_16x16x32_bf16 v[20:23], v[212:215], v[160:163], v[20:23]
	v_mfma_f32_16x16x32_bf16 v[16:19], v[220:223], v[160:163], v[16:19]
	v_mfma_f32_16x16x32_bf16 v[4:7], v[212:215], v[192:195], v[4:7]
	v_mfma_f32_16x16x32_bf16 v[0:3], v[220:223], v[192:195], v[0:3]
	v_mfma_f32_16x16x32_bf16 v[56:59], v[236:239], v[76:79], v[48:51]
	v_mfma_f32_16x16x32_bf16 v[36:39], v[216:219], v[84:87], v[36:39]
	v_mfma_f32_16x16x32_bf16 v[32:35], v[236:239], v[84:87], v[32:35]
	v_mfma_f32_16x16x32_bf16 v[20:23], v[216:219], v[164:167], v[20:23]
	v_mfma_f32_16x16x32_bf16 v[16:19], v[236:239], v[164:167], v[16:19]
	v_mfma_f32_16x16x32_bf16 v[4:7], v[216:219], v[196:199], v[4:7]
	v_mfma_f32_16x16x32_bf16 v[0:3], v[236:239], v[196:199], v[0:3]
	s_add_u32 s8, s8, 0x100
	s_addc_u32 s9, s9, 0
	s_add_u32 s56, s56, 0x100
	s_addc_u32 s57, s57, 0
	s_cmp_gt_u32 s58, 13
	s_barrier
	s_cbranch_scc0 .LBB0_678
	s_lshl_b32 s1, s0, 8
	s_add_i32 s2, s1, s51
	s_lshl_b32 s1, s6, 8
	v_mov_b32_e32 v160, v205
	v_mov_b32_e32 v208, v204
	s_or_b32 s1, s1, s52
	s_nop 0
	v_lshl_add_u32 v192, v208, 3, s1
	s_add_i32 s1, s0, -16
	s_lshr_b32 s1, s1, 3
	s_add_i32 s1, s1, 1
	s_cmp_gt_i32 s0, 15
	s_cselect_b32 s3, s1, 0
	s_mul_i32 s96, s3, 0x1800
	s_lshl_b64 s[0:1], s[96:97], 2
	s_add_u32 s0, s45, s0
	v_ashrrev_i32_e32 v193, 31, v192
	s_addc_u32 s1, s46, s1
	v_lshlrev_b64 v[196:197], 2, v[192:193]
	s_lshl_b32 s96, s3, 10
	v_lshl_add_u64 v[48:49], s[0:1], 0, v[196:197]
	s_lshl_b64 s[0:1], s[96:97], 2
	s_add_u32 s0, s49, s0
	s_addc_u32 s1, s50, s1
	v_lshl_add_u64 v[52:53], s[0:1], 0, v[196:197]
	global_load_dwordx4 v[80:83], v[48:49], off offset:16
	global_load_dwordx4 v[84:87], v[48:49], off
	global_load_dwordx4 v[72:75], v[52:53], off offset:16
	global_load_dwordx4 v[76:79], v[52:53], off
	global_load_dwordx4 v[60:63], v[48:49], off offset:528
	global_load_dwordx4 v[68:71], v[48:49], off offset:512
	s_nop 0
	global_load_dwordx4 v[48:51], v[52:53], off offset:528
	s_nop 0
	global_load_dwordx4 v[52:55], v[52:53], off offset:512
	v_add_u32_e32 v194, s2, v160
	v_ashrrev_i32_e32 v195, 31, v194
	v_lshlrev_b64 v[160:161], 10, v[194:195]
	v_lshl_add_u64 v[198:199], v[160:161], 0, v[192:193]
	v_cndmask_b32_e64 v160, 0, 1, s[74:75]
	v_cmp_gt_i32_e64 s[0:1], s71, v194
	v_cmp_ne_u32_e64 s[6:7], 1, v160
	s_andn2_b64 vcc, exec, s[74:75]
	s_mov_b64 s[2:3], -1
	s_cbranch_vccnz .LBB0_681
	v_lshl_add_u64 v[160:161], v[198:199], 1, s[14:15]
	v_mov_b32_e32 v222, v160
	v_mov_b32_e32 v223, v161
	global_load_dwordx4 v[210:213], v[222:223], off
	global_load_dwordx4 v[214:217], v[222:223], off offset:256
	s_mov_b64 s[80:81], 0x8000
	v_lshl_add_u64 v[222:223], v[222:223], 0, s[80:81]
	global_load_dwordx4 v[218:221], v[222:223], off
	global_load_dwordx4 v[236:239], v[222:223], off offset:256
	s_mov_b64 s[2:3], 0
	s_waitcnt vmcnt(3)
	v_lshlrev_b32_e32 v164, 16, v210
	v_and_b32_e32 v165, 0xffff0000, v210
	v_lshlrev_b32_e32 v166, 16, v211
	v_and_b32_e32 v167, 0xffff0000, v211
	v_lshlrev_b32_e32 v160, 16, v212
	v_and_b32_e32 v161, 0xffff0000, v212
	v_lshlrev_b32_e32 v162, 16, v213
	v_and_b32_e32 v163, 0xffff0000, v213
	s_mov_b64 s[80:81], 0x8000
	v_lshl_add_u64 v[222:223], v[222:223], 0, s[80:81]
	global_load_dwordx4 v[210:213], v[222:223], off

.LBB0_879:
	s_ashr_i32 s39, s38, 31
	v_cmp_lt_i64_e32 vcc, s[12:13], v[178:179]
	s_lshl_b64 s[12:13], s[38:39], 19
	s_add_u32 s40, s49, s12
	s_addc_u32 s41, s50, s13
	s_lshl_b32 s84, s82, 18
	s_add_u32 s40, s40, s84
	s_addc_u32 s41, s41, 0
	s_and_b64 s[12:13], vcc, exec
	s_cselect_b32 s1, s41, s11
	s_cselect_b32 s9, s40, s10
	s_ashr_i32 s37, s36, 31
	s_lshl_b64 s[12:13], s[36:37], 19
	s_add_u32 s42, s51, s12
	s_addc_u32 s43, s52, s13
	s_and_b64 s[12:13], vcc, exec
	s_cselect_b32 s14, s43, s3
	s_cselect_b32 s15, s42, s2
	s_add_u32 s10, s10, 0x40080
	s_addc_u32 s11, s11, 0
	s_add_u32 s37, s2, 0x100
	s_addc_u32 s39, s3, 0
	s_mov_b32 s67, -2
	s_cmp_lg_u32 s83, 0
	s_cbranch_scc1 .Lup_half_peel
	s_add_u32 s2, s10, 0xfffc0080
	s_addc_u32 s3, s11, -1
	ds_read_b128 v[48:51], v237
	ds_read_b128 v[52:55], v237 offset:1024
	ds_read_b128 v[104:107], v237 offset:2048
	ds_read_b128 v[108:111], v237 offset:3072
	s_cmp_eq_u32 s67, 12
	s_cselect_b32 s13, s1, s3
	s_cselect_b32 s12, s9, s2
	s_cselect_b32 s3, s14, s39
	s_cselect_b32 s2, s15, s37
	ds_read_b128 v[112:115], v238
	ds_read_b128 v[116:119], v238 offset:1024
	ds_read_b128 v[120:123], v238 offset:2048
	ds_read_b128 v[156:159], v238 offset:3072
	ds_read_b128 v[160:163], v238 offset:4096
	ds_read_b128 v[164:167], v238 offset:5120
	ds_read_b128 v[190:193], v238 offset:6144
	ds_read_b128 v[194:197], v238 offset:7168
	s_barrier
	s_waitcnt lgkmcnt(0)
	v_mfma_f32_16x16x32_bf16 v[152:155], v[48:51], v[112:115], 0
	v_mfma_f32_16x16x32_bf16 v[68:71], v[104:107], v[112:115], 0
	v_mfma_f32_16x16x32_bf16 v[148:151], v[48:51], v[120:123], 0
	v_mfma_f32_16x16x32_bf16 v[64:67], v[104:107], v[120:123], 0
	v_mfma_f32_16x16x32_bf16 v[136:139], v[48:51], v[160:163], 0
	v_mfma_f32_16x16x32_bf16 v[44:47], v[104:107], v[160:163], 0
	v_mfma_f32_16x16x32_bf16 v[128:131], v[48:51], v[190:193], 0
	v_mfma_f32_16x16x32_bf16 v[40:43], v[104:107], v[190:193], 0
	v_mfma_f32_16x16x32_bf16 v[152:155], v[52:55], v[116:119], v[152:155]
	v_mfma_f32_16x16x32_bf16 v[68:71], v[108:111], v[116:119], v[68:71]
	v_mfma_f32_16x16x32_bf16 v[148:151], v[52:55], v[156:159], v[148:151]
	v_mfma_f32_16x16x32_bf16 v[64:67], v[108:111], v[156:159], v[64:67]
	v_mfma_f32_16x16x32_bf16 v[136:139], v[52:55], v[164:167], v[136:139]
	v_mfma_f32_16x16x32_bf16 v[44:47], v[108:111], v[164:167], v[44:47]
	v_mfma_f32_16x16x32_bf16 v[128:131], v[52:55], v[194:197], v[128:131]
	v_mfma_f32_16x16x32_bf16 v[40:43], v[108:111], v[194:197], v[40:43]
	s_barrier
	s_add_i32 m0, s54, 0xc000
	ds_read_b128 v[198:201], v237 offset:16384
	ds_read_b128 v[202:205], v237 offset:17408
	ds_read_b128 v[206:209], v237 offset:18432
	ds_read_b128 v[210:213], v237 offset:19456
	global_load_lds_dwordx4 v186, s[10:11]
	s_add_i32 m0, s54, 0xe000
	s_add_u32 s98, s2, 0x80
	s_addc_u32 s99, s3, 0
	global_load_lds_dwordx4 v188, s[10:11]
	s_barrier
	s_waitcnt lgkmcnt(0)
	v_mfma_f32_16x16x32_bf16 v[144:147], v[198:201], v[112:115], 0
	v_mfma_f32_16x16x32_bf16 v[60:63], v[206:209], v[112:115], 0
	v_mfma_f32_16x16x32_bf16 v[56:59], v[206:209], v[120:123], 0
	v_mfma_f32_16x16x32_bf16 v[36:39], v[206:209], v[160:163], 0
	v_mfma_f32_16x16x32_bf16 v[32:35], v[206:209], v[190:193], 0
	v_mfma_f32_16x16x32_bf16 v[144:147], v[202:205], v[116:119], v[144:147]
	v_mfma_f32_16x16x32_bf16 v[60:63], v[210:213], v[116:119], v[60:63]
	v_mfma_f32_16x16x32_bf16 v[112:115], v[198:201], v[120:123], 0
	v_mfma_f32_16x16x32_bf16 v[56:59], v[210:213], v[156:159], v[56:59]
	v_mfma_f32_16x16x32_bf16 v[116:119], v[198:201], v[160:163], 0
	v_mfma_f32_16x16x32_bf16 v[36:39], v[210:213], v[164:167], v[36:39]
	v_mfma_f32_16x16x32_bf16 v[120:123], v[198:201], v[190:193], 0
	v_mfma_f32_16x16x32_bf16 v[32:35], v[210:213], v[194:197], v[32:35]
	v_mfma_f32_16x16x32_bf16 v[112:115], v[202:205], v[156:159], v[112:115]
	v_mfma_f32_16x16x32_bf16 v[116:119], v[202:205], v[164:167], v[116:119]
	v_mfma_f32_16x16x32_bf16 v[120:123], v[202:205], v[194:197], v[120:123]
	s_add_u32 s100, s12, 0x80
	s_addc_u32 s101, s13, 0
	s_barrier
	ds_read_b128 v[124:127], v238 offset:16384
	ds_read_b128 v[132:135], v238 offset:17408
	ds_read_b128 v[140:143], v238 offset:18432
	ds_read_b128 v[156:159], v238 offset:19456
	ds_read_b128 v[160:163], v238 offset:20480
	ds_read_b128 v[164:167], v238 offset:21504
	ds_read_b128 v[190:193], v238 offset:22528
	ds_read_b128 v[194:197], v238 offset:23552
	s_add_i32 m0, s53, 0x10000
	s_nop 0
	global_load_lds_dwordx4 v168, s[2:3]
	s_add_i32 m0, s53, 0x12000
	s_nop 0
	global_load_lds_dwordx4 v184, s[2:3]
	s_barrier
	s_waitcnt lgkmcnt(0)
	v_mfma_f32_16x16x32_bf16 v[100:103], v[48:51], v[124:127], 0
	v_mfma_f32_16x16x32_bf16 v[28:31], v[104:107], v[124:127], 0
	v_mfma_f32_16x16x32_bf16 v[96:99], v[48:51], v[140:143], 0
	v_mfma_f32_16x16x32_bf16 v[24:27], v[104:107], v[140:143], 0
	v_mfma_f32_16x16x32_bf16 v[84:87], v[48:51], v[160:163], 0
	v_mfma_f32_16x16x32_bf16 v[12:15], v[104:107], v[160:163], 0
	v_mfma_f32_16x16x32_bf16 v[8:11], v[104:107], v[190:193], 0
	v_mfma_f32_16x16x32_bf16 v[100:103], v[52:55], v[132:135], v[100:103]
	v_mfma_f32_16x16x32_bf16 v[28:31], v[108:111], v[132:135], v[28:31]
	v_mfma_f32_16x16x32_bf16 v[96:99], v[52:55], v[156:159], v[96:99]
	v_mfma_f32_16x16x32_bf16 v[24:27], v[108:111], v[156:159], v[24:27]
	v_mfma_f32_16x16x32_bf16 v[84:87], v[52:55], v[164:167], v[84:87]
	v_mfma_f32_16x16x32_bf16 v[12:15], v[108:111], v[164:167], v[12:15]
	v_mfma_f32_16x16x32_bf16 v[48:51], v[48:51], v[190:193], 0
	v_mfma_f32_16x16x32_bf16 v[8:11], v[108:111], v[194:197], v[8:11]
	v_mfma_f32_16x16x32_bf16 v[48:51], v[52:55], v[194:197], v[48:51]
	s_barrier
	s_mov_b32 m0, s54
	s_nop 0
	global_load_lds_dwordx4 v180, s[12:13]
	s_mov_b32 m0, s55
	s_nop 0
	global_load_lds_dwordx4 v182, s[12:13]
	s_add_i32 m0, s53, 0x14000
	s_add_u32 s68, s2, 0x40000
	s_addc_u32 s69, s3, 0
	global_load_lds_dwordx4 v168, s[68:69]
	s_add_i32 m0, s53, 0x16000
	s_add_u32 s12, s12, 0x40000
	s_addc_u32 s13, s13, 0
	global_load_lds_dwordx4 v184, s[68:69]
	s_waitcnt vmcnt(6)
	s_barrier
	v_mfma_f32_16x16x32_bf16 v[76:79], v[198:201], v[140:143], 0
	v_mfma_f32_16x16x32_bf16 v[20:23], v[206:209], v[124:127], 0
	v_mfma_f32_16x16x32_bf16 v[88:91], v[202:205], v[156:159], v[76:79]
	v_mfma_f32_16x16x32_bf16 v[16:19], v[206:209], v[140:143], 0
	v_mfma_f32_16x16x32_bf16 v[76:79], v[198:201], v[160:163], 0
	v_mfma_f32_16x16x32_bf16 v[4:7], v[206:209], v[160:163], 0
	v_mfma_f32_16x16x32_bf16 v[72:75], v[198:201], v[190:193], 0
	v_mfma_f32_16x16x32_bf16 v[0:3], v[206:209], v[190:193], 0
	v_mfma_f32_16x16x32_bf16 v[52:55], v[198:201], v[124:127], 0
	v_mfma_f32_16x16x32_bf16 v[20:23], v[210:213], v[132:135], v[20:23]
	v_mfma_f32_16x16x32_bf16 v[16:19], v[210:213], v[156:159], v[16:19]
	v_mfma_f32_16x16x32_bf16 v[80:83], v[202:205], v[164:167], v[76:79]
	v_mfma_f32_16x16x32_bf16 v[4:7], v[210:213], v[164:167], v[4:7]
	v_mfma_f32_16x16x32_bf16 v[72:75], v[202:205], v[194:197], v[72:75]
	v_mfma_f32_16x16x32_bf16 v[0:3], v[210:213], v[194:197], v[0:3]
	v_mfma_f32_16x16x32_bf16 v[52:55], v[202:205], v[132:135], v[52:55]
	s_barrier
	ds_read_b128 v[76:79], v237 offset:32768
	ds_read_b128 v[92:95], v237 offset:33792
	ds_read_b128 v[104:107], v237 offset:34816
	ds_read_b128 v[108:111], v237 offset:35840
	ds_read_b128 v[124:127], v238 offset:32768
	ds_read_b128 v[132:135], v238 offset:33792
	ds_read_b128 v[156:159], v238 offset:34816
	ds_read_b128 v[160:163], v238 offset:35840
	ds_read_b128 v[164:167], v238 offset:36864
	ds_read_b128 v[190:193], v238 offset:37888
	ds_read_b128 v[194:197], v238 offset:38912
	ds_read_b128 v[198:201], v238 offset:39936
	s_barrier
	s_waitcnt lgkmcnt(0)
	v_mfma_f32_16x16x32_bf16 v[140:143], v[76:79], v[124:127], v[152:155]
	v_mfma_f32_16x16x32_bf16 v[152:155], v[92:95], v[132:135], v[140:143]
	v_mfma_f32_16x16x32_bf16 v[68:71], v[104:107], v[124:127], v[68:71]
	v_mfma_f32_16x16x32_bf16 v[140:143], v[76:79], v[156:159], v[148:151]
	v_mfma_f32_16x16x32_bf16 v[64:67], v[104:107], v[156:159], v[64:67]
	v_mfma_f32_16x16x32_bf16 v[136:139], v[76:79], v[164:167], v[136:139]
	v_mfma_f32_16x16x32_bf16 v[44:47], v[104:107], v[164:167], v[44:47]
	v_mfma_f32_16x16x32_bf16 v[128:131], v[76:79], v[194:197], v[128:131]
	v_mfma_f32_16x16x32_bf16 v[40:43], v[104:107], v[194:197], v[40:43]
	v_mfma_f32_16x16x32_bf16 v[68:71], v[108:111], v[132:135], v[68:71]
	v_mfma_f32_16x16x32_bf16 v[148:151], v[92:95], v[160:163], v[140:143]
	v_mfma_f32_16x16x32_bf16 v[64:67], v[108:111], v[160:163], v[64:67]
	v_mfma_f32_16x16x32_bf16 v[136:139], v[92:95], v[190:193], v[136:139]
	v_mfma_f32_16x16x32_bf16 v[44:47], v[108:111], v[190:193], v[44:47]
	v_mfma_f32_16x16x32_bf16 v[128:131], v[92:95], v[198:201], v[128:131]
	v_mfma_f32_16x16x32_bf16 v[40:43], v[108:111], v[198:201], v[40:43]
	s_barrier
	s_mov_b32 m0, s56
	ds_read_b128 v[202:205], v237 offset:49152
	ds_read_b128 v[206:209], v237 offset:50176
	ds_read_b128 v[210:213], v237 offset:51200
	ds_read_b128 v[214:217], v237 offset:52224
	global_load_lds_dwordx4 v180, s[12:13]
	s_mov_b32 m0, s57
	s_nop 0
	global_load_lds_dwordx4 v182, s[12:13]
	s_barrier
	s_waitcnt lgkmcnt(0)
	v_mfma_f32_16x16x32_bf16 v[140:143], v[202:205], v[124:127], v[144:147]
	v_mfma_f32_16x16x32_bf16 v[112:115], v[202:205], v[156:159], v[112:115]
	v_mfma_f32_16x16x32_bf16 v[144:147], v[206:209], v[132:135], v[140:143]
	v_mfma_f32_16x16x32_bf16 v[60:63], v[210:213], v[124:127], v[60:63]
	v_mfma_f32_16x16x32_bf16 v[140:143], v[206:209], v[160:163], v[112:115]
	v_mfma_f32_16x16x32_bf16 v[112:115], v[202:205], v[164:167], v[116:119]
	v_mfma_f32_16x16x32_bf16 v[60:63], v[214:217], v[132:135], v[60:63]
	v_mfma_f32_16x16x32_bf16 v[56:59], v[210:213], v[156:159], v[56:59]
	v_mfma_f32_16x16x32_bf16 v[132:135], v[206:209], v[190:193], v[112:115]
	v_mfma_f32_16x16x32_bf16 v[36:39], v[210:213], v[164:167], v[36:39]
	v_mfma_f32_16x16x32_bf16 v[112:115], v[202:205], v[194:197], v[120:123]
	v_mfma_f32_16x16x32_bf16 v[32:35], v[210:213], v[194:197], v[32:35]
	v_mfma_f32_16x16x32_bf16 v[56:59], v[214:217], v[160:163], v[56:59]
	v_mfma_f32_16x16x32_bf16 v[36:39], v[214:217], v[190:193], v[36:39]
	v_mfma_f32_16x16x32_bf16 v[124:127], v[206:209], v[198:201], v[112:115]
	v_mfma_f32_16x16x32_bf16 v[32:35], v[214:217], v[198:201], v[32:35]
	s_barrier
	ds_read_b128 v[112:115], v238 offset:49152
	ds_read_b128 v[116:119], v238 offset:50176
	ds_read_b128 v[120:123], v238 offset:51200
	ds_read_b128 v[156:159], v238 offset:52224
	ds_read_b128 v[160:163], v238 offset:53248
	ds_read_b128 v[164:167], v238 offset:54272
	ds_read_b128 v[190:193], v238 offset:55296
	ds_read_b128 v[194:197], v238 offset:56320
	s_add_i32 m0, s53, 0x18000
	s_nop 0
	global_load_lds_dwordx4 v168, s[98:99]
	s_add_i32 m0, s53, 0x1a000
	s_nop 0
	global_load_lds_dwordx4 v184, s[98:99]
	s_barrier
	s_waitcnt lgkmcnt(0)
	v_mfma_f32_16x16x32_bf16 v[100:103], v[76:79], v[112:115], v[100:103]
	v_mfma_f32_16x16x32_bf16 v[28:31], v[104:107], v[112:115], v[28:31]
	v_mfma_f32_16x16x32_bf16 v[96:99], v[76:79], v[120:123], v[96:99]
	v_mfma_f32_16x16x32_bf16 v[24:27], v[104:107], v[120:123], v[24:27]
	v_mfma_f32_16x16x32_bf16 v[84:87], v[76:79], v[160:163], v[84:87]
	v_mfma_f32_16x16x32_bf16 v[12:15], v[104:107], v[160:163], v[12:15]
	v_mfma_f32_16x16x32_bf16 v[48:51], v[76:79], v[190:193], v[48:51]
	v_mfma_f32_16x16x32_bf16 v[8:11], v[104:107], v[190:193], v[8:11]
	v_mfma_f32_16x16x32_bf16 v[100:103], v[92:95], v[116:119], v[100:103]
	v_mfma_f32_16x16x32_bf16 v[28:31], v[108:111], v[116:119], v[28:31]
	v_mfma_f32_16x16x32_bf16 v[96:99], v[92:95], v[156:159], v[96:99]
	v_mfma_f32_16x16x32_bf16 v[24:27], v[108:111], v[156:159], v[24:27]
	v_mfma_f32_16x16x32_bf16 v[84:87], v[92:95], v[164:167], v[84:87]
	v_mfma_f32_16x16x32_bf16 v[12:15], v[108:111], v[164:167], v[12:15]
	v_mfma_f32_16x16x32_bf16 v[76:79], v[92:95], v[194:197], v[48:51]
	v_mfma_f32_16x16x32_bf16 v[8:11], v[108:111], v[194:197], v[8:11]
	s_barrier
	s_mov_b32 m0, s62
	s_nop 0
	global_load_lds_dwordx4 v180, s[100:101]
	s_mov_b32 m0, s63
	s_nop 0
	global_load_lds_dwordx4 v182, s[100:101]
	s_add_i32 m0, s53, 0x1c000
	s_add_u32 s2, s2, 0x40080
	s_addc_u32 s3, s3, 0
	global_load_lds_dwordx4 v168, s[2:3]
	s_add_i32 m0, s53, 0x1e000
	s_add_i32 s67, s67, 2
	global_load_lds_dwordx4 v184, s[2:3]
	s_waitcnt vmcnt(6)
	s_barrier
	v_mfma_f32_16x16x32_bf16 v[48:51], v[202:205], v[112:115], v[52:55]
	v_mfma_f32_16x16x32_bf16 v[92:95], v[206:209], v[116:119], v[48:51]
	v_mfma_f32_16x16x32_bf16 v[48:51], v[202:205], v[120:123], v[88:91]
	v_mfma_f32_16x16x32_bf16 v[88:91], v[206:209], v[156:159], v[48:51]
	v_mfma_f32_16x16x32_bf16 v[48:51], v[202:205], v[160:163], v[80:83]
	v_mfma_f32_16x16x32_bf16 v[20:23], v[210:213], v[112:115], v[20:23]
	v_mfma_f32_16x16x32_bf16 v[16:19], v[210:213], v[120:123], v[16:19]
	v_mfma_f32_16x16x32_bf16 v[80:83], v[206:209], v[164:167], v[48:51]
	v_mfma_f32_16x16x32_bf16 v[4:7], v[210:213], v[160:163], v[4:7]
	v_mfma_f32_16x16x32_bf16 v[48:51], v[202:205], v[190:193], v[72:75]
	v_mfma_f32_16x16x32_bf16 v[0:3], v[210:213], v[190:193], v[0:3]
	v_mfma_f32_16x16x32_bf16 v[20:23], v[214:217], v[116:119], v[20:23]
	v_mfma_f32_16x16x32_bf16 v[16:19], v[214:217], v[156:159], v[16:19]
	v_mfma_f32_16x16x32_bf16 v[4:7], v[214:217], v[164:167], v[4:7]
	v_mfma_f32_16x16x32_bf16 v[72:75], v[206:209], v[194:197], v[48:51]
	v_mfma_f32_16x16x32_bf16 v[0:3], v[214:217], v[194:197], v[0:3]
	s_add_u32 s10, s10, 0x100
	s_addc_u32 s11, s11, 0
	s_add_u32 s37, s37, 0x100
	s_addc_u32 s39, s39, 0
	s_cmp_gt_u32 s67, 13
	s_barrier
.LBB0_880:
	s_add_u32 s2, s10, 0xfffc0080
	s_addc_u32 s3, s11, -1
	ds_read_b128 v[48:51], v237
	ds_read_b128 v[52:55], v237 offset:1024
	ds_read_b128 v[104:107], v237 offset:2048
	ds_read_b128 v[108:111], v237 offset:3072
	s_cmp_eq_u32 s67, 12
	s_cselect_b32 s13, s1, s3
	s_cselect_b32 s12, s9, s2
	s_cselect_b32 s3, s14, s39
	s_cselect_b32 s2, s15, s37
	ds_read_b128 v[112:115], v238
	ds_read_b128 v[116:119], v238 offset:1024
	ds_read_b128 v[120:123], v238 offset:2048
	ds_read_b128 v[156:159], v238 offset:3072
	ds_read_b128 v[160:163], v238 offset:4096
	ds_read_b128 v[164:167], v238 offset:5120
	ds_read_b128 v[190:193], v238 offset:6144
	ds_read_b128 v[194:197], v238 offset:7168
	s_barrier
	s_waitcnt lgkmcnt(0)
	v_mfma_f32_16x16x32_bf16 v[152:155], v[48:51], v[112:115], v[152:155]
	v_mfma_f32_16x16x32_bf16 v[68:71], v[104:107], v[112:115], v[68:71]
	v_mfma_f32_16x16x32_bf16 v[148:151], v[48:51], v[120:123], v[148:151]
	v_mfma_f32_16x16x32_bf16 v[64:67], v[104:107], v[120:123], v[64:67]
	v_mfma_f32_16x16x32_bf16 v[136:139], v[48:51], v[160:163], v[136:139]
	v_mfma_f32_16x16x32_bf16 v[44:47], v[104:107], v[160:163], v[44:47]
	v_mfma_f32_16x16x32_bf16 v[128:131], v[48:51], v[190:193], v[128:131]
	v_mfma_f32_16x16x32_bf16 v[40:43], v[104:107], v[190:193], v[40:43]
	v_mfma_f32_16x16x32_bf16 v[152:155], v[52:55], v[116:119], v[152:155]
	v_mfma_f32_16x16x32_bf16 v[68:71], v[108:111], v[116:119], v[68:71]
	v_mfma_f32_16x16x32_bf16 v[148:151], v[52:55], v[156:159], v[148:151]
	v_mfma_f32_16x16x32_bf16 v[64:67], v[108:111], v[156:159], v[64:67]
	v_mfma_f32_16x16x32_bf16 v[136:139], v[52:55], v[164:167], v[136:139]
	v_mfma_f32_16x16x32_bf16 v[44:47], v[108:111], v[164:167], v[44:47]
	v_mfma_f32_16x16x32_bf16 v[128:131], v[52:55], v[194:197], v[128:131]
	v_mfma_f32_16x16x32_bf16 v[40:43], v[108:111], v[194:197], v[40:43]
	s_barrier
	s_add_i32 m0, s54, 0xc000
	ds_read_b128 v[198:201], v237 offset:16384
	ds_read_b128 v[202:205], v237 offset:17408
	ds_read_b128 v[206:209], v237 offset:18432
	ds_read_b128 v[210:213], v237 offset:19456
	global_load_lds_dwordx4 v186, s[10:11]
	s_add_i32 m0, s54, 0xe000
	s_add_u32 s98, s2, 0x80
	s_addc_u32 s99, s3, 0
	global_load_lds_dwordx4 v188, s[10:11]
	s_barrier
	s_waitcnt lgkmcnt(0)
	v_mfma_f32_16x16x32_bf16 v[144:147], v[198:201], v[112:115], v[144:147]
	v_mfma_f32_16x16x32_bf16 v[60:63], v[206:209], v[112:115], v[60:63]
	v_mfma_f32_16x16x32_bf16 v[56:59], v[206:209], v[120:123], v[56:59]
	v_mfma_f32_16x16x32_bf16 v[36:39], v[206:209], v[160:163], v[36:39]
	v_mfma_f32_16x16x32_bf16 v[32:35], v[206:209], v[190:193], v[32:35]
	v_mfma_f32_16x16x32_bf16 v[144:147], v[202:205], v[116:119], v[144:147]
	v_mfma_f32_16x16x32_bf16 v[60:63], v[210:213], v[116:119], v[60:63]
	v_mfma_f32_16x16x32_bf16 v[112:115], v[198:201], v[120:123], v[140:143]
	v_mfma_f32_16x16x32_bf16 v[56:59], v[210:213], v[156:159], v[56:59]
	v_mfma_f32_16x16x32_bf16 v[116:119], v[198:201], v[160:163], v[132:135]
	v_mfma_f32_16x16x32_bf16 v[36:39], v[210:213], v[164:167], v[36:39]
	v_mfma_f32_16x16x32_bf16 v[120:123], v[198:201], v[190:193], v[124:127]
	v_mfma_f32_16x16x32_bf16 v[32:35], v[210:213], v[194:197], v[32:35]
	v_mfma_f32_16x16x32_bf16 v[112:115], v[202:205], v[156:159], v[112:115]
	v_mfma_f32_16x16x32_bf16 v[116:119], v[202:205], v[164:167], v[116:119]
	v_mfma_f32_16x16x32_bf16 v[120:123], v[202:205], v[194:197], v[120:123]
	s_add_u32 s100, s12, 0x80
	s_addc_u32 s101, s13, 0
	s_barrier
	ds_read_b128 v[124:127], v238 offset:16384
	ds_read_b128 v[132:135], v238 offset:17408
	ds_read_b128 v[140:143], v238 offset:18432
	ds_read_b128 v[156:159], v238 offset:19456
	ds_read_b128 v[160:163], v238 offset:20480
	ds_read_b128 v[164:167], v238 offset:21504
	ds_read_b128 v[190:193], v238 offset:22528
	ds_read_b128 v[194:197], v238 offset:23552
	s_add_i32 m0, s53, 0x10000
	s_nop 0
	global_load_lds_dwordx4 v168, s[2:3]
	s_add_i32 m0, s53, 0x12000
	s_nop 0
	global_load_lds_dwordx4 v184, s[2:3]
	s_barrier
	s_waitcnt lgkmcnt(0)
	v_mfma_f32_16x16x32_bf16 v[100:103], v[48:51], v[124:127], v[100:103]
	v_mfma_f32_16x16x32_bf16 v[28:31], v[104:107], v[124:127], v[28:31]
	v_mfma_f32_16x16x32_bf16 v[96:99], v[48:51], v[140:143], v[96:99]
	v_mfma_f32_16x16x32_bf16 v[24:27], v[104:107], v[140:143], v[24:27]
	v_mfma_f32_16x16x32_bf16 v[84:87], v[48:51], v[160:163], v[84:87]
	v_mfma_f32_16x16x32_bf16 v[12:15], v[104:107], v[160:163], v[12:15]
	v_mfma_f32_16x16x32_bf16 v[8:11], v[104:107], v[190:193], v[8:11]
	v_mfma_f32_16x16x32_bf16 v[100:103], v[52:55], v[132:135], v[100:103]
	v_mfma_f32_16x16x32_bf16 v[28:31], v[108:111], v[132:135], v[28:31]
	v_mfma_f32_16x16x32_bf16 v[96:99], v[52:55], v[156:159], v[96:99]
	v_mfma_f32_16x16x32_bf16 v[24:27], v[108:111], v[156:159], v[24:27]
	v_mfma_f32_16x16x32_bf16 v[84:87], v[52:55], v[164:167], v[84:87]
	v_mfma_f32_16x16x32_bf16 v[12:15], v[108:111], v[164:167], v[12:15]
	v_mfma_f32_16x16x32_bf16 v[48:51], v[48:51], v[190:193], v[76:79]
	v_mfma_f32_16x16x32_bf16 v[8:11], v[108:111], v[194:197], v[8:11]
	v_mfma_f32_16x16x32_bf16 v[48:51], v[52:55], v[194:197], v[48:51]
	s_barrier
	s_mov_b32 m0, s54
	s_nop 0
	global_load_lds_dwordx4 v180, s[12:13]
	s_mov_b32 m0, s55
	s_nop 0
	global_load_lds_dwordx4 v182, s[12:13]
	s_add_i32 m0, s53, 0x14000
	s_add_u32 s68, s2, 0x40000
	s_addc_u32 s69, s3, 0
	global_load_lds_dwordx4 v168, s[68:69]
	s_add_i32 m0, s53, 0x16000
	s_add_u32 s12, s12, 0x40000
	s_addc_u32 s13, s13, 0
	global_load_lds_dwordx4 v184, s[68:69]
	s_waitcnt vmcnt(6)
	s_barrier
	v_mfma_f32_16x16x32_bf16 v[76:79], v[198:201], v[140:143], v[88:91]
	v_mfma_f32_16x16x32_bf16 v[20:23], v[206:209], v[124:127], v[20:23]
	v_mfma_f32_16x16x32_bf16 v[88:91], v[202:205], v[156:159], v[76:79]
	v_mfma_f32_16x16x32_bf16 v[16:19], v[206:209], v[140:143], v[16:19]
	v_mfma_f32_16x16x32_bf16 v[76:79], v[198:201], v[160:163], v[80:83]
	v_mfma_f32_16x16x32_bf16 v[4:7], v[206:209], v[160:163], v[4:7]
	v_mfma_f32_16x16x32_bf16 v[72:75], v[198:201], v[190:193], v[72:75]
	v_mfma_f32_16x16x32_bf16 v[0:3], v[206:209], v[190:193], v[0:3]
	v_mfma_f32_16x16x32_bf16 v[52:55], v[198:201], v[124:127], v[92:95]
	v_mfma_f32_16x16x32_bf16 v[20:23], v[210:213], v[132:135], v[20:23]
	v_mfma_f32_16x16x32_bf16 v[16:19], v[210:213], v[156:159], v[16:19]
	v_mfma_f32_16x16x32_bf16 v[80:83], v[202:205], v[164:167], v[76:79]
	v_mfma_f32_16x16x32_bf16 v[4:7], v[210:213], v[164:167], v[4:7]
	v_mfma_f32_16x16x32_bf16 v[72:75], v[202:205], v[194:197], v[72:75]
	v_mfma_f32_16x16x32_bf16 v[0:3], v[210:213], v[194:197], v[0:3]
	v_mfma_f32_16x16x32_bf16 v[52:55], v[202:205], v[132:135], v[52:55]
	s_barrier
	ds_read_b128 v[76:79], v237 offset:32768
	ds_read_b128 v[92:95], v237 offset:33792
	ds_read_b128 v[104:107], v237 offset:34816
	ds_read_b128 v[108:111], v237 offset:35840
	ds_read_b128 v[124:127], v238 offset:32768
	ds_read_b128 v[132:135], v238 offset:33792
	ds_read_b128 v[156:159], v238 offset:34816
	ds_read_b128 v[160:163], v238 offset:35840
	ds_read_b128 v[164:167], v238 offset:36864
	ds_read_b128 v[190:193], v238 offset:37888
	ds_read_b128 v[194:197], v238 offset:38912
	ds_read_b128 v[198:201], v238 offset:39936
	s_barrier
	s_waitcnt lgkmcnt(0)
	v_mfma_f32_16x16x32_bf16 v[140:143], v[76:79], v[124:127], v[152:155]
	v_mfma_f32_16x16x32_bf16 v[152:155], v[92:95], v[132:135], v[140:143]
	v_mfma_f32_16x16x32_bf16 v[68:71], v[104:107], v[124:127], v[68:71]
	v_mfma_f32_16x16x32_bf16 v[140:143], v[76:79], v[156:159], v[148:151]
	v_mfma_f32_16x16x32_bf16 v[64:67], v[104:107], v[156:159], v[64:67]
	v_mfma_f32_16x16x32_bf16 v[136:139], v[76:79], v[164:167], v[136:139]
	v_mfma_f32_16x16x32_bf16 v[44:47], v[104:107], v[164:167], v[44:47]
	v_mfma_f32_16x16x32_bf16 v[128:131], v[76:79], v[194:197], v[128:131]
	v_mfma_f32_16x16x32_bf16 v[40:43], v[104:107], v[194:197], v[40:43]
	v_mfma_f32_16x16x32_bf16 v[68:71], v[108:111], v[132:135], v[68:71]
	v_mfma_f32_16x16x32_bf16 v[148:151], v[92:95], v[160:163], v[140:143]
	v_mfma_f32_16x16x32_bf16 v[64:67], v[108:111], v[160:163], v[64:67]
	v_mfma_f32_16x16x32_bf16 v[136:139], v[92:95], v[190:193], v[136:139]
	v_mfma_f32_16x16x32_bf16 v[44:47], v[108:111], v[190:193], v[44:47]
	v_mfma_f32_16x16x32_bf16 v[128:131], v[92:95], v[198:201], v[128:131]
	v_mfma_f32_16x16x32_bf16 v[40:43], v[108:111], v[198:201], v[40:43]
	s_barrier
	s_mov_b32 m0, s56
	ds_read_b128 v[202:205], v237 offset:49152
	ds_read_b128 v[206:209], v237 offset:50176
	ds_read_b128 v[210:213], v237 offset:51200
	ds_read_b128 v[214:217], v237 offset:52224
	global_load_lds_dwordx4 v180, s[12:13]
	s_mov_b32 m0, s57
	s_nop 0
	global_load_lds_dwordx4 v182, s[12:13]
	s_barrier
	s_waitcnt lgkmcnt(0)
	v_mfma_f32_16x16x32_bf16 v[140:143], v[202:205], v[124:127], v[144:147]
	v_mfma_f32_16x16x32_bf16 v[112:115], v[202:205], v[156:159], v[112:115]
	v_mfma_f32_16x16x32_bf16 v[144:147], v[206:209], v[132:135], v[140:143]
	v_mfma_f32_16x16x32_bf16 v[60:63], v[210:213], v[124:127], v[60:63]
	v_mfma_f32_16x16x32_bf16 v[140:143], v[206:209], v[160:163], v[112:115]
	v_mfma_f32_16x16x32_bf16 v[112:115], v[202:205], v[164:167], v[116:119]
	v_mfma_f32_16x16x32_bf16 v[60:63], v[214:217], v[132:135], v[60:63]
	v_mfma_f32_16x16x32_bf16 v[56:59], v[210:213], v[156:159], v[56:59]
	v_mfma_f32_16x16x32_bf16 v[132:135], v[206:209], v[190:193], v[112:115]
	v_mfma_f32_16x16x32_bf16 v[36:39], v[210:213], v[164:167], v[36:39]
	v_mfma_f32_16x16x32_bf16 v[112:115], v[202:205], v[194:197], v[120:123]
	v_mfma_f32_16x16x32_bf16 v[32:35], v[210:213], v[194:197], v[32:35]
	v_mfma_f32_16x16x32_bf16 v[56:59], v[214:217], v[160:163], v[56:59]
	v_mfma_f32_16x16x32_bf16 v[36:39], v[214:217], v[190:193], v[36:39]
	v_mfma_f32_16x16x32_bf16 v[124:127], v[206:209], v[198:201], v[112:115]
	v_mfma_f32_16x16x32_bf16 v[32:35], v[214:217], v[198:201], v[32:35]
	s_barrier
	ds_read_b128 v[112:115], v238 offset:49152
	ds_read_b128 v[116:119], v238 offset:50176
	ds_read_b128 v[120:123], v238 offset:51200
	ds_read_b128 v[156:159], v238 offset:52224
	ds_read_b128 v[160:163], v238 offset:53248
	ds_read_b128 v[164:167], v238 offset:54272
	ds_read_b128 v[190:193], v238 offset:55296
	ds_read_b128 v[194:197], v238 offset:56320
	s_add_i32 m0, s53, 0x18000
	s_nop 0
	global_load_lds_dwordx4 v168, s[98:99]
	s_add_i32 m0, s53, 0x1a000
	s_nop 0
	global_load_lds_dwordx4 v184, s[98:99]
	s_barrier
	s_waitcnt lgkmcnt(0)
	v_mfma_f32_16x16x32_bf16 v[100:103], v[76:79], v[112:115], v[100:103]
	v_mfma_f32_16x16x32_bf16 v[28:31], v[104:107], v[112:115], v[28:31]
	v_mfma_f32_16x16x32_bf16 v[96:99], v[76:79], v[120:123], v[96:99]
	v_mfma_f32_16x16x32_bf16 v[24:27], v[104:107], v[120:123], v[24:27]
	v_mfma_f32_16x16x32_bf16 v[84:87], v[76:79], v[160:163], v[84:87]
	v_mfma_f32_16x16x32_bf16 v[12:15], v[104:107], v[160:163], v[12:15]
	v_mfma_f32_16x16x32_bf16 v[48:51], v[76:79], v[190:193], v[48:51]
	v_mfma_f32_16x16x32_bf16 v[8:11], v[104:107], v[190:193], v[8:11]
	v_mfma_f32_16x16x32_bf16 v[100:103], v[92:95], v[116:119], v[100:103]
	v_mfma_f32_16x16x32_bf16 v[28:31], v[108:111], v[116:119], v[28:31]
	v_mfma_f32_16x16x32_bf16 v[96:99], v[92:95], v[156:159], v[96:99]
	v_mfma_f32_16x16x32_bf16 v[24:27], v[108:111], v[156:159], v[24:27]
	v_mfma_f32_16x16x32_bf16 v[84:87], v[92:95], v[164:167], v[84:87]
	v_mfma_f32_16x16x32_bf16 v[12:15], v[108:111], v[164:167], v[12:15]
	v_mfma_f32_16x16x32_bf16 v[76:79], v[92:95], v[194:197], v[48:51]
	v_mfma_f32_16x16x32_bf16 v[8:11], v[108:111], v[194:197], v[8:11]
	s_barrier
	s_mov_b32 m0, s62
	s_nop 0
	global_load_lds_dwordx4 v180, s[100:101]
	s_mov_b32 m0, s63
	s_nop 0
	global_load_lds_dwordx4 v182, s[100:101]
	s_add_i32 m0, s53, 0x1c000
	s_add_u32 s2, s2, 0x40080
	s_addc_u32 s3, s3, 0
	global_load_lds_dwordx4 v168, s[2:3]
	s_add_i32 m0, s53, 0x1e000
	s_add_i32 s67, s67, 2
	global_load_lds_dwordx4 v184, s[2:3]
	s_waitcnt vmcnt(6)
	s_barrier
	v_mfma_f32_16x16x32_bf16 v[48:51], v[202:205], v[112:115], v[52:55]
	v_mfma_f32_16x16x32_bf16 v[92:95], v[206:209], v[116:119], v[48:51]
	v_mfma_f32_16x16x32_bf16 v[48:51], v[202:205], v[120:123], v[88:91]
	v_mfma_f32_16x16x32_bf16 v[88:91], v[206:209], v[156:159], v[48:51]
	v_mfma_f32_16x16x32_bf16 v[48:51], v[202:205], v[160:163], v[80:83]
	v_mfma_f32_16x16x32_bf16 v[20:23], v[210:213], v[112:115], v[20:23]
	v_mfma_f32_16x16x32_bf16 v[16:19], v[210:213], v[120:123], v[16:19]
	v_mfma_f32_16x16x32_bf16 v[80:83], v[206:209], v[164:167], v[48:51]
	v_mfma_f32_16x16x32_bf16 v[4:7], v[210:213], v[160:163], v[4:7]
	v_mfma_f32_16x16x32_bf16 v[48:51], v[202:205], v[190:193], v[72:75]
	v_mfma_f32_16x16x32_bf16 v[0:3], v[210:213], v[190:193], v[0:3]
	v_mfma_f32_16x16x32_bf16 v[20:23], v[214:217], v[116:119], v[20:23]
	v_mfma_f32_16x16x32_bf16 v[16:19], v[214:217], v[156:159], v[16:19]
	v_mfma_f32_16x16x32_bf16 v[4:7], v[214:217], v[164:167], v[4:7]
	v_mfma_f32_16x16x32_bf16 v[72:75], v[206:209], v[194:197], v[48:51]
	v_mfma_f32_16x16x32_bf16 v[0:3], v[214:217], v[194:197], v[0:3]
	s_add_u32 s10, s10, 0x100
	s_addc_u32 s11, s11, 0
	s_add_u32 s37, s37, 0x100
	s_addc_u32 s39, s39, 0
	s_cmp_gt_u32 s67, 13
	s_barrier
	s_cbranch_scc0 .LBB0_880

.LBB0_1048:
	s_add_u32 s56, s2, 0x100
	s_addc_u32 s57, s3, 0
	s_mov_b32 s58, -2
	s_add_u32 s2, s24, 0x100
	s_addc_u32 s3, s25, 0
	ds_read_b128 v[40:43], v194
	ds_read_b128 v[44:47], v194 offset:1024
	ds_read_b128 v[48:51], v194 offset:2048
	ds_read_b128 v[52:55], v194 offset:3072
	s_cmp_eq_u32 s58, 40
	s_cselect_b32 s27, s1, s3
	s_cselect_b32 s26, s0, s2
	s_cselect_b32 s9, s23, s57
	s_cselect_b32 s8, s22, s56
	ds_read_b128 v[56:59], v195
	ds_read_b128 v[60:63], v195 offset:1024
	ds_read_b128 v[72:75], v195 offset:2048
	ds_read_b128 v[84:87], v195 offset:3072
	ds_read_b128 v[182:185], v195 offset:4096
	ds_read_b128 v[186:189], v195 offset:5120
	ds_read_b128 v[196:199], v195 offset:6144
	ds_read_b128 v[200:203], v195 offset:7168
	s_barrier
	s_waitcnt lgkmcnt(0)
	v_mfma_f32_16x16x32_bf16 v[156:159], v[40:43], v[56:59], 0
	v_mfma_f32_16x16x32_bf16 v[152:155], v[48:51], v[56:59], 0
	v_mfma_f32_16x16x32_bf16 v[140:143], v[40:43], v[72:75], 0
	v_mfma_f32_16x16x32_bf16 v[136:139], v[48:51], v[72:75], 0
	v_mfma_f32_16x16x32_bf16 v[124:127], v[40:43], v[182:185], 0
	v_mfma_f32_16x16x32_bf16 v[120:123], v[48:51], v[182:185], 0
	v_mfma_f32_16x16x32_bf16 v[108:111], v[40:43], v[196:199], 0
	v_mfma_f32_16x16x32_bf16 v[104:107], v[48:51], v[196:199], 0
	v_mfma_f32_16x16x32_bf16 v[156:159], v[44:47], v[60:63], v[156:159]
	v_mfma_f32_16x16x32_bf16 v[152:155], v[52:55], v[60:63], v[152:155]
	v_mfma_f32_16x16x32_bf16 v[140:143], v[44:47], v[84:87], v[140:143]
	v_mfma_f32_16x16x32_bf16 v[136:139], v[52:55], v[84:87], v[136:139]
	v_mfma_f32_16x16x32_bf16 v[124:127], v[44:47], v[186:189], v[124:127]
	v_mfma_f32_16x16x32_bf16 v[120:123], v[52:55], v[186:189], v[120:123]
	v_mfma_f32_16x16x32_bf16 v[108:111], v[44:47], v[200:203], v[108:111]
	v_mfma_f32_16x16x32_bf16 v[104:107], v[52:55], v[200:203], v[104:107]
	s_barrier
	s_add_i32 m0, s37, 0xc000
	ds_read_b128 v[204:207], v194 offset:16384
	ds_read_b128 v[208:211], v194 offset:17408
	ds_read_b128 v[212:215], v194 offset:18432
	ds_read_b128 v[216:219], v194 offset:19456
	global_load_lds_dwordx4 v166, s[24:25]
	s_add_i32 m0, s37, 0xe000
	s_add_u32 s98, s8, 0x80
	s_addc_u32 s99, s9, 0
	global_load_lds_dwordx4 v180, s[24:25]
	s_barrier
	s_waitcnt lgkmcnt(0)
	v_mfma_f32_16x16x32_bf16 v[148:151], v[204:207], v[56:59], 0
	v_mfma_f32_16x16x32_bf16 v[56:59], v[212:215], v[56:59], 0
	v_mfma_f32_16x16x32_bf16 v[148:151], v[208:211], v[60:63], v[148:151]
	v_mfma_f32_16x16x32_bf16 v[56:59], v[216:219], v[60:63], v[56:59]
	v_mfma_f32_16x16x32_bf16 v[60:63], v[204:207], v[72:75], 0
	v_mfma_f32_16x16x32_bf16 v[72:75], v[212:215], v[72:75], 0
	v_mfma_f32_16x16x32_bf16 v[112:115], v[212:215], v[182:185], 0
	v_mfma_f32_16x16x32_bf16 v[100:103], v[204:207], v[196:199], 0
	v_mfma_f32_16x16x32_bf16 v[96:99], v[212:215], v[196:199], 0
	v_mfma_f32_16x16x32_bf16 v[60:63], v[208:211], v[84:87], v[60:63]
	v_mfma_f32_16x16x32_bf16 v[72:75], v[216:219], v[84:87], v[72:75]
	v_mfma_f32_16x16x32_bf16 v[84:87], v[204:207], v[182:185], 0
	v_mfma_f32_16x16x32_bf16 v[112:115], v[216:219], v[186:189], v[112:115]
	v_mfma_f32_16x16x32_bf16 v[100:103], v[208:211], v[200:203], v[100:103]
	v_mfma_f32_16x16x32_bf16 v[96:99], v[216:219], v[200:203], v[96:99]
	v_mfma_f32_16x16x32_bf16 v[84:87], v[208:211], v[186:189], v[84:87]
	s_add_u32 s100, s26, 0x80
	s_addc_u32 s101, s27, 0
	s_barrier
	ds_read_b128 v[116:119], v195 offset:16384
	ds_read_b128 v[128:131], v195 offset:17408
	ds_read_b128 v[132:135], v195 offset:18432
	ds_read_b128 v[144:147], v195 offset:19456
	ds_read_b128 v[182:185], v195 offset:20480
	ds_read_b128 v[186:189], v195 offset:21504
	ds_read_b128 v[196:199], v195 offset:22528
	ds_read_b128 v[200:203], v195 offset:23552
	s_add_i32 m0, s36, 0x10000
	s_nop 0
	global_load_lds_dwordx4 v168, s[8:9]
	s_add_i32 m0, s36, 0x12000
	s_nop 0
	global_load_lds_dwordx4 v164, s[8:9]
	s_barrier
	s_waitcnt lgkmcnt(0)
	v_mfma_f32_16x16x32_bf16 v[92:95], v[40:43], v[116:119], 0
	v_mfma_f32_16x16x32_bf16 v[88:91], v[48:51], v[116:119], 0
	v_mfma_f32_16x16x32_bf16 v[68:71], v[40:43], v[132:135], 0
	v_mfma_f32_16x16x32_bf16 v[64:67], v[48:51], v[132:135], 0
	v_mfma_f32_16x16x32_bf16 v[28:31], v[40:43], v[182:185], 0
	v_mfma_f32_16x16x32_bf16 v[24:27], v[48:51], v[182:185], 0
	v_mfma_f32_16x16x32_bf16 v[12:15], v[40:43], v[196:199], 0
	v_mfma_f32_16x16x32_bf16 v[8:11], v[48:51], v[196:199], 0
	v_mfma_f32_16x16x32_bf16 v[92:95], v[44:47], v[128:131], v[92:95]
	v_mfma_f32_16x16x32_bf16 v[88:91], v[52:55], v[128:131], v[88:91]
	v_mfma_f32_16x16x32_bf16 v[68:71], v[44:47], v[144:147], v[68:71]
	v_mfma_f32_16x16x32_bf16 v[64:67], v[52:55], v[144:147], v[64:67]
	v_mfma_f32_16x16x32_bf16 v[28:31], v[44:47], v[186:189], v[28:31]
	v_mfma_f32_16x16x32_bf16 v[24:27], v[52:55], v[186:189], v[24:27]
	v_mfma_f32_16x16x32_bf16 v[12:15], v[44:47], v[200:203], v[12:15]
	v_mfma_f32_16x16x32_bf16 v[8:11], v[52:55], v[200:203], v[8:11]
	s_barrier
	s_mov_b32 m0, s37
	s_nop 0
	global_load_lds_dwordx4 v160, s[26:27]
	s_mov_b32 m0, s38
	s_nop 0
	global_load_lds_dwordx4 v162, s[26:27]
	s_add_i32 m0, s36, 0x14000
	s_add_u32 s24, s8, 0xb0000
	s_addc_u32 s25, s9, 0
	global_load_lds_dwordx4 v168, s[24:25]
	s_add_i32 m0, s36, 0x16000
	s_nop 0
	global_load_lds_dwordx4 v164, s[24:25]
	s_waitcnt vmcnt(6)
	s_barrier
	v_mfma_f32_16x16x32_bf16 v[36:39], v[204:207], v[132:135], 0
	v_mfma_f32_16x16x32_bf16 v[32:35], v[212:215], v[132:135], 0
	v_mfma_f32_16x16x32_bf16 v[20:23], v[204:207], v[182:185], 0
	v_mfma_f32_16x16x32_bf16 v[16:19], v[212:215], v[182:185], 0
	v_mfma_f32_16x16x32_bf16 v[4:7], v[204:207], v[196:199], 0
	v_mfma_f32_16x16x32_bf16 v[0:3], v[212:215], v[196:199], 0
	v_mfma_f32_16x16x32_bf16 v[40:43], v[204:207], v[116:119], 0
	v_mfma_f32_16x16x32_bf16 v[44:47], v[212:215], v[116:119], 0
	v_mfma_f32_16x16x32_bf16 v[36:39], v[208:211], v[144:147], v[36:39]
	v_mfma_f32_16x16x32_bf16 v[32:35], v[216:219], v[144:147], v[32:35]
	v_mfma_f32_16x16x32_bf16 v[20:23], v[208:211], v[186:189], v[20:23]
	v_mfma_f32_16x16x32_bf16 v[16:19], v[216:219], v[186:189], v[16:19]
	v_mfma_f32_16x16x32_bf16 v[4:7], v[208:211], v[200:203], v[4:7]
	v_mfma_f32_16x16x32_bf16 v[0:3], v[216:219], v[200:203], v[0:3]
	v_mfma_f32_16x16x32_bf16 v[40:43], v[208:211], v[128:131], v[40:43]
	v_mfma_f32_16x16x32_bf16 v[44:47], v[216:219], v[128:131], v[44:47]
	s_barrier
	ds_read_b128 v[48:51], v194 offset:32768
	ds_read_b128 v[52:55], v194 offset:33792
	ds_read_b128 v[76:79], v194 offset:34816
	ds_read_b128 v[80:83], v194 offset:35840
	s_add_u32 s24, s26, 0xb0000
	s_addc_u32 s25, s27, 0
	ds_read_b128 v[116:119], v195 offset:32768
	ds_read_b128 v[128:131], v195 offset:33792
	ds_read_b128 v[182:185], v195 offset:34816
	ds_read_b128 v[186:189], v195 offset:35840
	ds_read_b128 v[196:199], v195 offset:36864
	ds_read_b128 v[200:203], v195 offset:37888
	ds_read_b128 v[204:207], v195 offset:38912
	ds_read_b128 v[208:211], v195 offset:39936
	s_barrier
	s_waitcnt lgkmcnt(0)
	v_mfma_f32_16x16x32_bf16 v[132:135], v[48:51], v[116:119], v[156:159]
	v_mfma_f32_16x16x32_bf16 v[156:159], v[52:55], v[128:131], v[132:135]
	v_mfma_f32_16x16x32_bf16 v[132:135], v[76:79], v[116:119], v[152:155]
	v_mfma_f32_16x16x32_bf16 v[152:155], v[80:83], v[128:131], v[132:135]
	v_mfma_f32_16x16x32_bf16 v[132:135], v[48:51], v[182:185], v[140:143]
	v_mfma_f32_16x16x32_bf16 v[140:143], v[52:55], v[186:189], v[132:135]
	v_mfma_f32_16x16x32_bf16 v[132:135], v[76:79], v[182:185], v[136:139]
	v_mfma_f32_16x16x32_bf16 v[124:127], v[48:51], v[196:199], v[124:127]
	v_mfma_f32_16x16x32_bf16 v[120:123], v[76:79], v[196:199], v[120:123]
	v_mfma_f32_16x16x32_bf16 v[108:111], v[48:51], v[204:207], v[108:111]
	v_mfma_f32_16x16x32_bf16 v[104:107], v[76:79], v[204:207], v[104:107]
	v_mfma_f32_16x16x32_bf16 v[136:139], v[80:83], v[186:189], v[132:135]
	v_mfma_f32_16x16x32_bf16 v[124:127], v[52:55], v[200:203], v[124:127]
	v_mfma_f32_16x16x32_bf16 v[120:123], v[80:83], v[200:203], v[120:123]
	v_mfma_f32_16x16x32_bf16 v[108:111], v[52:55], v[208:211], v[108:111]
	v_mfma_f32_16x16x32_bf16 v[104:107], v[80:83], v[208:211], v[104:107]
	s_barrier
	s_mov_b32 m0, s39
	ds_read_b128 v[212:215], v194 offset:49152
	ds_read_b128 v[216:219], v194 offset:50176
	ds_read_b128 v[220:223], v194 offset:51200
	ds_read_b128 v[236:239], v194 offset:52224
	global_load_lds_dwordx4 v160, s[24:25]
	s_mov_b32 m0, s40
	s_nop 0
	global_load_lds_dwordx4 v162, s[24:25]
	s_barrier
	s_waitcnt lgkmcnt(0)
	v_mfma_f32_16x16x32_bf16 v[56:59], v[220:223], v[116:119], v[56:59]
	v_mfma_f32_16x16x32_bf16 v[132:135], v[212:215], v[116:119], v[148:151]
	v_mfma_f32_16x16x32_bf16 v[144:147], v[236:239], v[128:131], v[56:59]
	v_mfma_f32_16x16x32_bf16 v[56:59], v[212:215], v[182:185], v[60:63]
	v_mfma_f32_16x16x32_bf16 v[148:151], v[216:219], v[128:131], v[132:135]
	v_mfma_f32_16x16x32_bf16 v[132:135], v[216:219], v[186:189], v[56:59]
	v_mfma_f32_16x16x32_bf16 v[56:59], v[220:223], v[182:185], v[72:75]
	v_mfma_f32_16x16x32_bf16 v[128:131], v[236:239], v[186:189], v[56:59]
	v_mfma_f32_16x16x32_bf16 v[56:59], v[212:215], v[196:199], v[84:87]
	v_mfma_f32_16x16x32_bf16 v[116:119], v[216:219], v[200:203], v[56:59]
	v_mfma_f32_16x16x32_bf16 v[56:59], v[220:223], v[196:199], v[112:115]
	v_mfma_f32_16x16x32_bf16 v[112:115], v[236:239], v[200:203], v[56:59]
	v_mfma_f32_16x16x32_bf16 v[56:59], v[212:215], v[204:207], v[100:103]
	v_mfma_f32_16x16x32_bf16 v[100:103], v[216:219], v[208:211], v[56:59]
	v_mfma_f32_16x16x32_bf16 v[56:59], v[220:223], v[204:207], v[96:99]
	v_mfma_f32_16x16x32_bf16 v[96:99], v[236:239], v[208:211], v[56:59]
	s_barrier
	s_nop 2
	ds_read_b128 v[56:59], v195 offset:49152
	ds_read_b128 v[60:63], v195 offset:50176
	ds_read_b128 v[72:75], v195 offset:51200
	ds_read_b128 v[84:87], v195 offset:52224
	ds_read_b128 v[182:185], v195 offset:53248
	ds_read_b128 v[186:189], v195 offset:54272
	ds_read_b128 v[196:199], v195 offset:55296
	ds_read_b128 v[200:203], v195 offset:56320
	s_add_i32 m0, s36, 0x18000
	s_nop 0
	global_load_lds_dwordx4 v168, s[98:99]
	s_add_i32 m0, s36, 0x1a000
	s_nop 0
	global_load_lds_dwordx4 v164, s[98:99]
	s_barrier
	s_waitcnt lgkmcnt(0)
	v_mfma_f32_16x16x32_bf16 v[92:95], v[48:51], v[56:59], v[92:95]
	v_mfma_f32_16x16x32_bf16 v[88:91], v[76:79], v[56:59], v[88:91]
	v_mfma_f32_16x16x32_bf16 v[68:71], v[48:51], v[72:75], v[68:71]
	v_mfma_f32_16x16x32_bf16 v[64:67], v[76:79], v[72:75], v[64:67]
	v_mfma_f32_16x16x32_bf16 v[28:31], v[48:51], v[182:185], v[28:31]
	v_mfma_f32_16x16x32_bf16 v[24:27], v[76:79], v[182:185], v[24:27]
	v_mfma_f32_16x16x32_bf16 v[12:15], v[48:51], v[196:199], v[12:15]
	v_mfma_f32_16x16x32_bf16 v[8:11], v[76:79], v[196:199], v[8:11]
	v_mfma_f32_16x16x32_bf16 v[92:95], v[52:55], v[60:63], v[92:95]
	v_mfma_f32_16x16x32_bf16 v[88:91], v[80:83], v[60:63], v[88:91]
	v_mfma_f32_16x16x32_bf16 v[68:71], v[52:55], v[84:87], v[68:71]
	v_mfma_f32_16x16x32_bf16 v[64:67], v[80:83], v[84:87], v[64:67]
	v_mfma_f32_16x16x32_bf16 v[28:31], v[52:55], v[186:189], v[28:31]
	v_mfma_f32_16x16x32_bf16 v[24:27], v[80:83], v[186:189], v[24:27]
	v_mfma_f32_16x16x32_bf16 v[12:15], v[52:55], v[200:203], v[12:15]
	v_mfma_f32_16x16x32_bf16 v[8:11], v[80:83], v[200:203], v[8:11]
	s_barrier
	s_mov_b32 m0, s47
	s_nop 0
	global_load_lds_dwordx4 v160, s[100:101]
	s_mov_b32 m0, s49
	s_nop 0
	global_load_lds_dwordx4 v162, s[100:101]
	s_add_i32 m0, s36, 0x1c000
	s_add_u32 s8, s8, 0xb0080
	s_addc_u32 s9, s9, 0
	global_load_lds_dwordx4 v168, s[8:9]
	s_add_i32 m0, s36, 0x1e000
	s_add_i32 s58, s58, 2
	global_load_lds_dwordx4 v164, s[8:9]
	s_waitcnt vmcnt(6)
	s_barrier
	v_mfma_f32_16x16x32_bf16 v[40:43], v[212:215], v[56:59], v[40:43]
	v_mfma_f32_16x16x32_bf16 v[80:83], v[216:219], v[60:63], v[40:43]
	v_mfma_f32_16x16x32_bf16 v[40:43], v[220:223], v[56:59], v[44:47]
	v_mfma_f32_16x16x32_bf16 v[36:39], v[212:215], v[72:75], v[36:39]
	v_mfma_f32_16x16x32_bf16 v[32:35], v[220:223], v[72:75], v[32:35]
	v_mfma_f32_16x16x32_bf16 v[20:23], v[212:215], v[182:185], v[20:23]
	v_mfma_f32_16x16x32_bf16 v[16:19], v[220:223], v[182:185], v[16:19]
	v_mfma_f32_16x16x32_bf16 v[4:7], v[212:215], v[196:199], v[4:7]
	v_mfma_f32_16x16x32_bf16 v[0:3], v[220:223], v[196:199], v[0:3]
	v_mfma_f32_16x16x32_bf16 v[76:79], v[236:239], v[60:63], v[40:43]
	v_mfma_f32_16x16x32_bf16 v[36:39], v[216:219], v[84:87], v[36:39]
	v_mfma_f32_16x16x32_bf16 v[32:35], v[236:239], v[84:87], v[32:35]
	v_mfma_f32_16x16x32_bf16 v[20:23], v[216:219], v[186:189], v[20:23]
	v_mfma_f32_16x16x32_bf16 v[16:19], v[236:239], v[186:189], v[16:19]
	v_mfma_f32_16x16x32_bf16 v[4:7], v[216:219], v[200:203], v[4:7]
	v_mfma_f32_16x16x32_bf16 v[0:3], v[236:239], v[200:203], v[0:3]
	s_add_u32 s56, s56, 0x100
	s_addc_u32 s57, s57, 0
	s_cmp_gt_u32 s58, 41
	s_mov_b64 s[24:25], s[2:3]
	s_barrier
.LBB0_1049:
	s_add_u32 s2, s24, 0x100
	s_addc_u32 s3, s25, 0
	ds_read_b128 v[40:43], v194
	ds_read_b128 v[44:47], v194 offset:1024
	ds_read_b128 v[48:51], v194 offset:2048
	ds_read_b128 v[52:55], v194 offset:3072
	s_cmp_eq_u32 s58, 40
	s_cselect_b32 s27, s1, s3
	s_cselect_b32 s26, s0, s2
	s_cselect_b32 s9, s23, s57
	s_cselect_b32 s8, s22, s56
	ds_read_b128 v[56:59], v195
	ds_read_b128 v[60:63], v195 offset:1024
	ds_read_b128 v[72:75], v195 offset:2048
	ds_read_b128 v[84:87], v195 offset:3072
	ds_read_b128 v[182:185], v195 offset:4096
	ds_read_b128 v[186:189], v195 offset:5120
	ds_read_b128 v[196:199], v195 offset:6144
	ds_read_b128 v[200:203], v195 offset:7168
	s_barrier
	s_waitcnt lgkmcnt(0)
	v_mfma_f32_16x16x32_bf16 v[156:159], v[40:43], v[56:59], v[156:159]
	v_mfma_f32_16x16x32_bf16 v[152:155], v[48:51], v[56:59], v[152:155]
	v_mfma_f32_16x16x32_bf16 v[140:143], v[40:43], v[72:75], v[140:143]
	v_mfma_f32_16x16x32_bf16 v[136:139], v[48:51], v[72:75], v[136:139]
	v_mfma_f32_16x16x32_bf16 v[124:127], v[40:43], v[182:185], v[124:127]
	v_mfma_f32_16x16x32_bf16 v[120:123], v[48:51], v[182:185], v[120:123]
	v_mfma_f32_16x16x32_bf16 v[108:111], v[40:43], v[196:199], v[108:111]
	v_mfma_f32_16x16x32_bf16 v[104:107], v[48:51], v[196:199], v[104:107]
	v_mfma_f32_16x16x32_bf16 v[156:159], v[44:47], v[60:63], v[156:159]
	v_mfma_f32_16x16x32_bf16 v[152:155], v[52:55], v[60:63], v[152:155]
	v_mfma_f32_16x16x32_bf16 v[140:143], v[44:47], v[84:87], v[140:143]
	v_mfma_f32_16x16x32_bf16 v[136:139], v[52:55], v[84:87], v[136:139]
	v_mfma_f32_16x16x32_bf16 v[124:127], v[44:47], v[186:189], v[124:127]
	v_mfma_f32_16x16x32_bf16 v[120:123], v[52:55], v[186:189], v[120:123]
	v_mfma_f32_16x16x32_bf16 v[108:111], v[44:47], v[200:203], v[108:111]
	v_mfma_f32_16x16x32_bf16 v[104:107], v[52:55], v[200:203], v[104:107]
	s_barrier
	s_add_i32 m0, s37, 0xc000
	ds_read_b128 v[204:207], v194 offset:16384
	ds_read_b128 v[208:211], v194 offset:17408
	ds_read_b128 v[212:215], v194 offset:18432
	ds_read_b128 v[216:219], v194 offset:19456
	global_load_lds_dwordx4 v166, s[24:25]
	s_add_i32 m0, s37, 0xe000
	s_add_u32 s98, s8, 0x80
	s_addc_u32 s99, s9, 0
	global_load_lds_dwordx4 v180, s[24:25]
	s_barrier
	s_waitcnt lgkmcnt(0)
	v_mfma_f32_16x16x32_bf16 v[148:151], v[204:207], v[56:59], v[148:151]
	v_mfma_f32_16x16x32_bf16 v[56:59], v[212:215], v[56:59], v[144:147]
	v_mfma_f32_16x16x32_bf16 v[148:151], v[208:211], v[60:63], v[148:151]
	v_mfma_f32_16x16x32_bf16 v[56:59], v[216:219], v[60:63], v[56:59]
	v_mfma_f32_16x16x32_bf16 v[60:63], v[204:207], v[72:75], v[132:135]
	v_mfma_f32_16x16x32_bf16 v[72:75], v[212:215], v[72:75], v[128:131]
	v_mfma_f32_16x16x32_bf16 v[112:115], v[212:215], v[182:185], v[112:115]
	v_mfma_f32_16x16x32_bf16 v[100:103], v[204:207], v[196:199], v[100:103]
	v_mfma_f32_16x16x32_bf16 v[96:99], v[212:215], v[196:199], v[96:99]
	v_mfma_f32_16x16x32_bf16 v[60:63], v[208:211], v[84:87], v[60:63]
	v_mfma_f32_16x16x32_bf16 v[72:75], v[216:219], v[84:87], v[72:75]
	v_mfma_f32_16x16x32_bf16 v[84:87], v[204:207], v[182:185], v[116:119]
	v_mfma_f32_16x16x32_bf16 v[112:115], v[216:219], v[186:189], v[112:115]
	v_mfma_f32_16x16x32_bf16 v[100:103], v[208:211], v[200:203], v[100:103]
	v_mfma_f32_16x16x32_bf16 v[96:99], v[216:219], v[200:203], v[96:99]
	v_mfma_f32_16x16x32_bf16 v[84:87], v[208:211], v[186:189], v[84:87]
	s_add_u32 s100, s26, 0x80
	s_addc_u32 s101, s27, 0
	s_barrier
	ds_read_b128 v[116:119], v195 offset:16384
	ds_read_b128 v[128:131], v195 offset:17408
	ds_read_b128 v[132:135], v195 offset:18432
	ds_read_b128 v[144:147], v195 offset:19456
	ds_read_b128 v[182:185], v195 offset:20480
	ds_read_b128 v[186:189], v195 offset:21504
	ds_read_b128 v[196:199], v195 offset:22528
	ds_read_b128 v[200:203], v195 offset:23552
	s_add_i32 m0, s36, 0x10000
	s_nop 0
	global_load_lds_dwordx4 v168, s[8:9]
	s_add_i32 m0, s36, 0x12000
	s_nop 0
	global_load_lds_dwordx4 v164, s[8:9]
	s_barrier
	s_waitcnt lgkmcnt(0)
	v_mfma_f32_16x16x32_bf16 v[92:95], v[40:43], v[116:119], v[92:95]
	v_mfma_f32_16x16x32_bf16 v[88:91], v[48:51], v[116:119], v[88:91]
	v_mfma_f32_16x16x32_bf16 v[68:71], v[40:43], v[132:135], v[68:71]
	v_mfma_f32_16x16x32_bf16 v[64:67], v[48:51], v[132:135], v[64:67]
	v_mfma_f32_16x16x32_bf16 v[28:31], v[40:43], v[182:185], v[28:31]
	v_mfma_f32_16x16x32_bf16 v[24:27], v[48:51], v[182:185], v[24:27]
	v_mfma_f32_16x16x32_bf16 v[12:15], v[40:43], v[196:199], v[12:15]
	v_mfma_f32_16x16x32_bf16 v[8:11], v[48:51], v[196:199], v[8:11]
	v_mfma_f32_16x16x32_bf16 v[92:95], v[44:47], v[128:131], v[92:95]
	v_mfma_f32_16x16x32_bf16 v[88:91], v[52:55], v[128:131], v[88:91]
	v_mfma_f32_16x16x32_bf16 v[68:71], v[44:47], v[144:147], v[68:71]
	v_mfma_f32_16x16x32_bf16 v[64:67], v[52:55], v[144:147], v[64:67]
	v_mfma_f32_16x16x32_bf16 v[28:31], v[44:47], v[186:189], v[28:31]
	v_mfma_f32_16x16x32_bf16 v[24:27], v[52:55], v[186:189], v[24:27]
	v_mfma_f32_16x16x32_bf16 v[12:15], v[44:47], v[200:203], v[12:15]
	v_mfma_f32_16x16x32_bf16 v[8:11], v[52:55], v[200:203], v[8:11]
	s_barrier
	s_mov_b32 m0, s37
	s_nop 0
	global_load_lds_dwordx4 v160, s[26:27]
	s_mov_b32 m0, s38
	s_nop 0
	global_load_lds_dwordx4 v162, s[26:27]
	s_add_i32 m0, s36, 0x14000
	s_add_u32 s24, s8, 0xb0000
	s_addc_u32 s25, s9, 0
	global_load_lds_dwordx4 v168, s[24:25]
	s_add_i32 m0, s36, 0x16000
	s_nop 0
	global_load_lds_dwordx4 v164, s[24:25]
	s_waitcnt vmcnt(6)
	s_barrier
	v_mfma_f32_16x16x32_bf16 v[36:39], v[204:207], v[132:135], v[36:39]
	v_mfma_f32_16x16x32_bf16 v[32:35], v[212:215], v[132:135], v[32:35]
	v_mfma_f32_16x16x32_bf16 v[20:23], v[204:207], v[182:185], v[20:23]
	v_mfma_f32_16x16x32_bf16 v[16:19], v[212:215], v[182:185], v[16:19]
	v_mfma_f32_16x16x32_bf16 v[4:7], v[204:207], v[196:199], v[4:7]
	v_mfma_f32_16x16x32_bf16 v[0:3], v[212:215], v[196:199], v[0:3]
	v_mfma_f32_16x16x32_bf16 v[40:43], v[204:207], v[116:119], v[80:83]
	v_mfma_f32_16x16x32_bf16 v[44:47], v[212:215], v[116:119], v[76:79]
	v_mfma_f32_16x16x32_bf16 v[36:39], v[208:211], v[144:147], v[36:39]
	v_mfma_f32_16x16x32_bf16 v[32:35], v[216:219], v[144:147], v[32:35]
	v_mfma_f32_16x16x32_bf16 v[20:23], v[208:211], v[186:189], v[20:23]
	v_mfma_f32_16x16x32_bf16 v[16:19], v[216:219], v[186:189], v[16:19]
	v_mfma_f32_16x16x32_bf16 v[4:7], v[208:211], v[200:203], v[4:7]
	v_mfma_f32_16x16x32_bf16 v[0:3], v[216:219], v[200:203], v[0:3]
	v_mfma_f32_16x16x32_bf16 v[40:43], v[208:211], v[128:131], v[40:43]
	v_mfma_f32_16x16x32_bf16 v[44:47], v[216:219], v[128:131], v[44:47]
	s_barrier
	ds_read_b128 v[48:51], v194 offset:32768
	ds_read_b128 v[52:55], v194 offset:33792
	ds_read_b128 v[76:79], v194 offset:34816
	ds_read_b128 v[80:83], v194 offset:35840
	s_add_u32 s24, s26, 0xb0000
	s_addc_u32 s25, s27, 0
	ds_read_b128 v[116:119], v195 offset:32768
	ds_read_b128 v[128:131], v195 offset:33792
	ds_read_b128 v[182:185], v195 offset:34816
	ds_read_b128 v[186:189], v195 offset:35840
	ds_read_b128 v[196:199], v195 offset:36864
	ds_read_b128 v[200:203], v195 offset:37888
	ds_read_b128 v[204:207], v195 offset:38912
	ds_read_b128 v[208:211], v195 offset:39936
	s_barrier
	s_waitcnt lgkmcnt(0)
	v_mfma_f32_16x16x32_bf16 v[132:135], v[48:51], v[116:119], v[156:159]
	v_mfma_f32_16x16x32_bf16 v[156:159], v[52:55], v[128:131], v[132:135]
	v_mfma_f32_16x16x32_bf16 v[132:135], v[76:79], v[116:119], v[152:155]
	v_mfma_f32_16x16x32_bf16 v[152:155], v[80:83], v[128:131], v[132:135]
	v_mfma_f32_16x16x32_bf16 v[132:135], v[48:51], v[182:185], v[140:143]
	v_mfma_f32_16x16x32_bf16 v[140:143], v[52:55], v[186:189], v[132:135]
	v_mfma_f32_16x16x32_bf16 v[132:135], v[76:79], v[182:185], v[136:139]
	v_mfma_f32_16x16x32_bf16 v[124:127], v[48:51], v[196:199], v[124:127]
	v_mfma_f32_16x16x32_bf16 v[120:123], v[76:79], v[196:199], v[120:123]
	v_mfma_f32_16x16x32_bf16 v[108:111], v[48:51], v[204:207], v[108:111]
	v_mfma_f32_16x16x32_bf16 v[104:107], v[76:79], v[204:207], v[104:107]
	v_mfma_f32_16x16x32_bf16 v[136:139], v[80:83], v[186:189], v[132:135]
	v_mfma_f32_16x16x32_bf16 v[124:127], v[52:55], v[200:203], v[124:127]
	v_mfma_f32_16x16x32_bf16 v[120:123], v[80:83], v[200:203], v[120:123]
	v_mfma_f32_16x16x32_bf16 v[108:111], v[52:55], v[208:211], v[108:111]
	v_mfma_f32_16x16x32_bf16 v[104:107], v[80:83], v[208:211], v[104:107]
	s_barrier
	s_mov_b32 m0, s39
	ds_read_b128 v[212:215], v194 offset:49152
	ds_read_b128 v[216:219], v194 offset:50176
	ds_read_b128 v[220:223], v194 offset:51200
	ds_read_b128 v[236:239], v194 offset:52224
	global_load_lds_dwordx4 v160, s[24:25]
	s_mov_b32 m0, s40
	s_nop 0
	global_load_lds_dwordx4 v162, s[24:25]
	s_barrier
	s_waitcnt lgkmcnt(0)
	v_mfma_f32_16x16x32_bf16 v[56:59], v[220:223], v[116:119], v[56:59]
	v_mfma_f32_16x16x32_bf16 v[132:135], v[212:215], v[116:119], v[148:151]
	v_mfma_f32_16x16x32_bf16 v[144:147], v[236:239], v[128:131], v[56:59]
	v_mfma_f32_16x16x32_bf16 v[56:59], v[212:215], v[182:185], v[60:63]
	v_mfma_f32_16x16x32_bf16 v[148:151], v[216:219], v[128:131], v[132:135]
	v_mfma_f32_16x16x32_bf16 v[132:135], v[216:219], v[186:189], v[56:59]
	v_mfma_f32_16x16x32_bf16 v[56:59], v[220:223], v[182:185], v[72:75]
	v_mfma_f32_16x16x32_bf16 v[128:131], v[236:239], v[186:189], v[56:59]
	v_mfma_f32_16x16x32_bf16 v[56:59], v[212:215], v[196:199], v[84:87]
	v_mfma_f32_16x16x32_bf16 v[116:119], v[216:219], v[200:203], v[56:59]
	v_mfma_f32_16x16x32_bf16 v[56:59], v[220:223], v[196:199], v[112:115]
	v_mfma_f32_16x16x32_bf16 v[112:115], v[236:239], v[200:203], v[56:59]
	v_mfma_f32_16x16x32_bf16 v[56:59], v[212:215], v[204:207], v[100:103]
	v_mfma_f32_16x16x32_bf16 v[100:103], v[216:219], v[208:211], v[56:59]
	v_mfma_f32_16x16x32_bf16 v[56:59], v[220:223], v[204:207], v[96:99]
	v_mfma_f32_16x16x32_bf16 v[96:99], v[236:239], v[208:211], v[56:59]
	s_barrier
	s_nop 2
	ds_read_b128 v[56:59], v195 offset:49152
	ds_read_b128 v[60:63], v195 offset:50176
	ds_read_b128 v[72:75], v195 offset:51200
	ds_read_b128 v[84:87], v195 offset:52224
	ds_read_b128 v[182:185], v195 offset:53248
	ds_read_b128 v[186:189], v195 offset:54272
	ds_read_b128 v[196:199], v195 offset:55296
	ds_read_b128 v[200:203], v195 offset:56320
	s_add_i32 m0, s36, 0x18000
	s_nop 0
	global_load_lds_dwordx4 v168, s[98:99]
	s_add_i32 m0, s36, 0x1a000
	s_nop 0
	global_load_lds_dwordx4 v164, s[98:99]
	s_barrier
	s_waitcnt lgkmcnt(0)
	v_mfma_f32_16x16x32_bf16 v[92:95], v[48:51], v[56:59], v[92:95]
	v_mfma_f32_16x16x32_bf16 v[88:91], v[76:79], v[56:59], v[88:91]
	v_mfma_f32_16x16x32_bf16 v[68:71], v[48:51], v[72:75], v[68:71]
	v_mfma_f32_16x16x32_bf16 v[64:67], v[76:79], v[72:75], v[64:67]
	v_mfma_f32_16x16x32_bf16 v[28:31], v[48:51], v[182:185], v[28:31]
	v_mfma_f32_16x16x32_bf16 v[24:27], v[76:79], v[182:185], v[24:27]
	v_mfma_f32_16x16x32_bf16 v[12:15], v[48:51], v[196:199], v[12:15]
	v_mfma_f32_16x16x32_bf16 v[8:11], v[76:79], v[196:199], v[8:11]
	v_mfma_f32_16x16x32_bf16 v[92:95], v[52:55], v[60:63], v[92:95]
	v_mfma_f32_16x16x32_bf16 v[88:91], v[80:83], v[60:63], v[88:91]
	v_mfma_f32_16x16x32_bf16 v[68:71], v[52:55], v[84:87], v[68:71]
	v_mfma_f32_16x16x32_bf16 v[64:67], v[80:83], v[84:87], v[64:67]
	v_mfma_f32_16x16x32_bf16 v[28:31], v[52:55], v[186:189], v[28:31]
	v_mfma_f32_16x16x32_bf16 v[24:27], v[80:83], v[186:189], v[24:27]
	v_mfma_f32_16x16x32_bf16 v[12:15], v[52:55], v[200:203], v[12:15]
	v_mfma_f32_16x16x32_bf16 v[8:11], v[80:83], v[200:203], v[8:11]
	s_barrier
	s_mov_b32 m0, s47
	s_nop 0
	global_load_lds_dwordx4 v160, s[100:101]
	s_mov_b32 m0, s49
	s_nop 0
	global_load_lds_dwordx4 v162, s[100:101]
	s_add_i32 m0, s36, 0x1c000
	s_add_u32 s8, s8, 0xb0080
	s_addc_u32 s9, s9, 0
	global_load_lds_dwordx4 v168, s[8:9]
	s_add_i32 m0, s36, 0x1e000
	s_add_i32 s58, s58, 2
	global_load_lds_dwordx4 v164, s[8:9]
	s_waitcnt vmcnt(6)
	s_barrier
	v_mfma_f32_16x16x32_bf16 v[40:43], v[212:215], v[56:59], v[40:43]
	v_mfma_f32_16x16x32_bf16 v[80:83], v[216:219], v[60:63], v[40:43]
	v_mfma_f32_16x16x32_bf16 v[40:43], v[220:223], v[56:59], v[44:47]
	v_mfma_f32_16x16x32_bf16 v[36:39], v[212:215], v[72:75], v[36:39]
	v_mfma_f32_16x16x32_bf16 v[32:35], v[220:223], v[72:75], v[32:35]
	v_mfma_f32_16x16x32_bf16 v[20:23], v[212:215], v[182:185], v[20:23]
	v_mfma_f32_16x16x32_bf16 v[16:19], v[220:223], v[182:185], v[16:19]
	v_mfma_f32_16x16x32_bf16 v[4:7], v[212:215], v[196:199], v[4:7]
	v_mfma_f32_16x16x32_bf16 v[0:3], v[220:223], v[196:199], v[0:3]
	v_mfma_f32_16x16x32_bf16 v[76:79], v[236:239], v[60:63], v[40:43]
	v_mfma_f32_16x16x32_bf16 v[36:39], v[216:219], v[84:87], v[36:39]
	v_mfma_f32_16x16x32_bf16 v[32:35], v[236:239], v[84:87], v[32:35]
	v_mfma_f32_16x16x32_bf16 v[20:23], v[216:219], v[186:189], v[20:23]
	v_mfma_f32_16x16x32_bf16 v[16:19], v[236:239], v[186:189], v[16:19]
	v_mfma_f32_16x16x32_bf16 v[4:7], v[216:219], v[200:203], v[4:7]
	v_mfma_f32_16x16x32_bf16 v[0:3], v[236:239], v[200:203], v[0:3]
	s_add_u32 s56, s56, 0x100
	s_addc_u32 s57, s57, 0
	s_cmp_gt_u32 s58, 41
	s_mov_b64 s[24:25], s[2:3]
	s_barrier
	s_cbranch_scc0 .LBB0_1049
	s_lshl_b32 s2, s55, 8
	v_mov_b32_e32 v186, v193
	v_mov_b32_e32 v196, v192
	s_or_b32 s2, s2, s46
	v_mov_b32_e32 v52, 0
	v_lshl_add_u32 v182, v196, 3, s2
	s_add_i32 s2, s54, -16
	s_lshr_b32 s2, s2, 3
	s_add_i32 s2, s2, 1
	s_cmp_gt_i32 s54, 15
	s_cselect_b32 s8, s2, 0
	s_mul_i32 s96, s8, 0x1800
	s_lshl_b64 s[2:3], s[96:97], 2
	s_add_u32 s2, s41, s2
	v_ashrrev_i32_e32 v183, 31, v182
	s_addc_u32 s3, s42, s3
	v_lshlrev_b64 v[40:41], 2, v[182:183]
	v_lshl_add_u64 v[42:43], s[2:3], 0, v[40:41]
	global_load_dwordx4 v[72:75], v[42:43], off
	s_lshl_b32 s96, s8, 10
	s_lshl_b64 s[2:3], s[96:97], 2
	s_add_u32 s2, s43, s2
	s_addc_u32 s3, s44, s3
	v_lshl_add_u64 v[184:185], s[2:3], 0, v[40:41]
	s_and_b64 vcc, exec, s[4:5]
	v_mov_b32_e32 v60, 0
	v_mov_b32_e32 v61, v52
	v_mov_b32_e32 v62, 0
	v_mov_b32_e32 v63, 0
	s_cbranch_vccnz .LBB0_1052
	global_load_dwordx4 v[60:63], v[184:185], off
